# GEMM phase heads: dropped the duplicated lgkmcnt(0) wait between setprio and the first MFMA (30 sites)
# speedup vs baseline: 1.0334x; 1.0048x over previous
; #define PG8_STAGE(bufoff, gbase, voff) do { _Pragma("unroll") for (int _i = 0; _i < 2; ++_i) \
;         __builtin_amdgcn_global_load_lds((const unsigned*)((const char*)(gbase) + (voff)[_i]), (PG8_LAS unsigned*)(lds + (bufoff) + ldsw + _i * 8192), 16, 0, 0); } while (0)
; #define PG8_LDA(dst, b, h) do { _Pragma("unroll") for (int m = 0; m < 4; ++m) _Pragma("unroll") for (int k = 0; k < 2; ++k) dst[m][k] = *(const PG8_LAS bf16x8*)(lds + PG8_SA(b, h) + aoff + m * 2048 + k * 1024); } while (0)
; #define PG8_LDB(dst, b, h) do { _Pragma("unroll") for (int n = 0; n < 2; ++n) _Pragma("unroll") for (int k = 0; k < 2; ++k) dst[n][k] = *(const PG8_LAS bf16x8*)(lds + PG8_SB(b, h) + boff + n * 2048 + k * 1024); } while (0)
; #define PG8_MMA(ai, bj, At, Bt) do { __builtin_amdgcn_s_setprio(1); _Pragma("unroll") for (int m = 0; m < 4; ++m) _Pragma("unroll") for (int n = 0; n < 2; ++n) _Pragma("unroll") for (int k = 0; k < 2; ++k) \
;         acc[ai][bj][m][n] = __builtin_amdgcn_mfma_f32_16x16x32_bf16(Bt[n][k], At[m][k], acc[ai][bj][m][n], 0, 0, 0); __builtin_amdgcn_s_setprio(0); } while (0)
; #define PG8_WAIT_V(n) asm volatile("s_waitcnt vmcnt(" #n ")" ::: "memory")
; #define PG8_WAIT_L(n) asm volatile("s_waitcnt lgkmcnt(" #n ")" ::: "memory")
; #define PG8_BAR __builtin_amdgcn_s_barrier()
; #define PG8_SCHED __builtin_amdgcn_sched_barrier(0)
; template <class Epi, class Sched>
; __device__ __forceinline__ void gemm_phase(PG8_LAS unsigned char* lds, const Gemm g, const Sched& S, const Epi& E) {
;     ...
;             PG8_LDB(B0, 0, 0); PG8_SCHED; PG8_LDA(At, 0, 0); PG8_STAGE(PG8_SA(1, 1), a1 + hstep, voffA);
;             PG8_WAIT_L(8); PG8_BAR; PG8_WAIT_L(0); PG8_MMA(0, 0, At, B0); PG8_BAR; PG8_SCHED;
;             PG8_LDB(B1, 0, 1); PG8_STAGE(PG8_SB(0, 0), b2, voffB);
;             PG8_BAR; PG8_WAIT_L(0); PG8_MMA(0, 1, At, B1); PG8_BAR;
;             PG8_LDA(At, 0, 1); PG8_STAGE(PG8_SA(0, 0), a2, voffA);
;             PG8_BAR; PG8_WAIT_L(0); PG8_MMA(1, 0, At, B0); PG8_BAR; PG8_SCHED;
;             PG8_STAGE(PG8_SB(0, 1), b2 + hstep, voffB);
;             PG8_WAIT_V(6); PG8_BAR; PG8_MMA(1, 1, At, B1); PG8_BAR;
.LBB0_75:
	s_add_u32 s10, vcc_lo, 0xfffc0080
	s_addc_u32 s11, vcc_hi, -1
	s_add_i32 s89, 0, 0x10000
	v_add_u32_e32 v156, s89, v141
	ds_read_b128 v[144:147], v156
	ds_read_b128 v[148:151], v156 offset:1024
	ds_read_b128 v[152:155], v156 offset:2048
	ds_read_b128 v[156:159], v156 offset:3072
	s_cmp_eq_u32 s88, 12
	s_cselect_b32 s41, s39, s11
	s_cselect_b32 s40, s84, s10
	s_cselect_b32 s11, s37, s87
	s_cselect_b32 s10, s85, s86
	v_lshl_add_u64 v[202:203], vcc, 0, v[136:137]
	s_add_i32 m0, s21, 0xc000
	ds_read_b128 v[160:163], v143
	ds_read_b128 v[174:177], v143 offset:1024
	ds_read_b128 v[178:181], v143 offset:2048
	ds_read_b128 v[182:185], v143 offset:3072
	ds_read_b128 v[186:189], v143 offset:4096
	ds_read_b128 v[190:193], v143 offset:5120
	ds_read_b128 v[194:197], v143 offset:6144
	ds_read_b128 v[198:201], v143 offset:7168
	global_load_lds_dwordx4 v[202:203], off
	v_lshl_add_u64 v[202:203], vcc, 0, v[138:139]
	s_add_i32 m0, s21, 0xe000
	s_nop 0
	global_load_lds_dwordx4 v[202:203], off
	s_waitcnt lgkmcnt(8)
	s_barrier
	s_waitcnt lgkmcnt(0)
	s_setprio 1
	v_mfma_f32_16x16x32_bf16 v[126:129], v[144:147], v[160:163], v[126:129]
	v_mfma_f32_16x16x32_bf16 v[122:125], v[152:155], v[160:163], v[122:125]
	v_mfma_f32_16x16x32_bf16 v[118:121], v[144:147], v[178:181], v[118:121]
	v_mfma_f32_16x16x32_bf16 v[114:117], v[152:155], v[178:181], v[114:117]
	v_mfma_f32_16x16x32_bf16 v[102:105], v[144:147], v[186:189], v[102:105]
	v_mfma_f32_16x16x32_bf16 v[98:101], v[152:155], v[186:189], v[98:101]
	v_mfma_f32_16x16x32_bf16 v[86:89], v[144:147], v[194:197], v[86:89]
	v_mfma_f32_16x16x32_bf16 v[82:85], v[152:155], v[194:197], v[82:85]
	v_mfma_f32_16x16x32_bf16 v[126:129], v[148:151], v[174:177], v[126:129]
	v_mfma_f32_16x16x32_bf16 v[122:125], v[156:159], v[174:177], v[122:125]
	v_mfma_f32_16x16x32_bf16 v[118:121], v[148:151], v[182:185], v[118:121]
	v_mfma_f32_16x16x32_bf16 v[114:117], v[156:159], v[182:185], v[114:117]
	v_mfma_f32_16x16x32_bf16 v[102:105], v[148:151], v[190:193], v[102:105]
	v_mfma_f32_16x16x32_bf16 v[98:101], v[156:159], v[190:193], v[98:101]
	v_mfma_f32_16x16x32_bf16 v[86:89], v[148:151], v[198:201], v[86:89]
	v_mfma_f32_16x16x32_bf16 v[82:85], v[156:159], v[198:201], v[82:85]
	s_setprio 0
	s_barrier
	s_add_i32 s92, 0, 0x14000
	s_add_i32 s89, s89, s76
	v_add_u32_e32 v173, s92, v141
	v_lshl_add_u64 v[202:203], s[10:11], 0, v[0:1]
	s_mov_b32 m0, s89
	ds_read_b128 v[216:219], v173
	ds_read_b128 v[220:223], v173 offset:1024
	ds_read_b128 v[224:227], v173 offset:2048
	ds_read_b128 v[228:231], v173 offset:3072
	global_load_lds_dwordx4 v[202:203], off
	v_lshl_add_u64 v[232:233], s[10:11], 0, v[134:135]
	s_add_i32 m0, s89, 0x2000
	s_nop 0
	global_load_lds_dwordx4 v[232:233], off
	s_barrier
	s_waitcnt lgkmcnt(0)
	s_setprio 1
	v_mfma_f32_16x16x32_bf16 v[110:113], v[216:219], v[160:163], v[110:113]
	v_mfma_f32_16x16x32_bf16 v[106:109], v[224:227], v[160:163], v[106:109]
	v_mfma_f32_16x16x32_bf16 v[94:97], v[216:219], v[178:181], v[94:97]
	v_mfma_f32_16x16x32_bf16 v[90:93], v[224:227], v[178:181], v[90:93]
	v_mfma_f32_16x16x32_bf16 v[78:81], v[216:219], v[186:189], v[78:81]
	v_mfma_f32_16x16x32_bf16 v[74:77], v[224:227], v[186:189], v[74:77]
	v_mfma_f32_16x16x32_bf16 v[70:73], v[216:219], v[194:197], v[70:73]
	v_mfma_f32_16x16x32_bf16 v[66:69], v[224:227], v[194:197], v[66:69]
	v_mfma_f32_16x16x32_bf16 v[110:113], v[220:223], v[174:177], v[110:113]
	v_mfma_f32_16x16x32_bf16 v[106:109], v[228:231], v[174:177], v[106:109]
	v_mfma_f32_16x16x32_bf16 v[94:97], v[220:223], v[182:185], v[94:97]
	v_mfma_f32_16x16x32_bf16 v[90:93], v[228:231], v[182:185], v[90:93]
	v_mfma_f32_16x16x32_bf16 v[78:81], v[220:223], v[190:193], v[78:81]
	v_mfma_f32_16x16x32_bf16 v[74:77], v[228:231], v[190:193], v[74:77]
	v_mfma_f32_16x16x32_bf16 v[70:73], v[220:223], v[198:201], v[70:73]
	v_mfma_f32_16x16x32_bf16 v[66:69], v[228:231], v[198:201], v[66:69]
	s_setprio 0
	s_mov_b32 m0, s21
	v_lshl_add_u64 v[234:235], s[40:41], 0, v[130:131]
	s_barrier
	ds_read_b128 v[160:163], v143 offset:16384
	ds_read_b128 v[174:177], v143 offset:17408
	ds_read_b128 v[178:181], v143 offset:18432
	ds_read_b128 v[182:185], v143 offset:19456
	ds_read_b128 v[186:189], v143 offset:20480
	ds_read_b128 v[190:193], v143 offset:21504
	ds_read_b128 v[194:197], v143 offset:22528
	ds_read_b128 v[198:201], v143 offset:23552
	global_load_lds_dwordx4 v[234:235], off
	v_lshl_add_u64 v[236:237], s[40:41], 0, v[132:133]
	s_mov_b32 m0, s77
	s_nop 0
	global_load_lds_dwordx4 v[236:237], off
	s_barrier
	s_waitcnt lgkmcnt(0)
	s_setprio 1
	v_mfma_f32_16x16x32_bf16 v[62:65], v[144:147], v[160:163], v[62:65]
	v_mfma_f32_16x16x32_bf16 v[58:61], v[152:155], v[160:163], v[58:61]
	v_mfma_f32_16x16x32_bf16 v[54:57], v[144:147], v[178:181], v[54:57]
	v_mfma_f32_16x16x32_bf16 v[50:53], v[152:155], v[178:181], v[50:53]
	v_mfma_f32_16x16x32_bf16 v[38:41], v[144:147], v[186:189], v[38:41]
	v_mfma_f32_16x16x32_bf16 v[34:37], v[152:155], v[186:189], v[34:37]
	v_mfma_f32_16x16x32_bf16 v[22:25], v[144:147], v[194:197], v[22:25]
	v_mfma_f32_16x16x32_bf16 v[18:21], v[152:155], v[194:197], v[18:21]
	v_mfma_f32_16x16x32_bf16 v[62:65], v[148:151], v[174:177], v[62:65]
	v_mfma_f32_16x16x32_bf16 v[58:61], v[156:159], v[174:177], v[58:61]
	v_mfma_f32_16x16x32_bf16 v[54:57], v[148:151], v[182:185], v[54:57]
	v_mfma_f32_16x16x32_bf16 v[50:53], v[156:159], v[182:185], v[50:53]
	v_mfma_f32_16x16x32_bf16 v[38:41], v[148:151], v[190:193], v[38:41]
	v_mfma_f32_16x16x32_bf16 v[34:37], v[156:159], v[190:193], v[34:37]
	v_mfma_f32_16x16x32_bf16 v[22:25], v[148:151], v[198:201], v[22:25]
	v_mfma_f32_16x16x32_bf16 v[18:21], v[156:159], v[198:201], v[18:21]
	s_setprio 0
	s_barrier
; #define PG8_STAGE(bufoff, gbase, voff) do { _Pragma("unroll") for (int _i = 0; _i < 2; ++_i) \
;         __builtin_amdgcn_global_load_lds((const unsigned*)((const char*)(gbase) + (voff)[_i]), (PG8_LAS unsigned*)(lds + (bufoff) + ldsw + _i * 8192), 16, 0, 0); } while (0)
; #define PG8_LDA(dst, b, h) do { _Pragma("unroll") for (int m = 0; m < 4; ++m) _Pragma("unroll") for (int k = 0; k < 2; ++k) dst[m][k] = *(const PG8_LAS bf16x8*)(lds + PG8_SA(b, h) + aoff + m * 2048 + k * 1024); } while (0)
; #define PG8_LDB(dst, b, h) do { _Pragma("unroll") for (int n = 0; n < 2; ++n) _Pragma("unroll") for (int k = 0; k < 2; ++k) dst[n][k] = *(const PG8_LAS bf16x8*)(lds + PG8_SB(b, h) + boff + n * 2048 + k * 1024); } while (0)
; #define PG8_MMA(ai, bj, At, Bt) do { __builtin_amdgcn_s_setprio(1); _Pragma("unroll") for (int m = 0; m < 4; ++m) _Pragma("unroll") for (int n = 0; n < 2; ++n) _Pragma("unroll") for (int k = 0; k < 2; ++k) \
;         acc[ai][bj][m][n] = __builtin_amdgcn_mfma_f32_16x16x32_bf16(Bt[n][k], At[m][k], acc[ai][bj][m][n], 0, 0, 0); __builtin_amdgcn_s_setprio(0); } while (0)
; #define PG8_WAIT_V(n) asm volatile("s_waitcnt vmcnt(" #n ")" ::: "memory")
; #define PG8_WAIT_L(n) asm volatile("s_waitcnt lgkmcnt(" #n ")" ::: "memory")
; #define PG8_BAR __builtin_amdgcn_s_barrier()
; #define PG8_SCHED __builtin_amdgcn_sched_barrier(0)
; template <class Epi, class Sched>
; __device__ __forceinline__ void gemm_phase(PG8_LAS unsigned char* lds, const Gemm g, const Sched& S, const Epi& E) {
;     ...
;             PG8_STAGE(PG8_SB(0, 1), b2 + hstep, voffB);
;             PG8_WAIT_V(6); PG8_BAR; PG8_MMA(1, 1, At, B1); PG8_BAR;
;             PG8_LDB(B0, 1, 0); PG8_SCHED; PG8_LDA(At, 1, 0); PG8_STAGE(PG8_SA(0, 1), a2 + hstep, voffA);
;             PG8_WAIT_L(8); PG8_BAR; PG8_WAIT_L(0); PG8_MMA(0, 0, At, B0); PG8_BAR; PG8_SCHED;
;             PG8_LDB(B1, 1, 1); PG8_STAGE(PG8_SB(1, 0), b3, voffB);
;             PG8_BAR; PG8_WAIT_L(0); PG8_MMA(0, 1, At, B1); PG8_BAR;
;             PG8_LDA(At, 1, 1); PG8_STAGE(PG8_SA(1, 0), a3, voffA);
	s_add_u32 s90, s10, 0x40000
	s_addc_u32 s91, s11, 0
	s_add_i32 s89, s92, s76
	v_lshl_add_u64 v[144:145], s[90:91], 0, v[0:1]
	s_mov_b32 m0, s89
	s_nop 0
	global_load_lds_dwordx4 v[144:145], off
	v_lshl_add_u64 v[144:145], s[90:91], 0, v[134:135]
	s_add_i32 m0, s89, 0x2000
	s_nop 0
	global_load_lds_dwordx4 v[144:145], off
	s_waitcnt vmcnt(6)
	s_barrier
	s_setprio 1
	v_mfma_f32_16x16x32_bf16 v[46:49], v[216:219], v[160:163], v[46:49]
	v_mfma_f32_16x16x32_bf16 v[42:45], v[224:227], v[160:163], v[42:45]
	v_mfma_f32_16x16x32_bf16 v[30:33], v[216:219], v[178:181], v[30:33]
	v_mfma_f32_16x16x32_bf16 v[26:29], v[224:227], v[178:181], v[26:29]
	v_mfma_f32_16x16x32_bf16 v[14:17], v[216:219], v[186:189], v[14:17]
	v_mfma_f32_16x16x32_bf16 v[10:13], v[224:227], v[186:189], v[10:13]
	v_mfma_f32_16x16x32_bf16 v[6:9], v[216:219], v[194:197], v[6:9]
	v_mfma_f32_16x16x32_bf16 v[2:5], v[224:227], v[194:197], v[2:5]
	v_mfma_f32_16x16x32_bf16 v[46:49], v[220:223], v[174:177], v[46:49]
	v_mfma_f32_16x16x32_bf16 v[42:45], v[228:231], v[174:177], v[42:45]
	v_mfma_f32_16x16x32_bf16 v[30:33], v[220:223], v[182:185], v[30:33]
	v_mfma_f32_16x16x32_bf16 v[26:29], v[228:231], v[182:185], v[26:29]
	v_mfma_f32_16x16x32_bf16 v[14:17], v[220:223], v[190:193], v[14:17]
	v_mfma_f32_16x16x32_bf16 v[10:13], v[228:231], v[190:193], v[10:13]
	v_mfma_f32_16x16x32_bf16 v[6:9], v[220:223], v[198:201], v[6:9]
	v_mfma_f32_16x16x32_bf16 v[2:5], v[228:231], v[198:201], v[2:5]
	s_setprio 0
	s_add_i32 s89, 0, 0x18000
	v_add_u32_e32 v156, s89, v141
	s_barrier
	ds_read_b128 v[144:147], v156
	ds_read_b128 v[148:151], v156 offset:1024
	ds_read_b128 v[152:155], v156 offset:2048
	ds_read_b128 v[156:159], v156 offset:3072
	s_add_u32 s40, s40, 0x40000
	s_addc_u32 s41, s41, 0
	s_mov_b32 m0, s78
	v_lshl_add_u64 v[216:217], s[40:41], 0, v[130:131]
	ds_read_b128 v[160:163], v143 offset:32768
	ds_read_b128 v[174:177], v143 offset:33792
	ds_read_b128 v[178:181], v143 offset:34816
	ds_read_b128 v[182:185], v143 offset:35840
	ds_read_b128 v[186:189], v143 offset:36864
	ds_read_b128 v[190:193], v143 offset:37888
	ds_read_b128 v[194:197], v143 offset:38912
	ds_read_b128 v[198:201], v143 offset:39936
	global_load_lds_dwordx4 v[216:217], off
	v_lshl_add_u64 v[216:217], s[40:41], 0, v[132:133]
	s_mov_b32 m0, s79
	s_nop 0
	global_load_lds_dwordx4 v[216:217], off
	s_waitcnt lgkmcnt(8)
	s_barrier
	s_waitcnt lgkmcnt(0)
	s_setprio 1
	v_mfma_f32_16x16x32_bf16 v[126:129], v[144:147], v[160:163], v[126:129]
	v_mfma_f32_16x16x32_bf16 v[122:125], v[152:155], v[160:163], v[122:125]
	v_mfma_f32_16x16x32_bf16 v[118:121], v[144:147], v[178:181], v[118:121]
	v_mfma_f32_16x16x32_bf16 v[114:117], v[152:155], v[178:181], v[114:117]
	v_mfma_f32_16x16x32_bf16 v[102:105], v[144:147], v[186:189], v[102:105]
	v_mfma_f32_16x16x32_bf16 v[98:101], v[152:155], v[186:189], v[98:101]
	v_mfma_f32_16x16x32_bf16 v[86:89], v[144:147], v[194:197], v[86:89]
	v_mfma_f32_16x16x32_bf16 v[82:85], v[152:155], v[194:197], v[82:85]
	v_mfma_f32_16x16x32_bf16 v[126:129], v[148:151], v[174:177], v[126:129]
	v_mfma_f32_16x16x32_bf16 v[122:125], v[156:159], v[174:177], v[122:125]
	v_mfma_f32_16x16x32_bf16 v[118:121], v[148:151], v[182:185], v[118:121]
	v_mfma_f32_16x16x32_bf16 v[114:117], v[156:159], v[182:185], v[114:117]
	v_mfma_f32_16x16x32_bf16 v[102:105], v[148:151], v[190:193], v[102:105]
	v_mfma_f32_16x16x32_bf16 v[98:101], v[156:159], v[190:193], v[98:101]
	v_mfma_f32_16x16x32_bf16 v[86:89], v[148:151], v[198:201], v[86:89]
	v_mfma_f32_16x16x32_bf16 v[82:85], v[156:159], v[198:201], v[82:85]
	s_setprio 0
	s_barrier
	s_add_i32 s40, 0, 0x1c000
	s_add_i32 s41, s89, s76
	v_add_u32_e32 v173, s40, v141
	v_lshl_add_u64 v[202:203], v[202:203], 0, s[8:9]
	s_mov_b32 m0, s41
	ds_read_b128 v[216:219], v173
	ds_read_b128 v[220:223], v173 offset:1024
	ds_read_b128 v[224:227], v173 offset:2048
	ds_read_b128 v[228:231], v173 offset:3072
	global_load_lds_dwordx4 v[202:203], off
	v_lshl_add_u64 v[202:203], v[232:233], 0, s[8:9]
	s_add_i32 m0, s41, 0x2000
	s_nop 0
	global_load_lds_dwordx4 v[202:203], off
	s_barrier
	s_waitcnt lgkmcnt(0)
	s_setprio 1
	v_mfma_f32_16x16x32_bf16 v[110:113], v[216:219], v[160:163], v[110:113]
	v_mfma_f32_16x16x32_bf16 v[106:109], v[224:227], v[160:163], v[106:109]
	v_mfma_f32_16x16x32_bf16 v[94:97], v[216:219], v[178:181], v[94:97]
	v_mfma_f32_16x16x32_bf16 v[90:93], v[224:227], v[178:181], v[90:93]
	v_mfma_f32_16x16x32_bf16 v[78:81], v[216:219], v[186:189], v[78:81]
	v_mfma_f32_16x16x32_bf16 v[74:77], v[224:227], v[186:189], v[74:77]
	v_mfma_f32_16x16x32_bf16 v[70:73], v[216:219], v[194:197], v[70:73]
	v_mfma_f32_16x16x32_bf16 v[66:69], v[224:227], v[194:197], v[66:69]
	v_mfma_f32_16x16x32_bf16 v[110:113], v[220:223], v[174:177], v[110:113]
	v_mfma_f32_16x16x32_bf16 v[106:109], v[228:231], v[174:177], v[106:109]
	v_mfma_f32_16x16x32_bf16 v[94:97], v[220:223], v[182:185], v[94:97]
	v_mfma_f32_16x16x32_bf16 v[90:93], v[228:231], v[182:185], v[90:93]
	v_mfma_f32_16x16x32_bf16 v[78:81], v[220:223], v[190:193], v[78:81]
	v_mfma_f32_16x16x32_bf16 v[74:77], v[228:231], v[190:193], v[74:77]
	v_mfma_f32_16x16x32_bf16 v[70:73], v[220:223], v[198:201], v[70:73]
	v_mfma_f32_16x16x32_bf16 v[66:69], v[228:231], v[198:201], v[66:69]
	s_setprio 0
	s_mov_b32 m0, s80
	v_lshl_add_u64 v[202:203], v[234:235], 0, s[8:9]
	s_barrier
	ds_read_b128 v[160:163], v143 offset:49152
	ds_read_b128 v[174:177], v143 offset:50176
	ds_read_b128 v[178:181], v143 offset:51200
	ds_read_b128 v[182:185], v143 offset:52224
	ds_read_b128 v[186:189], v143 offset:53248
	ds_read_b128 v[190:193], v143 offset:54272
	ds_read_b128 v[194:197], v143 offset:55296
	ds_read_b128 v[198:201], v143 offset:56320
	global_load_lds_dwordx4 v[202:203], off
	v_lshl_add_u64 v[202:203], v[236:237], 0, s[8:9]
	s_mov_b32 m0, s81
	s_nop 0
	global_load_lds_dwordx4 v[202:203], off
	s_barrier
; #define PG8_STAGE(bufoff, gbase, voff) do { _Pragma("unroll") for (int _i = 0; _i < 2; ++_i) \
;         __builtin_amdgcn_global_load_lds((const unsigned*)((const char*)(gbase) + (voff)[_i]), (PG8_LAS unsigned*)(lds + (bufoff) + ldsw + _i * 8192), 16, 0, 0); } while (0)
; #define PG8_LDA(dst, b, h) do { _Pragma("unroll") for (int m = 0; m < 4; ++m) _Pragma("unroll") for (int k = 0; k < 2; ++k) dst[m][k] = *(const PG8_LAS bf16x8*)(lds + PG8_SA(b, h) + aoff + m * 2048 + k * 1024); } while (0)
; #define PG8_LDB(dst, b, h) do { _Pragma("unroll") for (int n = 0; n < 2; ++n) _Pragma("unroll") for (int k = 0; k < 2; ++k) dst[n][k] = *(const PG8_LAS bf16x8*)(lds + PG8_SB(b, h) + boff + n * 2048 + k * 1024); } while (0)
; #define PG8_MMA(ai, bj, At, Bt) do { __builtin_amdgcn_s_setprio(1); _Pragma("unroll") for (int m = 0; m < 4; ++m) _Pragma("unroll") for (int n = 0; n < 2; ++n) _Pragma("unroll") for (int k = 0; k < 2; ++k) \
;         acc[ai][bj][m][n] = __builtin_amdgcn_mfma_f32_16x16x32_bf16(Bt[n][k], At[m][k], acc[ai][bj][m][n], 0, 0, 0); __builtin_amdgcn_s_setprio(0); } while (0)
; #define PG8_WAIT_V(n) asm volatile("s_waitcnt vmcnt(" #n ")" ::: "memory")
; #define PG8_WAIT_L(n) asm volatile("s_waitcnt lgkmcnt(" #n ")" ::: "memory")
; #define PG8_BAR __builtin_amdgcn_s_barrier()
; #define PG8_SCHED __builtin_amdgcn_sched_barrier(0)
; template <class Epi, class Sched>
; __device__ __forceinline__ void gemm_phase(PG8_LAS unsigned char* lds, const Gemm g, const Sched& S, const Epi& E) {
;     ...
;             PG8_WAIT_V(6); PG8_BAR; PG8_MMA(1, 1, At, B1); PG8_BAR;
;             PG8_LDB(B0, 1, 0); PG8_SCHED; PG8_LDA(At, 1, 0); PG8_STAGE(PG8_SA(0, 1), a2 + hstep, voffA);
;             PG8_WAIT_L(8); PG8_BAR; PG8_WAIT_L(0); PG8_MMA(0, 0, At, B0); PG8_BAR; PG8_SCHED;
;             PG8_LDB(B1, 1, 1); PG8_STAGE(PG8_SB(1, 0), b3, voffB);
;             PG8_BAR; PG8_WAIT_L(0); PG8_MMA(0, 1, At, B1); PG8_BAR;
;             PG8_LDA(At, 1, 1); PG8_STAGE(PG8_SA(1, 0), a3, voffA);
;             PG8_BAR; PG8_WAIT_L(0); PG8_MMA(1, 0, At, B0); PG8_BAR; PG8_SCHED;
;             PG8_STAGE(PG8_SB(1, 1), b3 + hstep, voffB);
;             PG8_WAIT_V(6); PG8_BAR; PG8_MMA(1, 1, At, B1); PG8_BAR;
	s_waitcnt lgkmcnt(0)
	s_setprio 1
	v_mfma_f32_16x16x32_bf16 v[62:65], v[144:147], v[160:163], v[62:65]
	v_mfma_f32_16x16x32_bf16 v[58:61], v[152:155], v[160:163], v[58:61]
	v_mfma_f32_16x16x32_bf16 v[54:57], v[144:147], v[178:181], v[54:57]
	v_mfma_f32_16x16x32_bf16 v[50:53], v[152:155], v[178:181], v[50:53]
	v_mfma_f32_16x16x32_bf16 v[38:41], v[144:147], v[186:189], v[38:41]
	v_mfma_f32_16x16x32_bf16 v[34:37], v[152:155], v[186:189], v[34:37]
	v_mfma_f32_16x16x32_bf16 v[22:25], v[144:147], v[194:197], v[22:25]
	v_mfma_f32_16x16x32_bf16 v[18:21], v[152:155], v[194:197], v[18:21]
	v_mfma_f32_16x16x32_bf16 v[62:65], v[148:151], v[174:177], v[62:65]
	v_mfma_f32_16x16x32_bf16 v[58:61], v[156:159], v[174:177], v[58:61]
	v_mfma_f32_16x16x32_bf16 v[54:57], v[148:151], v[182:185], v[54:57]
	v_mfma_f32_16x16x32_bf16 v[50:53], v[156:159], v[182:185], v[50:53]
	v_mfma_f32_16x16x32_bf16 v[38:41], v[148:151], v[190:193], v[38:41]
	v_mfma_f32_16x16x32_bf16 v[34:37], v[156:159], v[190:193], v[34:37]
	v_mfma_f32_16x16x32_bf16 v[22:25], v[148:151], v[198:201], v[22:25]
	v_mfma_f32_16x16x32_bf16 v[18:21], v[156:159], v[198:201], v[18:21]
	s_setprio 0
	s_barrier
	s_add_u32 s10, s10, 0x40080
	s_addc_u32 s11, s11, 0
	s_add_i32 s40, s40, s76
	v_lshl_add_u64 v[144:145], s[10:11], 0, v[0:1]
	s_mov_b32 m0, s40
	s_nop 0
	global_load_lds_dwordx4 v[144:145], off
	v_lshl_add_u64 v[144:145], s[10:11], 0, v[134:135]
	s_add_i32 m0, s40, 0x2000
	s_nop 0
	global_load_lds_dwordx4 v[144:145], off
	s_waitcnt vmcnt(6)
	s_barrier
	s_setprio 1
	v_mfma_f32_16x16x32_bf16 v[46:49], v[216:219], v[160:163], v[46:49]
	v_mfma_f32_16x16x32_bf16 v[42:45], v[224:227], v[160:163], v[42:45]
	v_mfma_f32_16x16x32_bf16 v[30:33], v[216:219], v[178:181], v[30:33]
	v_mfma_f32_16x16x32_bf16 v[26:29], v[224:227], v[178:181], v[26:29]
	v_mfma_f32_16x16x32_bf16 v[14:17], v[216:219], v[186:189], v[14:17]
	v_mfma_f32_16x16x32_bf16 v[10:13], v[224:227], v[186:189], v[10:13]
	v_mfma_f32_16x16x32_bf16 v[6:9], v[216:219], v[194:197], v[6:9]
	v_mfma_f32_16x16x32_bf16 v[2:5], v[224:227], v[194:197], v[2:5]
	v_mfma_f32_16x16x32_bf16 v[46:49], v[220:223], v[174:177], v[46:49]
	v_mfma_f32_16x16x32_bf16 v[42:45], v[228:231], v[174:177], v[42:45]
	v_mfma_f32_16x16x32_bf16 v[30:33], v[220:223], v[182:185], v[30:33]
	v_mfma_f32_16x16x32_bf16 v[26:29], v[228:231], v[182:185], v[26:29]
	v_mfma_f32_16x16x32_bf16 v[14:17], v[220:223], v[190:193], v[14:17]
	v_mfma_f32_16x16x32_bf16 v[10:13], v[228:231], v[190:193], v[10:13]
	v_mfma_f32_16x16x32_bf16 v[6:9], v[220:223], v[198:201], v[6:9]
	v_mfma_f32_16x16x32_bf16 v[2:5], v[228:231], v[198:201], v[2:5]
	s_setprio 0
	s_add_i32 s88, s88, 2
	s_add_u32 vcc_lo, vcc_lo, 0x100
	s_addc_u32 vcc_hi, vcc_hi, 0
	s_add_u32 s86, s86, 0x100
	s_addc_u32 s87, s87, 0
	s_cmp_gt_u32 s88, 13
	s_barrier
	s_cbranch_scc0 .LBB0_75
; __device__ __forceinline__ unsigned pk2(float lo, float hi) { v2f v = {lo, hi}; return __builtin_bit_cast(unsigned, __builtin_convertvector(v, v2bf)); }
;     __device__ __forceinline__ void operator()(const f32x4 (&acc)[2][2][4][2], const Unit& u, int wr, int wc, int fr, int fq) const {
;         const int row0 = u.pm * 256 + wr * 64 + fr; int col0 = u.pn * 256 + wc * 32 + 8 * fq; int ld = ldz; bf16* base = Z;
;         if (SEG) { int c0, w; seg_of(u.pn * 256, c0, w); base = Z + (size_t)T * c0; ld = w; col0 -= c0; }
; #pragma unroll
;         for (int ai = 0; ai < 2; ++ai)
; #pragma unroll
;             for (int m = 0; m < 4; ++m) { bf16* rowp = base + (size_t)(row0 + ai * 128 + m * 16) * ld + col0;
; #pragma unroll
;                 for (int bj = 0; bj < 2; ++bj) { const f32x4 v0 = acc[ai][bj][m][0], v1 = acc[ai][bj][m][1];
;                     v4u w; w.x = pk2(v0[0], v0[1]); w.y = pk2(v0[2], v0[3]); w.z = pk2(v1[0], v1[1]); w.w = pk2(v1[2], v1[3]);
;                     *(v4u*)(rowp + bj * 128) = w; } }
	v_lshl_add_u32 v144, s20, 8, v140
	v_lshl_or_b32 v146, s83, 8, v142
	v_ashrrev_i32_e32 v147, 31, v146
	v_ashrrev_i32_e32 v145, 31, v144
	v_lshl_add_u64 v[146:147], v[146:147], 1, s[6:7]
	v_lshlrev_b64 v[148:149], 11, v[144:145]
	v_lshl_add_u64 v[148:149], v[146:147], 0, v[148:149]
	s_mov_b64 s[10:11], 0x40000
	v_cvt_pk_bf16_f32 v70, v70, v71
	v_cvt_pk_bf16_f32 v71, v72, v73
	v_cvt_pk_bf16_f32 v72, v66, v67
	v_lshl_add_u64 v[66:67], v[148:149], 0, s[10:11]
	v_cvt_pk_bf16_f32 v62, v62, v63
	v_cvt_pk_bf16_f32 v63, v64, v65
	v_cvt_pk_bf16_f32 v64, v58, v59
	v_add_co_u32_e32 v58, vcc, s67, v148
	v_cvt_pk_bf16_f32 v46, v46, v47
	v_cvt_pk_bf16_f32 v47, v48, v49
	v_cvt_pk_bf16_f32 v48, v42, v43
	v_cvt_pk_bf16_f32 v49, v44, v45
	s_mov_b64 s[10:11], 0x48000
	v_addc_co_u32_e32 v59, vcc, 0, v149, vcc
	global_store_dwordx4 v[66:67], v[46:49], off offset:256
	v_cvt_pk_bf16_f32 v30, v30, v31
	v_cvt_pk_bf16_f32 v31, v32, v33
	v_lshl_add_u64 v[46:47], v[148:149], 0, s[10:11]
	s_mov_b32 s10, 0x48000
	v_add_co_u32_e32 v48, vcc, s10, v148
	v_cvt_pk_bf16_f32 v32, v26, v27
	v_cvt_pk_bf16_f32 v33, v28, v29
	s_mov_b64 s[10:11], 0x50000
	v_cvt_pk_bf16_f32 v110, v110, v111
	v_cvt_pk_bf16_f32 v111, v112, v113
	v_cvt_pk_bf16_f32 v112, v106, v107
	v_or_b32_e32 v106, 16, v144
	v_addc_co_u32_e32 v49, vcc, 0, v149, vcc
	global_store_dwordx4 v[46:47], v[30:33], off offset:256
	v_ashrrev_i32_e32 v107, 31, v106
	v_cvt_pk_bf16_f32 v94, v94, v95
	v_lshl_add_u64 v[30:31], v[148:149], 0, s[10:11]
	s_mov_b32 s10, 0x50000
	v_cvt_pk_bf16_f32 v95, v96, v97
	v_cvt_pk_bf16_f32 v96, v90, v91
	v_or_b32_e32 v90, 32, v144
	v_add_co_u32_e32 v32, vcc, s10, v148
	v_cvt_pk_bf16_f32 v14, v14, v15
	v_cvt_pk_bf16_f32 v15, v16, v17
	v_cvt_pk_bf16_f32 v16, v10, v11
	v_cvt_pk_bf16_f32 v17, v12, v13
	s_mov_b64 s[10:11], 0x58000
	v_cvt_pk_bf16_f32 v113, v108, v109
	v_lshlrev_b64 v[106:107], 11, v[106:107]
	v_ashrrev_i32_e32 v91, 31, v90
	v_cvt_pk_bf16_f32 v78, v78, v79
	v_cvt_pk_bf16_f32 v79, v80, v81
	v_cvt_pk_bf16_f32 v80, v74, v75
	v_or_b32_e32 v74, 48, v144
	v_addc_co_u32_e32 v33, vcc, 0, v149, vcc
	global_store_dwordx4 v[30:31], v[14:17], off offset:256
	global_store_dwordx4 v[148:149], v[110:113], off offset:256
	v_cvt_pk_bf16_f32 v97, v92, v93
	v_lshl_add_u64 v[14:15], v[148:149], 0, s[10:11]
	s_mov_b32 s10, 0x58000
	v_lshl_add_u64 v[110:111], v[146:147], 0, v[106:107]
	v_lshlrev_b64 v[90:91], 11, v[90:91]
	v_ashrrev_i32_e32 v75, 31, v74
	v_add_co_u32_e32 v16, vcc, s10, v148
	global_store_dwordx4 v[110:111], v[94:97], off offset:256
	v_cvt_pk_bf16_f32 v81, v76, v77
	v_lshlrev_b64 v[74:75], 11, v[74:75]
	v_lshl_add_u64 v[94:95], v[146:147], 0, v[90:91]
	v_addc_co_u32_e32 v17, vcc, 0, v149, vcc
	v_cvt_pk_bf16_f32 v126, v126, v127
	v_cvt_pk_bf16_f32 v127, v128, v129
	v_cvt_pk_bf16_f32 v128, v122, v123
	v_cvt_pk_bf16_f32 v129, v124, v125
	v_cvt_pk_bf16_f32 v106, v118, v119
	v_cvt_pk_bf16_f32 v107, v120, v121
	v_cvt_pk_bf16_f32 v108, v114, v115
	v_cvt_pk_bf16_f32 v109, v116, v117
	v_cvt_pk_bf16_f32 v90, v102, v103
	v_cvt_pk_bf16_f32 v91, v104, v105
	v_cvt_pk_bf16_f32 v92, v98, v99
	v_cvt_pk_bf16_f32 v93, v100, v101
	global_store_dwordx4 v[94:95], v[78:81], off offset:256
	v_cvt_pk_bf16_f32 v76, v82, v83
	v_cvt_pk_bf16_f32 v77, v84, v85
	v_lshl_add_u64 v[78:79], v[146:147], 0, v[74:75]
	v_cvt_pk_bf16_f32 v74, v86, v87
	v_cvt_pk_bf16_f32 v75, v88, v89
	v_cvt_pk_bf16_f32 v73, v68, v69
	v_cvt_pk_bf16_f32 v65, v60, v61
	v_cvt_pk_bf16_f32 v42, v54, v55
	v_cvt_pk_bf16_f32 v43, v56, v57
	v_cvt_pk_bf16_f32 v44, v50, v51
	v_cvt_pk_bf16_f32 v45, v52, v53
	v_cvt_pk_bf16_f32 v26, v38, v39
	v_cvt_pk_bf16_f32 v27, v40, v41
	v_cvt_pk_bf16_f32 v28, v34, v35
	v_cvt_pk_bf16_f32 v29, v36, v37
	v_cvt_pk_bf16_f32 v10, v22, v23
	v_cvt_pk_bf16_f32 v11, v24, v25
	v_cvt_pk_bf16_f32 v12, v18, v19
	v_cvt_pk_bf16_f32 v13, v20, v21
	v_cvt_pk_bf16_f32 v6, v6, v7
	v_cvt_pk_bf16_f32 v7, v8, v9
	v_cvt_pk_bf16_f32 v8, v2, v3
	v_cvt_pk_bf16_f32 v9, v4, v5
	s_and_b64 vcc, exec, s[18:19]
	s_mov_b32 s83, s36
	s_mov_b32 s20, s38
	s_mov_b64 s[10:11], s[50:51]
	s_mov_b64 s[40:41], s[52:53]
	global_store_dwordx4 v[148:149], v[126:129], off
	global_store_dwordx4 v[110:111], v[106:109], off
	global_store_dwordx4 v[94:95], v[90:93], off
	global_store_dwordx4 v[78:79], v[74:77], off
	global_store_dwordx4 v[78:79], v[70:73], off offset:256
	global_store_dwordx4 v[58:59], v[62:65], off
	global_store_dwordx4 v[48:49], v[42:45], off
	global_store_dwordx4 v[32:33], v[26:29], off
	global_store_dwordx4 v[16:17], v[10:13], off
	global_store_dwordx4 v[14:15], v[6:9], off offset:256
	s_cbranch_vccz .LBB0_68
	s_waitcnt vmcnt(0)
	s_cmpk_gt_u32 s70, 0xff
	s_cbranch_scc1 .LBB0_58
	s_barrier
	s_branch .LBB0_58

; #define PG8_STAGE(bufoff, gbase, voff) do { _Pragma("unroll") for (int _i = 0; _i < 2; ++_i) \
;         __builtin_amdgcn_global_load_lds((const unsigned*)((const char*)(gbase) + (voff)[_i]), (PG8_LAS unsigned*)(lds + (bufoff) + ldsw + _i * 8192), 16, 0, 0); } while (0)
; #define PG8_LDA(dst, b, h) do { _Pragma("unroll") for (int m = 0; m < 4; ++m) _Pragma("unroll") for (int k = 0; k < 2; ++k) dst[m][k] = *(const PG8_LAS bf16x8*)(lds + PG8_SA(b, h) + aoff + m * 2048 + k * 1024); } while (0)
; #define PG8_LDB(dst, b, h) do { _Pragma("unroll") for (int n = 0; n < 2; ++n) _Pragma("unroll") for (int k = 0; k < 2; ++k) dst[n][k] = *(const PG8_LAS bf16x8*)(lds + PG8_SB(b, h) + boff + n * 2048 + k * 1024); } while (0)
; #define PG8_WAIT_L(n) asm volatile("s_waitcnt lgkmcnt(" #n ")" ::: "memory")
; #define PG8_BAR __builtin_amdgcn_s_barrier()
; #define PG8_SCHED __builtin_amdgcn_sched_barrier(0)
;     __device__ __forceinline__ bool next(int i, Unit& u) const { if (!S.next(i >> 2, u)) return false; u.seg = i & 3; return true; }
; template <class Epi, class Sched>
; __device__ __forceinline__ void gemm_phase(PG8_LAS unsigned char* lds, const Gemm g, const Sched& S, const Epi& E) {
;     ...
;         const bool has_next = S.next(ui + 1, nxt);
;         const char* nA = has_next ? (const char*)g.A + (size_t)nxt.pm * tstep + (size_t)nxt.seg * SEGB : cA; const char* nB = has_next ? (const char*)g.Bt + (size_t)nxt.pn * tstep + (size_t)nxt.seg * SEGB : cB;
;         for (int t = 0; t < nt; t += 2) {
;             const bool last = (t == nt - 2);
;             const char* a1 = cA + (size_t)(t + 1) * kstep;
;             const char* a2 = last ? nA : cA + (size_t)(t + 2) * kstep; const char* b2 = last ? nB : cB + (size_t)(t + 2) * kstep;
;             const char* a3 = a2 + kstep; const char* b3 = b2 + kstep;
;             if (last && has_next) S.a_ready(nxt);
;             PG8_LDB(B0, 0, 0); PG8_SCHED; PG8_LDA(At, 0, 0); PG8_STAGE(PG8_SA(1, 1), a1 + hstep, voffA);
;             PG8_WAIT_L(8); PG8_BAR; PG8_WAIT_L(0); PG8_MMA(0, 0, At, B0); PG8_BAR; PG8_SCHED;
;             PG8_LDB(B1, 0, 1); PG8_STAGE(PG8_SB(0, 0), b2, voffB);
;             PG8_BAR; PG8_WAIT_L(0); PG8_MMA(0, 1, At, B1); PG8_BAR;
;             PG8_LDA(At, 0, 1); PG8_STAGE(PG8_SA(0, 0), a2, voffA);
;             PG8_BAR; PG8_WAIT_L(0); PG8_MMA(1, 0, At, B0); PG8_BAR; PG8_SCHED;
.LBB0_87:
	s_ashr_i32 s19, s18, 31
	v_cmp_lt_i64_e32 vcc, s[20:21], v[166:167]
	s_lshl_b64 s[20:21], s[18:19], 19
	s_add_u32 s20, s56, s20
	s_addc_u32 s21, s57, s21
	s_and_b64 s[38:39], vcc, exec
	s_cselect_b32 s19, s21, s41
	s_cselect_b32 s79, s20, s40
	s_ashr_i32 s7, s6, 31
	s_lshl_b64 s[38:39], s[6:7], 19
	s_add_u32 s38, s52, s38
	s_addc_u32 s39, s53, s39
	s_and_b64 s[50:51], vcc, exec
	s_cselect_b32 s7, s39, s11
	s_cselect_b32 s80, s38, s10
	s_add_u32 s40, s40, 0x40080
	s_addc_u32 s41, s41, 0
	s_add_u32 s81, s10, 0x100
	s_addc_u32 s82, s11, 0
	s_mov_b32 s83, -2
	s_add_u32 s10, s40, 0xfffc0080
	s_addc_u32 s11, s41, -1
	s_add_i32 s84, 0, 0x10000
	v_add_u32_e32 v156, s84, v141
	ds_read_b128 v[144:147], v156
	ds_read_b128 v[148:151], v156 offset:1024
	ds_read_b128 v[152:155], v156 offset:2048
	ds_read_b128 v[156:159], v156 offset:3072
	s_cmp_eq_u32 s83, 12
	s_cselect_b32 s51, s19, s11
	s_cselect_b32 s50, s79, s10
	s_cselect_b32 s11, s7, s82
	s_cselect_b32 s10, s80, s81
	v_lshl_add_u64 v[202:203], s[40:41], 0, v[136:137]
	s_add_i32 m0, s71, 0xc000
	ds_read_b128 v[160:163], v143
	ds_read_b128 v[174:177], v143 offset:1024
	ds_read_b128 v[178:181], v143 offset:2048
	ds_read_b128 v[182:185], v143 offset:3072
	ds_read_b128 v[186:189], v143 offset:4096
	ds_read_b128 v[190:193], v143 offset:5120
	ds_read_b128 v[194:197], v143 offset:6144
	ds_read_b128 v[198:201], v143 offset:7168
	global_load_lds_dwordx4 v[202:203], off
	v_lshl_add_u64 v[202:203], s[40:41], 0, v[138:139]
	s_add_i32 m0, s71, 0xe000
	s_nop 0
	global_load_lds_dwordx4 v[202:203], off
	s_waitcnt lgkmcnt(8)
	s_barrier
	s_waitcnt lgkmcnt(0)
	s_setprio 1
	v_mfma_f32_16x16x32_bf16 v[126:129], v[144:147], v[160:163], 0
	v_mfma_f32_16x16x32_bf16 v[122:125], v[152:155], v[160:163], 0
	v_mfma_f32_16x16x32_bf16 v[118:121], v[144:147], v[178:181], 0
	v_mfma_f32_16x16x32_bf16 v[114:117], v[152:155], v[178:181], 0
	v_mfma_f32_16x16x32_bf16 v[102:105], v[144:147], v[186:189], 0
	v_mfma_f32_16x16x32_bf16 v[98:101], v[152:155], v[186:189], 0
	v_mfma_f32_16x16x32_bf16 v[86:89], v[144:147], v[194:197], 0
	v_mfma_f32_16x16x32_bf16 v[82:85], v[152:155], v[194:197], 0
	v_mfma_f32_16x16x32_bf16 v[126:129], v[148:151], v[174:177], v[126:129]
	v_mfma_f32_16x16x32_bf16 v[122:125], v[156:159], v[174:177], v[122:125]
	v_mfma_f32_16x16x32_bf16 v[118:121], v[148:151], v[182:185], v[118:121]
	v_mfma_f32_16x16x32_bf16 v[114:117], v[156:159], v[182:185], v[114:117]
	v_mfma_f32_16x16x32_bf16 v[102:105], v[148:151], v[190:193], v[102:105]
	v_mfma_f32_16x16x32_bf16 v[98:101], v[156:159], v[190:193], v[98:101]
	v_mfma_f32_16x16x32_bf16 v[86:89], v[148:151], v[198:201], v[86:89]
	v_mfma_f32_16x16x32_bf16 v[82:85], v[156:159], v[198:201], v[82:85]
	s_setprio 0
	s_barrier
	s_add_i32 s86, 0, 0x14000
	s_add_i32 s84, s84, s70
	v_add_u32_e32 v173, s86, v141
	v_lshl_add_u64 v[202:203], s[10:11], 0, v[0:1]
	s_mov_b32 m0, s84
	ds_read_b128 v[216:219], v173
	ds_read_b128 v[220:223], v173 offset:1024
	ds_read_b128 v[224:227], v173 offset:2048
	ds_read_b128 v[228:231], v173 offset:3072
	global_load_lds_dwordx4 v[202:203], off
	v_lshl_add_u64 v[232:233], s[10:11], 0, v[130:131]
	s_add_i32 m0, s84, 0x2000
	s_nop 0
	global_load_lds_dwordx4 v[232:233], off
	s_barrier
	s_waitcnt lgkmcnt(0)
	s_setprio 1
	v_mfma_f32_16x16x32_bf16 v[110:113], v[216:219], v[160:163], 0
	v_mfma_f32_16x16x32_bf16 v[106:109], v[224:227], v[160:163], 0
	v_mfma_f32_16x16x32_bf16 v[94:97], v[216:219], v[178:181], 0
	v_mfma_f32_16x16x32_bf16 v[90:93], v[224:227], v[178:181], 0
	v_mfma_f32_16x16x32_bf16 v[78:81], v[216:219], v[186:189], 0
	v_mfma_f32_16x16x32_bf16 v[74:77], v[224:227], v[186:189], 0
	v_mfma_f32_16x16x32_bf16 v[70:73], v[216:219], v[194:197], 0
	v_mfma_f32_16x16x32_bf16 v[66:69], v[224:227], v[194:197], 0
	v_mfma_f32_16x16x32_bf16 v[110:113], v[220:223], v[174:177], v[110:113]
	v_mfma_f32_16x16x32_bf16 v[106:109], v[228:231], v[174:177], v[106:109]
	v_mfma_f32_16x16x32_bf16 v[94:97], v[220:223], v[182:185], v[94:97]
	v_mfma_f32_16x16x32_bf16 v[90:93], v[228:231], v[182:185], v[90:93]
	v_mfma_f32_16x16x32_bf16 v[78:81], v[220:223], v[190:193], v[78:81]
	v_mfma_f32_16x16x32_bf16 v[74:77], v[228:231], v[190:193], v[74:77]
	v_mfma_f32_16x16x32_bf16 v[70:73], v[220:223], v[198:201], v[70:73]
	v_mfma_f32_16x16x32_bf16 v[66:69], v[228:231], v[198:201], v[66:69]
	s_setprio 0
	s_mov_b32 m0, s71
	v_lshl_add_u64 v[234:235], s[50:51], 0, v[134:135]
	s_barrier
	ds_read_b128 v[160:163], v143 offset:16384
	ds_read_b128 v[174:177], v143 offset:17408
	ds_read_b128 v[178:181], v143 offset:18432
	ds_read_b128 v[182:185], v143 offset:19456
	ds_read_b128 v[186:189], v143 offset:20480
	ds_read_b128 v[190:193], v143 offset:21504
	ds_read_b128 v[194:197], v143 offset:22528
	ds_read_b128 v[198:201], v143 offset:23552
	global_load_lds_dwordx4 v[234:235], off
	v_lshl_add_u64 v[236:237], s[50:51], 0, v[132:133]
	s_mov_b32 m0, s72
	s_nop 0
	global_load_lds_dwordx4 v[236:237], off
	s_barrier
	s_waitcnt lgkmcnt(0)
	s_setprio 1
	v_mfma_f32_16x16x32_bf16 v[62:65], v[144:147], v[160:163], 0
	v_mfma_f32_16x16x32_bf16 v[58:61], v[152:155], v[160:163], 0
	v_mfma_f32_16x16x32_bf16 v[54:57], v[144:147], v[178:181], 0
	v_mfma_f32_16x16x32_bf16 v[50:53], v[152:155], v[178:181], 0
	v_mfma_f32_16x16x32_bf16 v[38:41], v[144:147], v[186:189], 0
	v_mfma_f32_16x16x32_bf16 v[34:37], v[152:155], v[186:189], 0
	v_mfma_f32_16x16x32_bf16 v[22:25], v[144:147], v[194:197], 0
	v_mfma_f32_16x16x32_bf16 v[18:21], v[152:155], v[194:197], 0
	v_mfma_f32_16x16x32_bf16 v[62:65], v[148:151], v[174:177], v[62:65]
	v_mfma_f32_16x16x32_bf16 v[58:61], v[156:159], v[174:177], v[58:61]
	v_mfma_f32_16x16x32_bf16 v[54:57], v[148:151], v[182:185], v[54:57]
	v_mfma_f32_16x16x32_bf16 v[50:53], v[156:159], v[182:185], v[50:53]
	v_mfma_f32_16x16x32_bf16 v[38:41], v[148:151], v[190:193], v[38:41]
	v_mfma_f32_16x16x32_bf16 v[34:37], v[156:159], v[190:193], v[34:37]
	v_mfma_f32_16x16x32_bf16 v[22:25], v[148:151], v[198:201], v[22:25]
	v_mfma_f32_16x16x32_bf16 v[18:21], v[156:159], v[198:201], v[18:21]
	s_setprio 0
	s_barrier
; #define PG8_STAGE(bufoff, gbase, voff) do { _Pragma("unroll") for (int _i = 0; _i < 2; ++_i) \
;         __builtin_amdgcn_global_load_lds((const unsigned*)((const char*)(gbase) + (voff)[_i]), (PG8_LAS unsigned*)(lds + (bufoff) + ldsw + _i * 8192), 16, 0, 0); } while (0)
; #define PG8_LDA(dst, b, h) do { _Pragma("unroll") for (int m = 0; m < 4; ++m) _Pragma("unroll") for (int k = 0; k < 2; ++k) dst[m][k] = *(const PG8_LAS bf16x8*)(lds + PG8_SA(b, h) + aoff + m * 2048 + k * 1024); } while (0)
; #define PG8_LDB(dst, b, h) do { _Pragma("unroll") for (int n = 0; n < 2; ++n) _Pragma("unroll") for (int k = 0; k < 2; ++k) dst[n][k] = *(const PG8_LAS bf16x8*)(lds + PG8_SB(b, h) + boff + n * 2048 + k * 1024); } while (0)
; #define PG8_MMA(ai, bj, At, Bt) do { __builtin_amdgcn_s_setprio(1); _Pragma("unroll") for (int m = 0; m < 4; ++m) _Pragma("unroll") for (int n = 0; n < 2; ++n) _Pragma("unroll") for (int k = 0; k < 2; ++k) \
;         acc[ai][bj][m][n] = __builtin_amdgcn_mfma_f32_16x16x32_bf16(Bt[n][k], At[m][k], acc[ai][bj][m][n], 0, 0, 0); __builtin_amdgcn_s_setprio(0); } while (0)
; #define PG8_WAIT_V(n) asm volatile("s_waitcnt vmcnt(" #n ")" ::: "memory")
; #define PG8_WAIT_L(n) asm volatile("s_waitcnt lgkmcnt(" #n ")" ::: "memory")
; #define PG8_BAR __builtin_amdgcn_s_barrier()
; #define PG8_SCHED __builtin_amdgcn_sched_barrier(0)
; template <class Epi, class Sched>
; __device__ __forceinline__ void gemm_phase(PG8_LAS unsigned char* lds, const Gemm g, const Sched& S, const Epi& E) {
;     ...
;             PG8_STAGE(PG8_SB(0, 1), b2 + hstep, voffB);
;             PG8_WAIT_V(6); PG8_BAR; PG8_MMA(1, 1, At, B1); PG8_BAR;
;             PG8_LDB(B0, 1, 0); PG8_SCHED; PG8_LDA(At, 1, 0); PG8_STAGE(PG8_SA(0, 1), a2 + hstep, voffA);
;             PG8_WAIT_L(8); PG8_BAR; PG8_WAIT_L(0); PG8_MMA(0, 0, At, B0); PG8_BAR; PG8_SCHED;
;             PG8_LDB(B1, 1, 1); PG8_STAGE(PG8_SB(1, 0), b3, voffB);
;             PG8_BAR; PG8_WAIT_L(0); PG8_MMA(0, 1, At, B1); PG8_BAR;
;             PG8_LDA(At, 1, 1); PG8_STAGE(PG8_SA(1, 0), a3, voffA);
	s_add_u32 s84, s10, 0x40000
	s_addc_u32 s85, s11, 0
	s_add_i32 s86, s86, s70
	v_lshl_add_u64 v[144:145], s[84:85], 0, v[0:1]
	s_mov_b32 m0, s86
	s_nop 0
	global_load_lds_dwordx4 v[144:145], off
	v_lshl_add_u64 v[144:145], s[84:85], 0, v[130:131]
	s_add_i32 m0, s86, 0x2000
	s_nop 0
	global_load_lds_dwordx4 v[144:145], off
	s_waitcnt vmcnt(6)
	s_barrier
	s_setprio 1
	v_mfma_f32_16x16x32_bf16 v[46:49], v[216:219], v[160:163], 0
	v_mfma_f32_16x16x32_bf16 v[42:45], v[224:227], v[160:163], 0
	v_mfma_f32_16x16x32_bf16 v[30:33], v[216:219], v[178:181], 0
	v_mfma_f32_16x16x32_bf16 v[26:29], v[224:227], v[178:181], 0
	v_mfma_f32_16x16x32_bf16 v[14:17], v[216:219], v[186:189], 0
	v_mfma_f32_16x16x32_bf16 v[10:13], v[224:227], v[186:189], 0
	v_mfma_f32_16x16x32_bf16 v[6:9], v[216:219], v[194:197], 0
	v_mfma_f32_16x16x32_bf16 v[2:5], v[224:227], v[194:197], 0
	v_mfma_f32_16x16x32_bf16 v[46:49], v[220:223], v[174:177], v[46:49]
	v_mfma_f32_16x16x32_bf16 v[42:45], v[228:231], v[174:177], v[42:45]
	v_mfma_f32_16x16x32_bf16 v[30:33], v[220:223], v[182:185], v[30:33]
	v_mfma_f32_16x16x32_bf16 v[26:29], v[228:231], v[182:185], v[26:29]
	v_mfma_f32_16x16x32_bf16 v[14:17], v[220:223], v[190:193], v[14:17]
	v_mfma_f32_16x16x32_bf16 v[10:13], v[228:231], v[190:193], v[10:13]
	v_mfma_f32_16x16x32_bf16 v[6:9], v[220:223], v[198:201], v[6:9]
	v_mfma_f32_16x16x32_bf16 v[2:5], v[228:231], v[198:201], v[2:5]
	s_setprio 0
	s_add_i32 s84, 0, 0x18000
	v_add_u32_e32 v156, s84, v141
	s_barrier
	ds_read_b128 v[144:147], v156
	ds_read_b128 v[148:151], v156 offset:1024
	ds_read_b128 v[152:155], v156 offset:2048
	ds_read_b128 v[156:159], v156 offset:3072
	s_add_u32 s50, s50, 0x40000
	s_addc_u32 s51, s51, 0
	s_mov_b32 m0, s73
	v_lshl_add_u64 v[216:217], s[50:51], 0, v[134:135]
	ds_read_b128 v[160:163], v143 offset:32768
	ds_read_b128 v[174:177], v143 offset:33792
	ds_read_b128 v[178:181], v143 offset:34816
	ds_read_b128 v[182:185], v143 offset:35840
	ds_read_b128 v[186:189], v143 offset:36864
	ds_read_b128 v[190:193], v143 offset:37888
	ds_read_b128 v[194:197], v143 offset:38912
	ds_read_b128 v[198:201], v143 offset:39936
	global_load_lds_dwordx4 v[216:217], off
	v_lshl_add_u64 v[216:217], s[50:51], 0, v[132:133]
	s_mov_b32 m0, s74
	s_nop 0
	global_load_lds_dwordx4 v[216:217], off
	s_waitcnt lgkmcnt(8)
	s_barrier
	s_waitcnt lgkmcnt(0)
	s_setprio 1
	v_mfma_f32_16x16x32_bf16 v[126:129], v[144:147], v[160:163], v[126:129]
	v_mfma_f32_16x16x32_bf16 v[122:125], v[152:155], v[160:163], v[122:125]
	v_mfma_f32_16x16x32_bf16 v[118:121], v[144:147], v[178:181], v[118:121]
	v_mfma_f32_16x16x32_bf16 v[114:117], v[152:155], v[178:181], v[114:117]
	v_mfma_f32_16x16x32_bf16 v[102:105], v[144:147], v[186:189], v[102:105]
	v_mfma_f32_16x16x32_bf16 v[98:101], v[152:155], v[186:189], v[98:101]
	v_mfma_f32_16x16x32_bf16 v[86:89], v[144:147], v[194:197], v[86:89]
	v_mfma_f32_16x16x32_bf16 v[82:85], v[152:155], v[194:197], v[82:85]
	v_mfma_f32_16x16x32_bf16 v[126:129], v[148:151], v[174:177], v[126:129]
	v_mfma_f32_16x16x32_bf16 v[122:125], v[156:159], v[174:177], v[122:125]
	v_mfma_f32_16x16x32_bf16 v[118:121], v[148:151], v[182:185], v[118:121]
	v_mfma_f32_16x16x32_bf16 v[114:117], v[156:159], v[182:185], v[114:117]
	v_mfma_f32_16x16x32_bf16 v[102:105], v[148:151], v[190:193], v[102:105]
	v_mfma_f32_16x16x32_bf16 v[98:101], v[156:159], v[190:193], v[98:101]
	v_mfma_f32_16x16x32_bf16 v[86:89], v[148:151], v[198:201], v[86:89]
	v_mfma_f32_16x16x32_bf16 v[82:85], v[156:159], v[198:201], v[82:85]
	s_setprio 0
	s_barrier
	s_add_i32 s50, 0, 0x1c000
	s_add_i32 s51, s84, s70
	v_add_u32_e32 v173, s50, v141
	v_lshl_add_u64 v[202:203], v[202:203], 0, s[8:9]
	s_mov_b32 m0, s51
	ds_read_b128 v[216:219], v173
	ds_read_b128 v[220:223], v173 offset:1024
	ds_read_b128 v[224:227], v173 offset:2048
	ds_read_b128 v[228:231], v173 offset:3072
	global_load_lds_dwordx4 v[202:203], off
	v_lshl_add_u64 v[202:203], v[232:233], 0, s[8:9]
	s_add_i32 m0, s51, 0x2000
	s_nop 0
	global_load_lds_dwordx4 v[202:203], off
	s_barrier
	s_waitcnt lgkmcnt(0)
	s_setprio 1
	v_mfma_f32_16x16x32_bf16 v[110:113], v[216:219], v[160:163], v[110:113]
	v_mfma_f32_16x16x32_bf16 v[106:109], v[224:227], v[160:163], v[106:109]
	v_mfma_f32_16x16x32_bf16 v[94:97], v[216:219], v[178:181], v[94:97]
	v_mfma_f32_16x16x32_bf16 v[90:93], v[224:227], v[178:181], v[90:93]
	v_mfma_f32_16x16x32_bf16 v[78:81], v[216:219], v[186:189], v[78:81]
	v_mfma_f32_16x16x32_bf16 v[74:77], v[224:227], v[186:189], v[74:77]
	v_mfma_f32_16x16x32_bf16 v[70:73], v[216:219], v[194:197], v[70:73]
	v_mfma_f32_16x16x32_bf16 v[66:69], v[224:227], v[194:197], v[66:69]
	v_mfma_f32_16x16x32_bf16 v[110:113], v[220:223], v[174:177], v[110:113]
	v_mfma_f32_16x16x32_bf16 v[106:109], v[228:231], v[174:177], v[106:109]
	v_mfma_f32_16x16x32_bf16 v[94:97], v[220:223], v[182:185], v[94:97]
	v_mfma_f32_16x16x32_bf16 v[90:93], v[228:231], v[182:185], v[90:93]
	v_mfma_f32_16x16x32_bf16 v[78:81], v[220:223], v[190:193], v[78:81]
	v_mfma_f32_16x16x32_bf16 v[74:77], v[228:231], v[190:193], v[74:77]
	v_mfma_f32_16x16x32_bf16 v[70:73], v[220:223], v[198:201], v[70:73]
	v_mfma_f32_16x16x32_bf16 v[66:69], v[228:231], v[198:201], v[66:69]
	s_setprio 0
	s_mov_b32 m0, s75
	v_lshl_add_u64 v[202:203], v[234:235], 0, s[8:9]
	s_barrier
	ds_read_b128 v[160:163], v143 offset:49152
	ds_read_b128 v[174:177], v143 offset:50176
	ds_read_b128 v[178:181], v143 offset:51200
	ds_read_b128 v[182:185], v143 offset:52224
	ds_read_b128 v[186:189], v143 offset:53248
	ds_read_b128 v[190:193], v143 offset:54272
	ds_read_b128 v[194:197], v143 offset:55296
	ds_read_b128 v[198:201], v143 offset:56320
	global_load_lds_dwordx4 v[202:203], off
	v_lshl_add_u64 v[202:203], v[236:237], 0, s[8:9]
	s_mov_b32 m0, s76
	s_nop 0
	global_load_lds_dwordx4 v[202:203], off
	s_barrier
; #define PG8_STAGE(bufoff, gbase, voff) do { _Pragma("unroll") for (int _i = 0; _i < 2; ++_i) \
;         __builtin_amdgcn_global_load_lds((const unsigned*)((const char*)(gbase) + (voff)[_i]), (PG8_LAS unsigned*)(lds + (bufoff) + ldsw + _i * 8192), 16, 0, 0); } while (0)
; #define PG8_LDA(dst, b, h) do { _Pragma("unroll") for (int m = 0; m < 4; ++m) _Pragma("unroll") for (int k = 0; k < 2; ++k) dst[m][k] = *(const PG8_LAS bf16x8*)(lds + PG8_SA(b, h) + aoff + m * 2048 + k * 1024); } while (0)
; #define PG8_LDB(dst, b, h) do { _Pragma("unroll") for (int n = 0; n < 2; ++n) _Pragma("unroll") for (int k = 0; k < 2; ++k) dst[n][k] = *(const PG8_LAS bf16x8*)(lds + PG8_SB(b, h) + boff + n * 2048 + k * 1024); } while (0)
; #define PG8_WAIT_V(n) asm volatile("s_waitcnt vmcnt(" #n ")" ::: "memory")
; #define PG8_WAIT_L(n) asm volatile("s_waitcnt lgkmcnt(" #n ")" ::: "memory")
; #define PG8_BAR __builtin_amdgcn_s_barrier()
; #define PG8_SCHED __builtin_amdgcn_sched_barrier(0)
; template <class Epi, class Sched>
; __device__ __forceinline__ void gemm_phase(PG8_LAS unsigned char* lds, const Gemm g, const Sched& S, const Epi& E) {
;     ...
;             PG8_LDB(B0, 0, 0); PG8_SCHED; PG8_LDA(At, 0, 0); PG8_STAGE(PG8_SA(1, 1), a1 + hstep, voffA);
;             PG8_WAIT_L(8); PG8_BAR; PG8_WAIT_L(0); PG8_MMA(0, 0, At, B0); PG8_BAR; PG8_SCHED;
;             PG8_LDB(B1, 0, 1); PG8_STAGE(PG8_SB(0, 0), b2, voffB);
;             PG8_BAR; PG8_WAIT_L(0); PG8_MMA(0, 1, At, B1); PG8_BAR;
;             PG8_LDA(At, 0, 1); PG8_STAGE(PG8_SA(0, 0), a2, voffA);
;             PG8_BAR; PG8_WAIT_L(0); PG8_MMA(1, 0, At, B0); PG8_BAR; PG8_SCHED;
;             PG8_STAGE(PG8_SB(0, 1), b2 + hstep, voffB);
;             PG8_WAIT_V(6); PG8_BAR; PG8_MMA(1, 1, At, B1); PG8_BAR;
;             PG8_LDB(B0, 1, 0); PG8_SCHED; PG8_LDA(At, 1, 0); PG8_STAGE(PG8_SA(0, 1), a2 + hstep, voffA);
;             PG8_WAIT_L(8); PG8_BAR; PG8_WAIT_L(0); PG8_MMA(0, 0, At, B0); PG8_BAR; PG8_SCHED;
;             PG8_LDB(B1, 1, 1); PG8_STAGE(PG8_SB(1, 0), b3, voffB);
;             PG8_BAR; PG8_WAIT_L(0); PG8_MMA(0, 1, At, B1); PG8_BAR;
;             PG8_LDA(At, 1, 1); PG8_STAGE(PG8_SA(1, 0), a3, voffA);
;             PG8_BAR; PG8_WAIT_L(0); PG8_MMA(1, 0, At, B0); PG8_BAR; PG8_SCHED;
;             PG8_STAGE(PG8_SB(1, 1), b3 + hstep, voffB);
;             PG8_WAIT_V(6); PG8_BAR; PG8_MMA(1, 1, At, B1); PG8_BAR;
	s_waitcnt lgkmcnt(0)
	s_setprio 1
	v_mfma_f32_16x16x32_bf16 v[62:65], v[144:147], v[160:163], v[62:65]
	v_mfma_f32_16x16x32_bf16 v[58:61], v[152:155], v[160:163], v[58:61]
	v_mfma_f32_16x16x32_bf16 v[54:57], v[144:147], v[178:181], v[54:57]
	v_mfma_f32_16x16x32_bf16 v[50:53], v[152:155], v[178:181], v[50:53]
	v_mfma_f32_16x16x32_bf16 v[38:41], v[144:147], v[186:189], v[38:41]
	v_mfma_f32_16x16x32_bf16 v[34:37], v[152:155], v[186:189], v[34:37]
	v_mfma_f32_16x16x32_bf16 v[22:25], v[144:147], v[194:197], v[22:25]
	v_mfma_f32_16x16x32_bf16 v[18:21], v[152:155], v[194:197], v[18:21]
	v_mfma_f32_16x16x32_bf16 v[62:65], v[148:151], v[174:177], v[62:65]
	v_mfma_f32_16x16x32_bf16 v[58:61], v[156:159], v[174:177], v[58:61]
	v_mfma_f32_16x16x32_bf16 v[54:57], v[148:151], v[182:185], v[54:57]
	v_mfma_f32_16x16x32_bf16 v[50:53], v[156:159], v[182:185], v[50:53]
	v_mfma_f32_16x16x32_bf16 v[38:41], v[148:151], v[190:193], v[38:41]
	v_mfma_f32_16x16x32_bf16 v[34:37], v[156:159], v[190:193], v[34:37]
	v_mfma_f32_16x16x32_bf16 v[22:25], v[148:151], v[198:201], v[22:25]
	v_mfma_f32_16x16x32_bf16 v[18:21], v[156:159], v[198:201], v[18:21]
	s_setprio 0
	s_barrier
	s_add_u32 s10, s10, 0x40080
	s_addc_u32 s11, s11, 0
	s_add_i32 s50, s50, s70
	v_lshl_add_u64 v[144:145], s[10:11], 0, v[0:1]
	s_mov_b32 m0, s50
	s_nop 0
	global_load_lds_dwordx4 v[144:145], off
	v_lshl_add_u64 v[144:145], s[10:11], 0, v[130:131]
	s_add_i32 m0, s50, 0x2000
	s_nop 0
	global_load_lds_dwordx4 v[144:145], off
	s_waitcnt vmcnt(6)
	s_barrier
	s_setprio 1
	v_mfma_f32_16x16x32_bf16 v[46:49], v[216:219], v[160:163], v[46:49]
	v_mfma_f32_16x16x32_bf16 v[42:45], v[224:227], v[160:163], v[42:45]
	v_mfma_f32_16x16x32_bf16 v[30:33], v[216:219], v[178:181], v[30:33]
	v_mfma_f32_16x16x32_bf16 v[26:29], v[224:227], v[178:181], v[26:29]
	v_mfma_f32_16x16x32_bf16 v[14:17], v[216:219], v[186:189], v[14:17]
	v_mfma_f32_16x16x32_bf16 v[10:13], v[224:227], v[186:189], v[10:13]
	v_mfma_f32_16x16x32_bf16 v[6:9], v[216:219], v[194:197], v[6:9]
	v_mfma_f32_16x16x32_bf16 v[2:5], v[224:227], v[194:197], v[2:5]
	v_mfma_f32_16x16x32_bf16 v[46:49], v[220:223], v[174:177], v[46:49]
	v_mfma_f32_16x16x32_bf16 v[42:45], v[228:231], v[174:177], v[42:45]
	v_mfma_f32_16x16x32_bf16 v[30:33], v[220:223], v[182:185], v[30:33]
	v_mfma_f32_16x16x32_bf16 v[26:29], v[228:231], v[182:185], v[26:29]
	v_mfma_f32_16x16x32_bf16 v[14:17], v[220:223], v[190:193], v[14:17]
	v_mfma_f32_16x16x32_bf16 v[10:13], v[228:231], v[190:193], v[10:13]
	v_mfma_f32_16x16x32_bf16 v[6:9], v[220:223], v[198:201], v[6:9]
	v_mfma_f32_16x16x32_bf16 v[2:5], v[228:231], v[198:201], v[2:5]
	s_setprio 0
	s_add_i32 s83, s83, 2
	s_add_u32 s40, s40, 0x100
	s_addc_u32 s41, s41, 0
	s_add_u32 s81, s81, 0x100
	s_addc_u32 s82, s82, 0
	s_cmp_gt_u32 s83, 13
	s_barrier
.LBB0_88:
	s_add_u32 s10, s40, 0xfffc0080
	s_addc_u32 s11, s41, -1
	s_add_i32 s84, 0, 0x10000
	v_add_u32_e32 v156, s84, v141
	ds_read_b128 v[144:147], v156
	ds_read_b128 v[148:151], v156 offset:1024
	ds_read_b128 v[152:155], v156 offset:2048
	ds_read_b128 v[156:159], v156 offset:3072
	s_cmp_eq_u32 s83, 12
	s_cselect_b32 s51, s19, s11
	s_cselect_b32 s50, s79, s10
	s_cselect_b32 s11, s7, s82
	s_cselect_b32 s10, s80, s81
	v_lshl_add_u64 v[202:203], s[40:41], 0, v[136:137]
	s_add_i32 m0, s71, 0xc000
	ds_read_b128 v[160:163], v143
	ds_read_b128 v[174:177], v143 offset:1024
	ds_read_b128 v[178:181], v143 offset:2048
	ds_read_b128 v[182:185], v143 offset:3072
	ds_read_b128 v[186:189], v143 offset:4096
	ds_read_b128 v[190:193], v143 offset:5120
	ds_read_b128 v[194:197], v143 offset:6144
	ds_read_b128 v[198:201], v143 offset:7168
	global_load_lds_dwordx4 v[202:203], off
	v_lshl_add_u64 v[202:203], s[40:41], 0, v[138:139]
	s_add_i32 m0, s71, 0xe000
	s_nop 0
	global_load_lds_dwordx4 v[202:203], off
	s_waitcnt lgkmcnt(8)
	s_barrier
	s_waitcnt lgkmcnt(0)
	s_setprio 1
	v_mfma_f32_16x16x32_bf16 v[126:129], v[144:147], v[160:163], v[126:129]
	v_mfma_f32_16x16x32_bf16 v[122:125], v[152:155], v[160:163], v[122:125]
	v_mfma_f32_16x16x32_bf16 v[118:121], v[144:147], v[178:181], v[118:121]
	v_mfma_f32_16x16x32_bf16 v[114:117], v[152:155], v[178:181], v[114:117]
	v_mfma_f32_16x16x32_bf16 v[102:105], v[144:147], v[186:189], v[102:105]
	v_mfma_f32_16x16x32_bf16 v[98:101], v[152:155], v[186:189], v[98:101]
	v_mfma_f32_16x16x32_bf16 v[86:89], v[144:147], v[194:197], v[86:89]
	v_mfma_f32_16x16x32_bf16 v[82:85], v[152:155], v[194:197], v[82:85]
	v_mfma_f32_16x16x32_bf16 v[126:129], v[148:151], v[174:177], v[126:129]
	v_mfma_f32_16x16x32_bf16 v[122:125], v[156:159], v[174:177], v[122:125]
	v_mfma_f32_16x16x32_bf16 v[118:121], v[148:151], v[182:185], v[118:121]
	v_mfma_f32_16x16x32_bf16 v[114:117], v[156:159], v[182:185], v[114:117]
	v_mfma_f32_16x16x32_bf16 v[102:105], v[148:151], v[190:193], v[102:105]
	v_mfma_f32_16x16x32_bf16 v[98:101], v[156:159], v[190:193], v[98:101]
	v_mfma_f32_16x16x32_bf16 v[86:89], v[148:151], v[198:201], v[86:89]
	v_mfma_f32_16x16x32_bf16 v[82:85], v[156:159], v[198:201], v[82:85]
	s_setprio 0
	s_barrier
	s_add_i32 s86, 0, 0x14000
	s_add_i32 s84, s84, s70
	v_add_u32_e32 v173, s86, v141
	v_lshl_add_u64 v[202:203], s[10:11], 0, v[0:1]
	s_mov_b32 m0, s84
	ds_read_b128 v[216:219], v173
	ds_read_b128 v[220:223], v173 offset:1024
	ds_read_b128 v[224:227], v173 offset:2048
	ds_read_b128 v[228:231], v173 offset:3072
	global_load_lds_dwordx4 v[202:203], off
	v_lshl_add_u64 v[232:233], s[10:11], 0, v[130:131]
	s_add_i32 m0, s84, 0x2000
	s_nop 0
	global_load_lds_dwordx4 v[232:233], off
	s_barrier
; #define PG8_STAGE(bufoff, gbase, voff) do { _Pragma("unroll") for (int _i = 0; _i < 2; ++_i) \
;         __builtin_amdgcn_global_load_lds((const unsigned*)((const char*)(gbase) + (voff)[_i]), (PG8_LAS unsigned*)(lds + (bufoff) + ldsw + _i * 8192), 16, 0, 0); } while (0)
; #define PG8_LDA(dst, b, h) do { _Pragma("unroll") for (int m = 0; m < 4; ++m) _Pragma("unroll") for (int k = 0; k < 2; ++k) dst[m][k] = *(const PG8_LAS bf16x8*)(lds + PG8_SA(b, h) + aoff + m * 2048 + k * 1024); } while (0)
; #define PG8_LDB(dst, b, h) do { _Pragma("unroll") for (int n = 0; n < 2; ++n) _Pragma("unroll") for (int k = 0; k < 2; ++k) dst[n][k] = *(const PG8_LAS bf16x8*)(lds + PG8_SB(b, h) + boff + n * 2048 + k * 1024); } while (0)
; #define PG8_MMA(ai, bj, At, Bt) do { __builtin_amdgcn_s_setprio(1); _Pragma("unroll") for (int m = 0; m < 4; ++m) _Pragma("unroll") for (int n = 0; n < 2; ++n) _Pragma("unroll") for (int k = 0; k < 2; ++k) \
;         acc[ai][bj][m][n] = __builtin_amdgcn_mfma_f32_16x16x32_bf16(Bt[n][k], At[m][k], acc[ai][bj][m][n], 0, 0, 0); __builtin_amdgcn_s_setprio(0); } while (0)
; #define PG8_WAIT_V(n) asm volatile("s_waitcnt vmcnt(" #n ")" ::: "memory")
; #define PG8_WAIT_L(n) asm volatile("s_waitcnt lgkmcnt(" #n ")" ::: "memory")
; #define PG8_BAR __builtin_amdgcn_s_barrier()
; #define PG8_SCHED __builtin_amdgcn_sched_barrier(0)
; template <class Epi, class Sched>
; __device__ __forceinline__ void gemm_phase(PG8_LAS unsigned char* lds, const Gemm g, const Sched& S, const Epi& E) {
;     ...
;             PG8_BAR; PG8_WAIT_L(0); PG8_MMA(0, 1, At, B1); PG8_BAR;
;             PG8_LDA(At, 0, 1); PG8_STAGE(PG8_SA(0, 0), a2, voffA);
;             PG8_BAR; PG8_WAIT_L(0); PG8_MMA(1, 0, At, B0); PG8_BAR; PG8_SCHED;
;             PG8_STAGE(PG8_SB(0, 1), b2 + hstep, voffB);
;             PG8_WAIT_V(6); PG8_BAR; PG8_MMA(1, 1, At, B1); PG8_BAR;
;             PG8_LDB(B0, 1, 0); PG8_SCHED; PG8_LDA(At, 1, 0); PG8_STAGE(PG8_SA(0, 1), a2 + hstep, voffA);
;             PG8_WAIT_L(8); PG8_BAR; PG8_WAIT_L(0); PG8_MMA(0, 0, At, B0); PG8_BAR; PG8_SCHED;
;             PG8_LDB(B1, 1, 1); PG8_STAGE(PG8_SB(1, 0), b3, voffB);
;             PG8_BAR; PG8_WAIT_L(0); PG8_MMA(0, 1, At, B1); PG8_BAR;
;             PG8_LDA(At, 1, 1); PG8_STAGE(PG8_SA(1, 0), a3, voffA);
	s_waitcnt lgkmcnt(0)
	s_setprio 1
	v_mfma_f32_16x16x32_bf16 v[110:113], v[216:219], v[160:163], v[110:113]
	v_mfma_f32_16x16x32_bf16 v[106:109], v[224:227], v[160:163], v[106:109]
	v_mfma_f32_16x16x32_bf16 v[94:97], v[216:219], v[178:181], v[94:97]
	v_mfma_f32_16x16x32_bf16 v[90:93], v[224:227], v[178:181], v[90:93]
	v_mfma_f32_16x16x32_bf16 v[78:81], v[216:219], v[186:189], v[78:81]
	v_mfma_f32_16x16x32_bf16 v[74:77], v[224:227], v[186:189], v[74:77]
	v_mfma_f32_16x16x32_bf16 v[70:73], v[216:219], v[194:197], v[70:73]
	v_mfma_f32_16x16x32_bf16 v[66:69], v[224:227], v[194:197], v[66:69]
	v_mfma_f32_16x16x32_bf16 v[110:113], v[220:223], v[174:177], v[110:113]
	v_mfma_f32_16x16x32_bf16 v[106:109], v[228:231], v[174:177], v[106:109]
	v_mfma_f32_16x16x32_bf16 v[94:97], v[220:223], v[182:185], v[94:97]
	v_mfma_f32_16x16x32_bf16 v[90:93], v[228:231], v[182:185], v[90:93]
	v_mfma_f32_16x16x32_bf16 v[78:81], v[220:223], v[190:193], v[78:81]
	v_mfma_f32_16x16x32_bf16 v[74:77], v[228:231], v[190:193], v[74:77]
	v_mfma_f32_16x16x32_bf16 v[70:73], v[220:223], v[198:201], v[70:73]
	v_mfma_f32_16x16x32_bf16 v[66:69], v[228:231], v[198:201], v[66:69]
	s_setprio 0
	s_mov_b32 m0, s71
	v_lshl_add_u64 v[234:235], s[50:51], 0, v[134:135]
	s_barrier
	ds_read_b128 v[160:163], v143 offset:16384
	ds_read_b128 v[174:177], v143 offset:17408
	ds_read_b128 v[178:181], v143 offset:18432
	ds_read_b128 v[182:185], v143 offset:19456
	ds_read_b128 v[186:189], v143 offset:20480
	ds_read_b128 v[190:193], v143 offset:21504
	ds_read_b128 v[194:197], v143 offset:22528
	ds_read_b128 v[198:201], v143 offset:23552
	global_load_lds_dwordx4 v[234:235], off
	v_lshl_add_u64 v[236:237], s[50:51], 0, v[132:133]
	s_mov_b32 m0, s72
	s_nop 0
	global_load_lds_dwordx4 v[236:237], off
	s_barrier
	s_waitcnt lgkmcnt(0)
	s_setprio 1
	v_mfma_f32_16x16x32_bf16 v[62:65], v[144:147], v[160:163], v[62:65]
	v_mfma_f32_16x16x32_bf16 v[58:61], v[152:155], v[160:163], v[58:61]
	v_mfma_f32_16x16x32_bf16 v[54:57], v[144:147], v[178:181], v[54:57]
	v_mfma_f32_16x16x32_bf16 v[50:53], v[152:155], v[178:181], v[50:53]
	v_mfma_f32_16x16x32_bf16 v[38:41], v[144:147], v[186:189], v[38:41]
	v_mfma_f32_16x16x32_bf16 v[34:37], v[152:155], v[186:189], v[34:37]
	v_mfma_f32_16x16x32_bf16 v[22:25], v[144:147], v[194:197], v[22:25]
	v_mfma_f32_16x16x32_bf16 v[18:21], v[152:155], v[194:197], v[18:21]
	v_mfma_f32_16x16x32_bf16 v[62:65], v[148:151], v[174:177], v[62:65]
	v_mfma_f32_16x16x32_bf16 v[58:61], v[156:159], v[174:177], v[58:61]
	v_mfma_f32_16x16x32_bf16 v[54:57], v[148:151], v[182:185], v[54:57]
	v_mfma_f32_16x16x32_bf16 v[50:53], v[156:159], v[182:185], v[50:53]
	v_mfma_f32_16x16x32_bf16 v[38:41], v[148:151], v[190:193], v[38:41]
	v_mfma_f32_16x16x32_bf16 v[34:37], v[156:159], v[190:193], v[34:37]
	v_mfma_f32_16x16x32_bf16 v[22:25], v[148:151], v[198:201], v[22:25]
	v_mfma_f32_16x16x32_bf16 v[18:21], v[156:159], v[198:201], v[18:21]
	s_setprio 0
	s_barrier
	s_add_u32 s84, s10, 0x40000
	s_addc_u32 s85, s11, 0
	s_add_i32 s86, s86, s70
	v_lshl_add_u64 v[144:145], s[84:85], 0, v[0:1]
	s_mov_b32 m0, s86
	s_nop 0
	global_load_lds_dwordx4 v[144:145], off
	v_lshl_add_u64 v[144:145], s[84:85], 0, v[130:131]
	s_add_i32 m0, s86, 0x2000
	s_nop 0
	global_load_lds_dwordx4 v[144:145], off
	s_waitcnt vmcnt(6)
	s_barrier
	s_setprio 1
	v_mfma_f32_16x16x32_bf16 v[46:49], v[216:219], v[160:163], v[46:49]
	v_mfma_f32_16x16x32_bf16 v[42:45], v[224:227], v[160:163], v[42:45]
	v_mfma_f32_16x16x32_bf16 v[30:33], v[216:219], v[178:181], v[30:33]
	v_mfma_f32_16x16x32_bf16 v[26:29], v[224:227], v[178:181], v[26:29]
	v_mfma_f32_16x16x32_bf16 v[14:17], v[216:219], v[186:189], v[14:17]
	v_mfma_f32_16x16x32_bf16 v[10:13], v[224:227], v[186:189], v[10:13]
	v_mfma_f32_16x16x32_bf16 v[6:9], v[216:219], v[194:197], v[6:9]
	v_mfma_f32_16x16x32_bf16 v[2:5], v[224:227], v[194:197], v[2:5]
	v_mfma_f32_16x16x32_bf16 v[46:49], v[220:223], v[174:177], v[46:49]
	v_mfma_f32_16x16x32_bf16 v[42:45], v[228:231], v[174:177], v[42:45]
	v_mfma_f32_16x16x32_bf16 v[30:33], v[220:223], v[182:185], v[30:33]
	v_mfma_f32_16x16x32_bf16 v[26:29], v[228:231], v[182:185], v[26:29]
	v_mfma_f32_16x16x32_bf16 v[14:17], v[220:223], v[190:193], v[14:17]
	v_mfma_f32_16x16x32_bf16 v[10:13], v[228:231], v[190:193], v[10:13]
	v_mfma_f32_16x16x32_bf16 v[6:9], v[220:223], v[198:201], v[6:9]
	v_mfma_f32_16x16x32_bf16 v[2:5], v[228:231], v[198:201], v[2:5]
	s_setprio 0
	s_add_i32 s84, 0, 0x18000
	v_add_u32_e32 v156, s84, v141
	s_barrier
	ds_read_b128 v[144:147], v156
	ds_read_b128 v[148:151], v156 offset:1024
	ds_read_b128 v[152:155], v156 offset:2048
	ds_read_b128 v[156:159], v156 offset:3072
	s_add_u32 s50, s50, 0x40000
	s_addc_u32 s51, s51, 0
	s_mov_b32 m0, s73
	v_lshl_add_u64 v[216:217], s[50:51], 0, v[134:135]
	ds_read_b128 v[160:163], v143 offset:32768
	ds_read_b128 v[174:177], v143 offset:33792
	ds_read_b128 v[178:181], v143 offset:34816
	ds_read_b128 v[182:185], v143 offset:35840
	ds_read_b128 v[186:189], v143 offset:36864
	ds_read_b128 v[190:193], v143 offset:37888
	ds_read_b128 v[194:197], v143 offset:38912
	ds_read_b128 v[198:201], v143 offset:39936
	global_load_lds_dwordx4 v[216:217], off
	v_lshl_add_u64 v[216:217], s[50:51], 0, v[132:133]
	s_mov_b32 m0, s74
	s_nop 0
	global_load_lds_dwordx4 v[216:217], off
	s_waitcnt lgkmcnt(8)
	s_barrier
; #define PG8_STAGE(bufoff, gbase, voff) do { _Pragma("unroll") for (int _i = 0; _i < 2; ++_i) \
;         __builtin_amdgcn_global_load_lds((const unsigned*)((const char*)(gbase) + (voff)[_i]), (PG8_LAS unsigned*)(lds + (bufoff) + ldsw + _i * 8192), 16, 0, 0); } while (0)
; #define PG8_LDA(dst, b, h) do { _Pragma("unroll") for (int m = 0; m < 4; ++m) _Pragma("unroll") for (int k = 0; k < 2; ++k) dst[m][k] = *(const PG8_LAS bf16x8*)(lds + PG8_SA(b, h) + aoff + m * 2048 + k * 1024); } while (0)
; #define PG8_LDB(dst, b, h) do { _Pragma("unroll") for (int n = 0; n < 2; ++n) _Pragma("unroll") for (int k = 0; k < 2; ++k) dst[n][k] = *(const PG8_LAS bf16x8*)(lds + PG8_SB(b, h) + boff + n * 2048 + k * 1024); } while (0)
; #define PG8_MMA(ai, bj, At, Bt) do { __builtin_amdgcn_s_setprio(1); _Pragma("unroll") for (int m = 0; m < 4; ++m) _Pragma("unroll") for (int n = 0; n < 2; ++n) _Pragma("unroll") for (int k = 0; k < 2; ++k) \
;         acc[ai][bj][m][n] = __builtin_amdgcn_mfma_f32_16x16x32_bf16(Bt[n][k], At[m][k], acc[ai][bj][m][n], 0, 0, 0); __builtin_amdgcn_s_setprio(0); } while (0)
; #define PG8_WAIT_V(n) asm volatile("s_waitcnt vmcnt(" #n ")" ::: "memory")
; #define PG8_WAIT_L(n) asm volatile("s_waitcnt lgkmcnt(" #n ")" ::: "memory")
; #define PG8_BAR __builtin_amdgcn_s_barrier()
; #define PG8_SCHED __builtin_amdgcn_sched_barrier(0)
; template <class Epi, class Sched>
; __device__ __forceinline__ void gemm_phase(PG8_LAS unsigned char* lds, const Gemm g, const Sched& S, const Epi& E) {
;     ...
;             PG8_WAIT_L(8); PG8_BAR; PG8_WAIT_L(0); PG8_MMA(0, 0, At, B0); PG8_BAR; PG8_SCHED;
;             PG8_LDB(B1, 1, 1); PG8_STAGE(PG8_SB(1, 0), b3, voffB);
;             PG8_BAR; PG8_WAIT_L(0); PG8_MMA(0, 1, At, B1); PG8_BAR;
;             PG8_LDA(At, 1, 1); PG8_STAGE(PG8_SA(1, 0), a3, voffA);
;             PG8_BAR; PG8_WAIT_L(0); PG8_MMA(1, 0, At, B0); PG8_BAR; PG8_SCHED;
;             PG8_STAGE(PG8_SB(1, 1), b3 + hstep, voffB);
;             PG8_WAIT_V(6); PG8_BAR; PG8_MMA(1, 1, At, B1); PG8_BAR;
; __device__ __forceinline__ void seg_of(int ct, int& c0, int& w) {
;     if (ct < OFF_LQ) { c0 = ct & ~1023; w = 1024; }
;     else if (ct < OFF_LG) { const int k = (ct - OFF_LQ) / 1536; c0 = OFF_LQ + k * 1536; w = 1536; }
;     else if (ct < OFF_GATE) { c0 = OFF_LG + ((ct - OFF_LG) & ~511); w = 512; }
;     else { c0 = OFF_GATE; w = 3072; }
	s_waitcnt lgkmcnt(0)
	s_setprio 1
	v_mfma_f32_16x16x32_bf16 v[126:129], v[144:147], v[160:163], v[126:129]
	v_mfma_f32_16x16x32_bf16 v[122:125], v[152:155], v[160:163], v[122:125]
	v_mfma_f32_16x16x32_bf16 v[118:121], v[144:147], v[178:181], v[118:121]
	v_mfma_f32_16x16x32_bf16 v[114:117], v[152:155], v[178:181], v[114:117]
	v_mfma_f32_16x16x32_bf16 v[102:105], v[144:147], v[186:189], v[102:105]
	v_mfma_f32_16x16x32_bf16 v[98:101], v[152:155], v[186:189], v[98:101]
	v_mfma_f32_16x16x32_bf16 v[86:89], v[144:147], v[194:197], v[86:89]
	v_mfma_f32_16x16x32_bf16 v[82:85], v[152:155], v[194:197], v[82:85]
	v_mfma_f32_16x16x32_bf16 v[126:129], v[148:151], v[174:177], v[126:129]
	v_mfma_f32_16x16x32_bf16 v[122:125], v[156:159], v[174:177], v[122:125]
	v_mfma_f32_16x16x32_bf16 v[118:121], v[148:151], v[182:185], v[118:121]
	v_mfma_f32_16x16x32_bf16 v[114:117], v[156:159], v[182:185], v[114:117]
	v_mfma_f32_16x16x32_bf16 v[102:105], v[148:151], v[190:193], v[102:105]
	v_mfma_f32_16x16x32_bf16 v[98:101], v[156:159], v[190:193], v[98:101]
	v_mfma_f32_16x16x32_bf16 v[86:89], v[148:151], v[198:201], v[86:89]
	v_mfma_f32_16x16x32_bf16 v[82:85], v[156:159], v[198:201], v[82:85]
	s_setprio 0
	s_barrier
	s_add_i32 s50, 0, 0x1c000
	s_add_i32 s51, s84, s70
	v_add_u32_e32 v173, s50, v141
	v_lshl_add_u64 v[202:203], v[202:203], 0, s[8:9]
	s_mov_b32 m0, s51
	ds_read_b128 v[216:219], v173
	ds_read_b128 v[220:223], v173 offset:1024
	ds_read_b128 v[224:227], v173 offset:2048
	ds_read_b128 v[228:231], v173 offset:3072
	global_load_lds_dwordx4 v[202:203], off
	v_lshl_add_u64 v[202:203], v[232:233], 0, s[8:9]
	s_add_i32 m0, s51, 0x2000
	s_nop 0
	global_load_lds_dwordx4 v[202:203], off
	s_barrier
	s_waitcnt lgkmcnt(0)
	s_setprio 1
	v_mfma_f32_16x16x32_bf16 v[110:113], v[216:219], v[160:163], v[110:113]
	v_mfma_f32_16x16x32_bf16 v[106:109], v[224:227], v[160:163], v[106:109]
	v_mfma_f32_16x16x32_bf16 v[94:97], v[216:219], v[178:181], v[94:97]
	v_mfma_f32_16x16x32_bf16 v[90:93], v[224:227], v[178:181], v[90:93]
	v_mfma_f32_16x16x32_bf16 v[78:81], v[216:219], v[186:189], v[78:81]
	v_mfma_f32_16x16x32_bf16 v[74:77], v[224:227], v[186:189], v[74:77]
	v_mfma_f32_16x16x32_bf16 v[70:73], v[216:219], v[194:197], v[70:73]
	v_mfma_f32_16x16x32_bf16 v[66:69], v[224:227], v[194:197], v[66:69]
	v_mfma_f32_16x16x32_bf16 v[110:113], v[220:223], v[174:177], v[110:113]
	v_mfma_f32_16x16x32_bf16 v[106:109], v[228:231], v[174:177], v[106:109]
	v_mfma_f32_16x16x32_bf16 v[94:97], v[220:223], v[182:185], v[94:97]
	v_mfma_f32_16x16x32_bf16 v[90:93], v[228:231], v[182:185], v[90:93]
	v_mfma_f32_16x16x32_bf16 v[78:81], v[220:223], v[190:193], v[78:81]
	v_mfma_f32_16x16x32_bf16 v[74:77], v[228:231], v[190:193], v[74:77]
	v_mfma_f32_16x16x32_bf16 v[70:73], v[220:223], v[198:201], v[70:73]
	v_mfma_f32_16x16x32_bf16 v[66:69], v[228:231], v[198:201], v[66:69]
	s_setprio 0
	s_mov_b32 m0, s75
	v_lshl_add_u64 v[202:203], v[234:235], 0, s[8:9]
	s_barrier
	ds_read_b128 v[160:163], v143 offset:49152
	ds_read_b128 v[174:177], v143 offset:50176
	ds_read_b128 v[178:181], v143 offset:51200
	ds_read_b128 v[182:185], v143 offset:52224
	ds_read_b128 v[186:189], v143 offset:53248
	ds_read_b128 v[190:193], v143 offset:54272
	ds_read_b128 v[194:197], v143 offset:55296
	ds_read_b128 v[198:201], v143 offset:56320
	global_load_lds_dwordx4 v[202:203], off
	v_lshl_add_u64 v[202:203], v[236:237], 0, s[8:9]
	s_mov_b32 m0, s76
	s_nop 0
	global_load_lds_dwordx4 v[202:203], off
	s_barrier
	s_waitcnt lgkmcnt(0)
	s_setprio 1
	v_mfma_f32_16x16x32_bf16 v[62:65], v[144:147], v[160:163], v[62:65]
	v_mfma_f32_16x16x32_bf16 v[58:61], v[152:155], v[160:163], v[58:61]
	v_mfma_f32_16x16x32_bf16 v[54:57], v[144:147], v[178:181], v[54:57]
	v_mfma_f32_16x16x32_bf16 v[50:53], v[152:155], v[178:181], v[50:53]
	v_mfma_f32_16x16x32_bf16 v[38:41], v[144:147], v[186:189], v[38:41]
	v_mfma_f32_16x16x32_bf16 v[34:37], v[152:155], v[186:189], v[34:37]
	v_mfma_f32_16x16x32_bf16 v[22:25], v[144:147], v[194:197], v[22:25]
	v_mfma_f32_16x16x32_bf16 v[18:21], v[152:155], v[194:197], v[18:21]
	v_mfma_f32_16x16x32_bf16 v[62:65], v[148:151], v[174:177], v[62:65]
	v_mfma_f32_16x16x32_bf16 v[58:61], v[156:159], v[174:177], v[58:61]
	v_mfma_f32_16x16x32_bf16 v[54:57], v[148:151], v[182:185], v[54:57]
	v_mfma_f32_16x16x32_bf16 v[50:53], v[156:159], v[182:185], v[50:53]
	v_mfma_f32_16x16x32_bf16 v[38:41], v[148:151], v[190:193], v[38:41]
	v_mfma_f32_16x16x32_bf16 v[34:37], v[156:159], v[190:193], v[34:37]
	v_mfma_f32_16x16x32_bf16 v[22:25], v[148:151], v[198:201], v[22:25]
	v_mfma_f32_16x16x32_bf16 v[18:21], v[156:159], v[198:201], v[18:21]
	s_setprio 0
	s_barrier
	s_add_u32 s10, s10, 0x40080
	s_addc_u32 s11, s11, 0
	s_add_i32 s50, s50, s70
	v_lshl_add_u64 v[144:145], s[10:11], 0, v[0:1]
	s_mov_b32 m0, s50
	s_nop 0
	global_load_lds_dwordx4 v[144:145], off
	v_lshl_add_u64 v[144:145], s[10:11], 0, v[130:131]
	s_add_i32 m0, s50, 0x2000
	s_nop 0
	global_load_lds_dwordx4 v[144:145], off
	s_waitcnt vmcnt(6)
	s_barrier
	s_setprio 1
	v_mfma_f32_16x16x32_bf16 v[46:49], v[216:219], v[160:163], v[46:49]
	v_mfma_f32_16x16x32_bf16 v[42:45], v[224:227], v[160:163], v[42:45]
	v_mfma_f32_16x16x32_bf16 v[30:33], v[216:219], v[178:181], v[30:33]
	v_mfma_f32_16x16x32_bf16 v[26:29], v[224:227], v[178:181], v[26:29]
	v_mfma_f32_16x16x32_bf16 v[14:17], v[216:219], v[186:189], v[14:17]
	v_mfma_f32_16x16x32_bf16 v[10:13], v[224:227], v[186:189], v[10:13]
	v_mfma_f32_16x16x32_bf16 v[6:9], v[216:219], v[194:197], v[6:9]
	v_mfma_f32_16x16x32_bf16 v[2:5], v[224:227], v[194:197], v[2:5]
	v_mfma_f32_16x16x32_bf16 v[46:49], v[220:223], v[174:177], v[46:49]
	v_mfma_f32_16x16x32_bf16 v[42:45], v[228:231], v[174:177], v[42:45]
	v_mfma_f32_16x16x32_bf16 v[30:33], v[220:223], v[182:185], v[30:33]
	v_mfma_f32_16x16x32_bf16 v[26:29], v[228:231], v[182:185], v[26:29]
	v_mfma_f32_16x16x32_bf16 v[14:17], v[220:223], v[190:193], v[14:17]
	v_mfma_f32_16x16x32_bf16 v[10:13], v[228:231], v[190:193], v[10:13]
	v_mfma_f32_16x16x32_bf16 v[6:9], v[220:223], v[198:201], v[6:9]
	v_mfma_f32_16x16x32_bf16 v[2:5], v[228:231], v[198:201], v[2:5]
	s_setprio 0
	s_add_i32 s83, s83, 2
	s_add_u32 s40, s40, 0x100
	s_addc_u32 s41, s41, 0
	s_add_u32 s81, s81, 0x100
	s_addc_u32 s82, s82, 0
	s_cmp_gt_u32 s83, 13
	s_barrier
	s_cbranch_scc0 .LBB0_88
	s_lshl_b32 s7, s28, 8
	s_cmp_gt_i32 s28, 15
	s_mov_b64 s[50:51], -1
	s_cbranch_scc0 .LBB0_95
	s_cmpk_gt_u32 s7, 0x21ff
	s_cbranch_scc0 .LBB0_92
	s_min_u32 s10, s7, 0x2800
	s_and_b32 s40, s10, 0x3e00
	s_cmpk_lt_u32 s7, 0x2800
	s_movk_i32 s10, 0x200
	s_cselect_b32 s28, s10, 0xc00
	s_mov_b64 s[50:51], 0
	s_mov_b64 s[10:11], s[28:29]

; #define PG8_STAGE(bufoff, gbase, voff) do { _Pragma("unroll") for (int _i = 0; _i < 2; ++_i) \
;         __builtin_amdgcn_global_load_lds((const unsigned*)((const char*)(gbase) + (voff)[_i]), (PG8_LAS unsigned*)(lds + (bufoff) + ldsw + _i * 8192), 16, 0, 0); } while (0)
; #define PG8_LDA(dst, b, h) do { _Pragma("unroll") for (int m = 0; m < 4; ++m) _Pragma("unroll") for (int k = 0; k < 2; ++k) dst[m][k] = *(const PG8_LAS bf16x8*)(lds + PG8_SA(b, h) + aoff + m * 2048 + k * 1024); } while (0)
; #define PG8_LDB(dst, b, h) do { _Pragma("unroll") for (int n = 0; n < 2; ++n) _Pragma("unroll") for (int k = 0; k < 2; ++k) dst[n][k] = *(const PG8_LAS bf16x8*)(lds + PG8_SB(b, h) + boff + n * 2048 + k * 1024); } while (0)
; #define PG8_MMA(ai, bj, At, Bt) do { __builtin_amdgcn_s_setprio(1); _Pragma("unroll") for (int m = 0; m < 4; ++m) _Pragma("unroll") for (int n = 0; n < 2; ++n) _Pragma("unroll") for (int k = 0; k < 2; ++k) \
;         acc[ai][bj][m][n] = __builtin_amdgcn_mfma_f32_16x16x32_bf16(Bt[n][k], At[m][k], acc[ai][bj][m][n], 0, 0, 0); __builtin_amdgcn_s_setprio(0); } while (0)
; #define PG8_WAIT_V(n) asm volatile("s_waitcnt vmcnt(" #n ")" ::: "memory")
; #define PG8_WAIT_L(n) asm volatile("s_waitcnt lgkmcnt(" #n ")" ::: "memory")
; #define PG8_BAR __builtin_amdgcn_s_barrier()
; #define PG8_SCHED __builtin_amdgcn_sched_barrier(0)
; template <class Epi, class Sched>
; __device__ __forceinline__ void gemm_phase(PG8_LAS unsigned char* lds, const Gemm g, const Sched& S, const Epi& E) {
;     ...
;             PG8_LDB(B0, 0, 0); PG8_SCHED; PG8_LDA(At, 0, 0); PG8_STAGE(PG8_SA(1, 1), a1 + hstep, voffA);
;             PG8_WAIT_L(8); PG8_BAR; PG8_WAIT_L(0); PG8_MMA(0, 0, At, B0); PG8_BAR; PG8_SCHED;
;             PG8_LDB(B1, 0, 1); PG8_STAGE(PG8_SB(0, 0), b2, voffB);
;             PG8_BAR; PG8_WAIT_L(0); PG8_MMA(0, 1, At, B1); PG8_BAR;
;             PG8_LDA(At, 0, 1); PG8_STAGE(PG8_SA(0, 0), a2, voffA);
;             PG8_BAR; PG8_WAIT_L(0); PG8_MMA(1, 0, At, B0); PG8_BAR; PG8_SCHED;
;             PG8_STAGE(PG8_SB(0, 1), b2 + hstep, voffB);
;             PG8_WAIT_V(6); PG8_BAR; PG8_MMA(1, 1, At, B1); PG8_BAR;
.LBB0_472:
	s_add_u32 s6, s50, 0xfff80080
	s_addc_u32 s7, s51, -1
	s_add_i32 s85, 0, 0x10000
	v_add_u32_e32 v0, s85, v222
	ds_read_b128 v[132:135], v0
	ds_read_b128 v[136:139], v0 offset:1024
	ds_read_b128 v[140:143], v0 offset:2048
	ds_read_b128 v[144:147], v0 offset:3072
	s_cmp_eq_u32 s84, 4
	s_cselect_b32 s53, s19, s7
	s_cselect_b32 s52, s41, s6
	s_cselect_b32 s7, s39, s83
	s_cselect_b32 s6, s81, s82
	v_lshl_add_u64 v[2:3], s[50:51], 0, v[182:183]
	s_add_i32 m0, s71, 0xc000
	ds_read_b128 v[148:151], v224
	ds_read_b128 v[152:155], v224 offset:1024
	ds_read_b128 v[156:159], v224 offset:2048
	ds_read_b128 v[160:163], v224 offset:3072
	ds_read_b128 v[186:189], v224 offset:4096
	ds_read_b128 v[190:193], v224 offset:5120
	ds_read_b128 v[194:197], v224 offset:6144
	ds_read_b128 v[198:201], v224 offset:7168
	global_load_lds_dwordx4 v[2:3], off
	v_lshl_add_u64 v[2:3], s[50:51], 0, v[184:185]
	s_add_i32 m0, s71, 0xe000
	s_nop 0
	global_load_lds_dwordx4 v[2:3], off
	s_waitcnt lgkmcnt(8)
	s_barrier
	s_waitcnt lgkmcnt(0)
	s_setprio 1
	v_mfma_f32_16x16x32_bf16 v[2:5], v[132:135], v[148:151], v[4:7]
	v_mfma_f32_16x16x32_bf16 v[6:9], v[140:143], v[148:151], v[8:11]
	v_mfma_f32_16x16x32_bf16 v[12:15], v[132:135], v[156:159], v[12:15]
	v_mfma_f32_16x16x32_bf16 v[16:19], v[140:143], v[156:159], v[16:19]
	v_mfma_f32_16x16x32_bf16 v[20:23], v[132:135], v[186:189], v[20:23]
	v_mfma_f32_16x16x32_bf16 v[24:27], v[140:143], v[186:189], v[24:27]
	v_mfma_f32_16x16x32_bf16 v[28:31], v[132:135], v[194:197], v[28:31]
	v_mfma_f32_16x16x32_bf16 v[32:35], v[140:143], v[194:197], v[32:35]
	v_mfma_f32_16x16x32_bf16 v[2:5], v[136:139], v[152:155], v[2:5]
	v_mfma_f32_16x16x32_bf16 v[8:11], v[144:147], v[152:155], v[6:9]
	v_mfma_f32_16x16x32_bf16 v[12:15], v[136:139], v[160:163], v[12:15]
	v_mfma_f32_16x16x32_bf16 v[16:19], v[144:147], v[160:163], v[16:19]
	v_mfma_f32_16x16x32_bf16 v[20:23], v[136:139], v[190:193], v[20:23]
	v_mfma_f32_16x16x32_bf16 v[24:27], v[144:147], v[190:193], v[24:27]
	v_mfma_f32_16x16x32_bf16 v[28:31], v[136:139], v[198:201], v[28:31]
	v_mfma_f32_16x16x32_bf16 v[32:35], v[144:147], v[198:201], v[32:35]
	s_setprio 0
	s_barrier
	s_add_i32 s88, 0, 0x14000
	s_add_i32 s85, s85, s70
	v_add_u32_e32 v0, s88, v222
	v_lshl_add_u64 v[202:203], s[6:7], 0, v[178:179]
	s_mov_b32 m0, s85
	ds_read_b128 v[226:229], v0
	ds_read_b128 v[230:233], v0 offset:1024
	ds_read_b128 v[234:237], v0 offset:2048
	ds_read_b128 v[238:241], v0 offset:3072
	global_load_lds_dwordx4 v[202:203], off
	v_lshl_add_u64 v[242:243], s[6:7], 0, v[174:175]
	s_add_i32 m0, s85, 0x2000
	s_nop 0
	global_load_lds_dwordx4 v[242:243], off
	s_barrier
	s_waitcnt lgkmcnt(0)
	s_setprio 1
	v_mfma_f32_16x16x32_bf16 v[36:39], v[226:229], v[148:151], v[36:39]
	v_mfma_f32_16x16x32_bf16 v[40:43], v[234:237], v[148:151], v[40:43]
	v_mfma_f32_16x16x32_bf16 v[44:47], v[226:229], v[156:159], v[44:47]
	v_mfma_f32_16x16x32_bf16 v[48:51], v[234:237], v[156:159], v[48:51]
	v_mfma_f32_16x16x32_bf16 v[52:55], v[226:229], v[186:189], v[52:55]
	v_mfma_f32_16x16x32_bf16 v[56:59], v[234:237], v[186:189], v[56:59]
	v_mfma_f32_16x16x32_bf16 v[60:63], v[226:229], v[194:197], v[60:63]
	v_mfma_f32_16x16x32_bf16 v[64:67], v[234:237], v[194:197], v[64:67]
	v_mfma_f32_16x16x32_bf16 v[36:39], v[230:233], v[152:155], v[36:39]
	v_mfma_f32_16x16x32_bf16 v[40:43], v[238:241], v[152:155], v[40:43]
	v_mfma_f32_16x16x32_bf16 v[44:47], v[230:233], v[160:163], v[44:47]
	v_mfma_f32_16x16x32_bf16 v[48:51], v[238:241], v[160:163], v[48:51]
	v_mfma_f32_16x16x32_bf16 v[52:55], v[230:233], v[190:193], v[52:55]
	v_mfma_f32_16x16x32_bf16 v[56:59], v[238:241], v[190:193], v[56:59]
	v_mfma_f32_16x16x32_bf16 v[60:63], v[230:233], v[198:201], v[60:63]
	v_mfma_f32_16x16x32_bf16 v[64:67], v[238:241], v[198:201], v[64:67]
	s_setprio 0
	s_mov_b32 m0, s71
	v_lshl_add_u64 v[244:245], s[52:53], 0, v[180:181]
	s_barrier
	ds_read_b128 v[148:151], v224 offset:16384
	ds_read_b128 v[152:155], v224 offset:17408
	ds_read_b128 v[156:159], v224 offset:18432
	ds_read_b128 v[160:163], v224 offset:19456
	ds_read_b128 v[186:189], v224 offset:20480
	ds_read_b128 v[190:193], v224 offset:21504
	ds_read_b128 v[194:197], v224 offset:22528
	ds_read_b128 v[198:201], v224 offset:23552
	global_load_lds_dwordx4 v[244:245], off
	v_lshl_add_u64 v[246:247], s[52:53], 0, v[176:177]
	s_mov_b32 m0, s72
	s_nop 0
	global_load_lds_dwordx4 v[246:247], off
	s_barrier
	s_waitcnt lgkmcnt(0)
	s_setprio 1
	v_mfma_f32_16x16x32_bf16 v[68:71], v[132:135], v[148:151], v[68:71]
	v_mfma_f32_16x16x32_bf16 v[72:75], v[140:143], v[148:151], v[72:75]
	v_mfma_f32_16x16x32_bf16 v[76:79], v[132:135], v[156:159], v[76:79]
	v_mfma_f32_16x16x32_bf16 v[80:83], v[140:143], v[156:159], v[80:83]
	v_mfma_f32_16x16x32_bf16 v[84:87], v[132:135], v[186:189], v[84:87]
	v_mfma_f32_16x16x32_bf16 v[88:91], v[140:143], v[186:189], v[88:91]
	v_mfma_f32_16x16x32_bf16 v[92:95], v[132:135], v[194:197], v[92:95]
	v_mfma_f32_16x16x32_bf16 v[96:99], v[140:143], v[194:197], v[96:99]
	v_mfma_f32_16x16x32_bf16 v[68:71], v[136:139], v[152:155], v[68:71]
	v_mfma_f32_16x16x32_bf16 v[72:75], v[144:147], v[152:155], v[72:75]
	v_mfma_f32_16x16x32_bf16 v[76:79], v[136:139], v[160:163], v[76:79]
	v_mfma_f32_16x16x32_bf16 v[80:83], v[144:147], v[160:163], v[80:83]
	v_mfma_f32_16x16x32_bf16 v[84:87], v[136:139], v[190:193], v[84:87]
	v_mfma_f32_16x16x32_bf16 v[88:91], v[144:147], v[190:193], v[88:91]
	v_mfma_f32_16x16x32_bf16 v[92:95], v[136:139], v[198:201], v[92:95]
	v_mfma_f32_16x16x32_bf16 v[96:99], v[144:147], v[198:201], v[96:99]
	s_setprio 0
	s_barrier
; #define PG8_STAGE(bufoff, gbase, voff) do { _Pragma("unroll") for (int _i = 0; _i < 2; ++_i) \
;         __builtin_amdgcn_global_load_lds((const unsigned*)((const char*)(gbase) + (voff)[_i]), (PG8_LAS unsigned*)(lds + (bufoff) + ldsw + _i * 8192), 16, 0, 0); } while (0)
; #define PG8_LDA(dst, b, h) do { _Pragma("unroll") for (int m = 0; m < 4; ++m) _Pragma("unroll") for (int k = 0; k < 2; ++k) dst[m][k] = *(const PG8_LAS bf16x8*)(lds + PG8_SA(b, h) + aoff + m * 2048 + k * 1024); } while (0)
; #define PG8_LDB(dst, b, h) do { _Pragma("unroll") for (int n = 0; n < 2; ++n) _Pragma("unroll") for (int k = 0; k < 2; ++k) dst[n][k] = *(const PG8_LAS bf16x8*)(lds + PG8_SB(b, h) + boff + n * 2048 + k * 1024); } while (0)
; #define PG8_MMA(ai, bj, At, Bt) do { __builtin_amdgcn_s_setprio(1); _Pragma("unroll") for (int m = 0; m < 4; ++m) _Pragma("unroll") for (int n = 0; n < 2; ++n) _Pragma("unroll") for (int k = 0; k < 2; ++k) \
;         acc[ai][bj][m][n] = __builtin_amdgcn_mfma_f32_16x16x32_bf16(Bt[n][k], At[m][k], acc[ai][bj][m][n], 0, 0, 0); __builtin_amdgcn_s_setprio(0); } while (0)
; #define PG8_WAIT_V(n) asm volatile("s_waitcnt vmcnt(" #n ")" ::: "memory")
; #define PG8_WAIT_L(n) asm volatile("s_waitcnt lgkmcnt(" #n ")" ::: "memory")
; #define PG8_BAR __builtin_amdgcn_s_barrier()
; #define PG8_SCHED __builtin_amdgcn_sched_barrier(0)
; template <class Epi, class Sched>
; __device__ __forceinline__ void gemm_phase(PG8_LAS unsigned char* lds, const Gemm g, const Sched& S, const Epi& E) {
;     ...
;             PG8_STAGE(PG8_SB(0, 1), b2 + hstep, voffB);
;             PG8_WAIT_V(6); PG8_BAR; PG8_MMA(1, 1, At, B1); PG8_BAR;
;             PG8_LDB(B0, 1, 0); PG8_SCHED; PG8_LDA(At, 1, 0); PG8_STAGE(PG8_SA(0, 1), a2 + hstep, voffA);
;             PG8_WAIT_L(8); PG8_BAR; PG8_WAIT_L(0); PG8_MMA(0, 0, At, B0); PG8_BAR; PG8_SCHED;
;             PG8_LDB(B1, 1, 1); PG8_STAGE(PG8_SB(1, 0), b3, voffB);
;             PG8_BAR; PG8_WAIT_L(0); PG8_MMA(0, 1, At, B1); PG8_BAR;
;             PG8_LDA(At, 1, 1); PG8_STAGE(PG8_SA(1, 0), a3, voffA);
	s_add_u32 s86, s6, 0x80000
	s_addc_u32 s87, s7, 0
	s_add_i32 s85, s88, s70
	v_lshl_add_u64 v[6:7], s[86:87], 0, v[178:179]
	s_mov_b32 m0, s85
	s_nop 0
	global_load_lds_dwordx4 v[6:7], off
	v_lshl_add_u64 v[6:7], s[86:87], 0, v[174:175]
	s_add_i32 m0, s85, 0x2000
	s_nop 0
	global_load_lds_dwordx4 v[6:7], off
	s_waitcnt vmcnt(6)
	s_barrier
	s_setprio 1
	v_mfma_f32_16x16x32_bf16 v[100:103], v[226:229], v[148:151], v[100:103]
	v_mfma_f32_16x16x32_bf16 v[104:107], v[234:237], v[148:151], v[104:107]
	v_mfma_f32_16x16x32_bf16 v[108:111], v[226:229], v[156:159], v[108:111]
	v_mfma_f32_16x16x32_bf16 v[112:115], v[234:237], v[156:159], v[112:115]
	v_mfma_f32_16x16x32_bf16 v[116:119], v[226:229], v[186:189], v[116:119]
	v_mfma_f32_16x16x32_bf16 v[120:123], v[234:237], v[186:189], v[120:123]
	v_mfma_f32_16x16x32_bf16 v[124:127], v[226:229], v[194:197], v[124:127]
	v_mfma_f32_16x16x32_bf16 v[128:131], v[234:237], v[194:197], v[128:131]
	v_mfma_f32_16x16x32_bf16 v[100:103], v[230:233], v[152:155], v[100:103]
	v_mfma_f32_16x16x32_bf16 v[104:107], v[238:241], v[152:155], v[104:107]
	v_mfma_f32_16x16x32_bf16 v[108:111], v[230:233], v[160:163], v[108:111]
	v_mfma_f32_16x16x32_bf16 v[112:115], v[238:241], v[160:163], v[112:115]
	v_mfma_f32_16x16x32_bf16 v[116:119], v[230:233], v[190:193], v[116:119]
	v_mfma_f32_16x16x32_bf16 v[120:123], v[238:241], v[190:193], v[120:123]
	v_mfma_f32_16x16x32_bf16 v[124:127], v[230:233], v[198:201], v[124:127]
	v_mfma_f32_16x16x32_bf16 v[128:131], v[238:241], v[198:201], v[128:131]
	s_setprio 0
	s_add_i32 s85, 0, 0x18000
	v_add_u32_e32 v0, s85, v222
	s_barrier
	ds_read_b128 v[132:135], v0
	ds_read_b128 v[136:139], v0 offset:1024
	ds_read_b128 v[140:143], v0 offset:2048
	ds_read_b128 v[144:147], v0 offset:3072
	s_add_u32 s52, s52, 0x80000
	s_addc_u32 s53, s53, 0
	s_mov_b32 m0, s73
	v_lshl_add_u64 v[6:7], s[52:53], 0, v[180:181]
	ds_read_b128 v[148:151], v224 offset:32768
	ds_read_b128 v[152:155], v224 offset:33792
	ds_read_b128 v[156:159], v224 offset:34816
	ds_read_b128 v[160:163], v224 offset:35840
	ds_read_b128 v[186:189], v224 offset:36864
	ds_read_b128 v[190:193], v224 offset:37888
	ds_read_b128 v[194:197], v224 offset:38912
	ds_read_b128 v[198:201], v224 offset:39936
	global_load_lds_dwordx4 v[6:7], off
	v_lshl_add_u64 v[6:7], s[52:53], 0, v[176:177]
	s_mov_b32 m0, s74
	s_nop 0
	global_load_lds_dwordx4 v[6:7], off
	s_waitcnt lgkmcnt(8)
	s_barrier
	s_waitcnt lgkmcnt(0)
	s_setprio 1
	v_mfma_f32_16x16x32_bf16 v[2:5], v[132:135], v[148:151], v[2:5]
	v_mfma_f32_16x16x32_bf16 v[8:11], v[140:143], v[148:151], v[8:11]
	v_mfma_f32_16x16x32_bf16 v[12:15], v[132:135], v[156:159], v[12:15]
	v_mfma_f32_16x16x32_bf16 v[16:19], v[140:143], v[156:159], v[16:19]
	v_mfma_f32_16x16x32_bf16 v[20:23], v[132:135], v[186:189], v[20:23]
	v_mfma_f32_16x16x32_bf16 v[24:27], v[140:143], v[186:189], v[24:27]
	v_mfma_f32_16x16x32_bf16 v[28:31], v[132:135], v[194:197], v[28:31]
	v_mfma_f32_16x16x32_bf16 v[32:35], v[140:143], v[194:197], v[32:35]
	v_mfma_f32_16x16x32_bf16 v[4:7], v[136:139], v[152:155], v[2:5]
	v_mfma_f32_16x16x32_bf16 v[8:11], v[144:147], v[152:155], v[8:11]
	v_mfma_f32_16x16x32_bf16 v[12:15], v[136:139], v[160:163], v[12:15]
	v_mfma_f32_16x16x32_bf16 v[16:19], v[144:147], v[160:163], v[16:19]
	v_mfma_f32_16x16x32_bf16 v[20:23], v[136:139], v[190:193], v[20:23]
	v_mfma_f32_16x16x32_bf16 v[24:27], v[144:147], v[190:193], v[24:27]
	v_mfma_f32_16x16x32_bf16 v[28:31], v[136:139], v[198:201], v[28:31]
	v_mfma_f32_16x16x32_bf16 v[32:35], v[144:147], v[198:201], v[32:35]
	s_setprio 0
	s_barrier
	s_add_i32 s52, 0, 0x1c000
	s_add_i32 s53, s85, s70
	v_add_u32_e32 v0, s52, v222
	v_lshl_add_u64 v[2:3], v[202:203], 0, s[8:9]
	s_mov_b32 m0, s53
	ds_read_b128 v[226:229], v0
	ds_read_b128 v[230:233], v0 offset:1024
	ds_read_b128 v[234:237], v0 offset:2048
	ds_read_b128 v[238:241], v0 offset:3072
	global_load_lds_dwordx4 v[2:3], off
	v_lshl_add_u64 v[2:3], v[242:243], 0, s[8:9]
	s_add_i32 m0, s53, 0x2000
	s_nop 0
	global_load_lds_dwordx4 v[2:3], off
	s_barrier
	s_waitcnt lgkmcnt(0)
	s_setprio 1
	v_mfma_f32_16x16x32_bf16 v[36:39], v[226:229], v[148:151], v[36:39]
	v_mfma_f32_16x16x32_bf16 v[40:43], v[234:237], v[148:151], v[40:43]
	v_mfma_f32_16x16x32_bf16 v[44:47], v[226:229], v[156:159], v[44:47]
	v_mfma_f32_16x16x32_bf16 v[48:51], v[234:237], v[156:159], v[48:51]
	v_mfma_f32_16x16x32_bf16 v[52:55], v[226:229], v[186:189], v[52:55]
	v_mfma_f32_16x16x32_bf16 v[56:59], v[234:237], v[186:189], v[56:59]
	v_mfma_f32_16x16x32_bf16 v[60:63], v[226:229], v[194:197], v[60:63]
	v_mfma_f32_16x16x32_bf16 v[64:67], v[234:237], v[194:197], v[64:67]
	v_mfma_f32_16x16x32_bf16 v[36:39], v[230:233], v[152:155], v[36:39]
	v_mfma_f32_16x16x32_bf16 v[40:43], v[238:241], v[152:155], v[40:43]
	v_mfma_f32_16x16x32_bf16 v[44:47], v[230:233], v[160:163], v[44:47]
	v_mfma_f32_16x16x32_bf16 v[48:51], v[238:241], v[160:163], v[48:51]
	v_mfma_f32_16x16x32_bf16 v[52:55], v[230:233], v[190:193], v[52:55]
	v_mfma_f32_16x16x32_bf16 v[56:59], v[238:241], v[190:193], v[56:59]
	v_mfma_f32_16x16x32_bf16 v[60:63], v[230:233], v[198:201], v[60:63]
	v_mfma_f32_16x16x32_bf16 v[64:67], v[238:241], v[198:201], v[64:67]
	s_setprio 0
	s_mov_b32 m0, s75
	v_lshl_add_u64 v[2:3], v[244:245], 0, s[8:9]
	s_barrier
	ds_read_b128 v[148:151], v224 offset:49152
	ds_read_b128 v[152:155], v224 offset:50176
	ds_read_b128 v[156:159], v224 offset:51200
	ds_read_b128 v[160:163], v224 offset:52224
	ds_read_b128 v[186:189], v224 offset:53248
	ds_read_b128 v[190:193], v224 offset:54272
	ds_read_b128 v[194:197], v224 offset:55296
	ds_read_b128 v[198:201], v224 offset:56320
	global_load_lds_dwordx4 v[2:3], off
	v_lshl_add_u64 v[2:3], v[246:247], 0, s[8:9]
	s_mov_b32 m0, s76
	s_nop 0
	global_load_lds_dwordx4 v[2:3], off
	s_barrier
; #define PG8_STAGE(bufoff, gbase, voff) do { _Pragma("unroll") for (int _i = 0; _i < 2; ++_i) \
;         __builtin_amdgcn_global_load_lds((const unsigned*)((const char*)(gbase) + (voff)[_i]), (PG8_LAS unsigned*)(lds + (bufoff) + ldsw + _i * 8192), 16, 0, 0); } while (0)
; #define PG8_MMA(ai, bj, At, Bt) do { __builtin_amdgcn_s_setprio(1); _Pragma("unroll") for (int m = 0; m < 4; ++m) _Pragma("unroll") for (int n = 0; n < 2; ++n) _Pragma("unroll") for (int k = 0; k < 2; ++k) \
;         acc[ai][bj][m][n] = __builtin_amdgcn_mfma_f32_16x16x32_bf16(Bt[n][k], At[m][k], acc[ai][bj][m][n], 0, 0, 0); __builtin_amdgcn_s_setprio(0); } while (0)
; #define PG8_WAIT_V(n) asm volatile("s_waitcnt vmcnt(" #n ")" ::: "memory")
; #define PG8_WAIT_L(n) asm volatile("s_waitcnt lgkmcnt(" #n ")" ::: "memory")
; #define PG8_BAR __builtin_amdgcn_s_barrier()
; #define PG8_SCHED __builtin_amdgcn_sched_barrier(0)
; template <class Epi, class Sched>
; __device__ __forceinline__ void gemm_phase(PG8_LAS unsigned char* lds, const Gemm g, const Sched& S, const Epi& E) {
;     ...
;             PG8_BAR; PG8_WAIT_L(0); PG8_MMA(1, 0, At, B0); PG8_BAR; PG8_SCHED;
;             PG8_STAGE(PG8_SB(1, 1), b3 + hstep, voffB);
;             PG8_WAIT_V(6); PG8_BAR; PG8_MMA(1, 1, At, B1); PG8_BAR;
;     __device__ __forceinline__ void operator()(f32x4 (&acc)[2][2][4][2], const Unit& u, int wr, int wc, int fr, int fq) const {
;     ...
; #pragma unroll
;         for (int ai = 0; ai < 2; ++ai) {
;             v4u gq[4][2];
; #pragma unroll
;             for (int m = 0; m < 4; ++m)
; #pragma unroll
;                 for (int bj = 0; bj < 2; ++bj) gq[m][bj] = *(const v4u*)(Z + (size_t)T * OFF_GATE + (size_t)(row0 + ai * 128 + m * 16) * 3072 + 2048 + col0 + bj * 128);
	s_waitcnt lgkmcnt(0)
	s_setprio 1
	v_mfma_f32_16x16x32_bf16 v[68:71], v[132:135], v[148:151], v[68:71]
	v_mfma_f32_16x16x32_bf16 v[72:75], v[140:143], v[148:151], v[72:75]
	v_mfma_f32_16x16x32_bf16 v[76:79], v[132:135], v[156:159], v[76:79]
	v_mfma_f32_16x16x32_bf16 v[80:83], v[140:143], v[156:159], v[80:83]
	v_mfma_f32_16x16x32_bf16 v[84:87], v[132:135], v[186:189], v[84:87]
	v_mfma_f32_16x16x32_bf16 v[88:91], v[140:143], v[186:189], v[88:91]
	v_mfma_f32_16x16x32_bf16 v[92:95], v[132:135], v[194:197], v[92:95]
	v_mfma_f32_16x16x32_bf16 v[96:99], v[140:143], v[194:197], v[96:99]
	v_mfma_f32_16x16x32_bf16 v[68:71], v[136:139], v[152:155], v[68:71]
	v_mfma_f32_16x16x32_bf16 v[72:75], v[144:147], v[152:155], v[72:75]
	v_mfma_f32_16x16x32_bf16 v[76:79], v[136:139], v[160:163], v[76:79]
	v_mfma_f32_16x16x32_bf16 v[80:83], v[144:147], v[160:163], v[80:83]
	v_mfma_f32_16x16x32_bf16 v[84:87], v[136:139], v[190:193], v[84:87]
	v_mfma_f32_16x16x32_bf16 v[88:91], v[144:147], v[190:193], v[88:91]
	v_mfma_f32_16x16x32_bf16 v[92:95], v[136:139], v[198:201], v[92:95]
	v_mfma_f32_16x16x32_bf16 v[96:99], v[144:147], v[198:201], v[96:99]
	s_setprio 0
	s_barrier
	s_add_u32 s6, s6, 0x80080
	s_addc_u32 s7, s7, 0
	s_add_i32 s52, s52, s70
	v_lshl_add_u64 v[2:3], s[6:7], 0, v[178:179]
	s_mov_b32 m0, s52
	s_nop 0
	global_load_lds_dwordx4 v[2:3], off
	v_lshl_add_u64 v[2:3], s[6:7], 0, v[174:175]
	s_add_i32 m0, s52, 0x2000
	s_nop 0
	global_load_lds_dwordx4 v[2:3], off
	s_waitcnt vmcnt(6)
	s_barrier
	s_setprio 1
	v_mfma_f32_16x16x32_bf16 v[100:103], v[226:229], v[148:151], v[100:103]
	v_mfma_f32_16x16x32_bf16 v[104:107], v[234:237], v[148:151], v[104:107]
	v_mfma_f32_16x16x32_bf16 v[108:111], v[226:229], v[156:159], v[108:111]
	v_mfma_f32_16x16x32_bf16 v[112:115], v[234:237], v[156:159], v[112:115]
	v_mfma_f32_16x16x32_bf16 v[116:119], v[226:229], v[186:189], v[116:119]
	v_mfma_f32_16x16x32_bf16 v[120:123], v[234:237], v[186:189], v[120:123]
	v_mfma_f32_16x16x32_bf16 v[124:127], v[226:229], v[194:197], v[124:127]
	v_mfma_f32_16x16x32_bf16 v[128:131], v[234:237], v[194:197], v[128:131]
	v_mfma_f32_16x16x32_bf16 v[100:103], v[230:233], v[152:155], v[100:103]
	v_mfma_f32_16x16x32_bf16 v[104:107], v[238:241], v[152:155], v[104:107]
	v_mfma_f32_16x16x32_bf16 v[108:111], v[230:233], v[160:163], v[108:111]
	v_mfma_f32_16x16x32_bf16 v[112:115], v[238:241], v[160:163], v[112:115]
	v_mfma_f32_16x16x32_bf16 v[116:119], v[230:233], v[190:193], v[116:119]
	v_mfma_f32_16x16x32_bf16 v[120:123], v[238:241], v[190:193], v[120:123]
	v_mfma_f32_16x16x32_bf16 v[124:127], v[230:233], v[198:201], v[124:127]
	v_mfma_f32_16x16x32_bf16 v[128:131], v[238:241], v[198:201], v[128:131]
	s_setprio 0
	s_add_i32 s84, s84, 2
	s_add_u32 s50, s50, 0x100
	s_addc_u32 s51, s51, 0
	s_add_u32 s82, s82, 0x100
	s_addc_u32 s83, s83, 0
	s_cmp_gt_u32 s84, 5
	s_barrier
	s_cbranch_scc0 .LBB0_472
	s_cmp_eq_u32 s78, 0
	s_cbranch_scc1 .LBB0_478
	v_lshl_add_u32 v2, s80, 8, v221
	v_lshl_or_b32 v192, s79, 8, v223
	s_mov_b64 s[6:7], -1
	s_cmp_lt_i32 s78, 3
	v_ashrrev_i32_e32 v193, 31, v192
	v_or_b32_e32 v190, 16, v2
	v_or_b32_e32 v188, 32, v2
	v_or_b32_e32 v186, 48, v2
	s_cbranch_scc1 .LBB0_476
	v_mov_b64_e32 v[196:197], s[46:47]
	v_mad_i64_i32 v[132:133], s[6:7], v2, s68, v[196:197]
	v_lshlrev_b64 v[194:195], 1, v[192:193]
	v_lshl_add_u64 v[132:133], v[132:133], 0, v[194:195]
	s_mov_b64 s[50:51], 0x14001000
	v_lshl_add_u64 v[134:135], v[132:133], 0, s[50:51]
	v_add_co_u32_e32 v132, vcc, 0x14001000, v132
	v_ashrrev_i32_e32 v3, 31, v2
	s_nop 0
	v_addc_co_u32_e32 v133, vcc, 0, v133, vcc
	global_load_dwordx4 v[160:163], v[132:133], off
	global_load_dwordx4 v[156:159], v[134:135], off offset:256
	v_mad_i64_i32 v[132:133], s[6:7], v190, s68, v[196:197]
	v_lshl_add_u64 v[132:133], v[132:133], 0, v[194:195]
	v_lshl_add_u64 v[134:135], v[132:133], 0, s[50:51]
	v_add_co_u32_e32 v132, vcc, 0x14001000, v132
	v_lshlrev_b64 v[198:199], 11, v[2:3]
	s_nop 0
	v_addc_co_u32_e32 v133, vcc, 0, v133, vcc
	global_load_dwordx4 v[152:155], v[132:133], off
	global_load_dwordx4 v[148:151], v[134:135], off offset:256
	v_mad_i64_i32 v[132:133], s[6:7], v188, s68, v[196:197]
	v_lshl_add_u64 v[132:133], v[132:133], 0, v[194:195]
	v_lshl_add_u64 v[134:135], v[132:133], 0, s[50:51]
	v_add_co_u32_e32 v132, vcc, 0x14001000, v132
	v_lshl_add_u64 v[198:199], s[56:57], 0, v[198:199]
	s_nop 0
	v_addc_co_u32_e32 v133, vcc, 0, v133, vcc
	global_load_dwordx4 v[144:147], v[132:133], off
	global_load_dwordx4 v[140:143], v[134:135], off offset:256
	v_mad_i64_i32 v[132:133], s[6:7], v186, s68, v[196:197]
	v_lshl_add_u64 v[132:133], v[132:133], 0, v[194:195]
	v_lshl_add_u64 v[134:135], v[132:133], 0, s[50:51]
	v_add_co_u32_e32 v132, vcc, 0x14001000, v132
	v_lshl_add_u64 v[198:199], v[198:199], 0, v[194:195]
	s_nop 0
	v_addc_co_u32_e32 v133, vcc, 0, v133, vcc
	global_load_dwordx4 v[136:139], v[132:133], off
	s_nop 0
	global_load_dwordx4 v[132:135], v[134:135], off offset:256
	v_ashrrev_i32_e32 v191, 31, v190
	v_ashrrev_i32_e32 v189, 31, v188
	v_ashrrev_i32_e32 v187, 31, v186
	v_add_u32_e32 v226, 0x80, v2
	s_mov_b32 s19, 0x14001000
	v_add_u32_e32 v202, 0x90, v2
	v_ashrrev_i32_e32 v227, 31, v226
	v_ashrrev_i32_e32 v203, 31, v202
	s_waitcnt vmcnt(0)
; __device__ __forceinline__ unsigned pk2(float lo, float hi) { v2f v = {lo, hi}; return __builtin_bit_cast(unsigned, __builtin_convertvector(v, v2bf)); }
; __device__ __forceinline__ float bflo(unsigned u) { return __uint_as_float(u << 16); }
; __device__ __forceinline__ float bfhi(unsigned u) { return __uint_as_float(u & 0xffff0000u); }
; #define SG(a_, g_) ((a_) * __builtin_amdgcn_rcpf(einv(g_)))
;     __device__ __forceinline__ void operator()(f32x4 (&acc)[2][2][4][2], const Unit& u, int wr, int wc, int fr, int fq) const {
;     ...
; #pragma unroll
;             for (int m = 0; m < 4; ++m) { const int row = row0 + ai * 128 + m * 16;
; #pragma unroll
;                 for (int bj = 0; bj < 2; ++bj) { const int col = col0 + bj * 128;
;                     const v4u gw = gq[m][bj];
;                     const f32x4 a0 = acc[ai][bj][m][0], a1 = acc[ai][bj][m][1];
;     ...
;                     v4u w; w.x = pk2(SG(a0[0], bflo(gw.x)), SG(a0[1], bfhi(gw.x))); w.y = pk2(SG(a0[2], bflo(gw.y)), SG(a0[3], bfhi(gw.y)));
;                     w.z = pk2(SG(a1[0], bflo(gw.z)), SG(a1[1], bfhi(gw.z))); w.w = pk2(SG(a1[2], bflo(gw.w)), SG(a1[3], bfhi(gw.w)));
;     ...
;                     *(v4u*)(MB + (size_t)row * 1024 + col) = w; } }
	v_lshlrev_b32_e32 v0, 16, v160
	v_max_f32_e64 v0, -v0, -v0
	v_min_f32_e32 v0, 0x41f00000, v0
	v_mul_f32_e32 v0, 0x3fb8aa3b, v0
	v_exp_f32_e32 v0, v0
	s_nop 0
	v_add_f32_e32 v0, 1.0, v0
	v_rcp_f32_e32 v200, v0
	v_and_b32_e32 v0, 0xffff0000, v160
	v_max_f32_e64 v0, -v0, -v0
	v_min_f32_e32 v0, 0x41f00000, v0
	v_mul_f32_e32 v0, 0x3fb8aa3b, v0
	v_exp_f32_e32 v0, v0
	s_nop 0
	v_add_f32_e32 v0, 1.0, v0
	v_rcp_f32_e32 v201, v0
	v_lshlrev_b32_e32 v0, 16, v161
	v_max_f32_e64 v0, -v0, -v0
	v_min_f32_e32 v0, 0x41f00000, v0
	v_mul_f32_e32 v0, 0x3fb8aa3b, v0
	v_exp_f32_e32 v0, v0
	v_pk_mul_f32 v[200:201], v[4:5], v[200:201]
	v_add_f32_e32 v0, 1.0, v0
	v_cvt_pk_bf16_f32 v160, v200, v201
	v_rcp_f32_e32 v200, v0
	v_and_b32_e32 v0, 0xffff0000, v161
	v_max_f32_e64 v0, -v0, -v0
	v_min_f32_e32 v0, 0x41f00000, v0
	v_mul_f32_e32 v0, 0x3fb8aa3b, v0
	v_exp_f32_e32 v0, v0
	s_nop 0
	v_add_f32_e32 v0, 1.0, v0
	v_rcp_f32_e32 v201, v0
	v_lshlrev_b32_e32 v0, 16, v162
	v_max_f32_e64 v0, -v0, -v0
	v_min_f32_e32 v0, 0x41f00000, v0
	v_mul_f32_e32 v0, 0x3fb8aa3b, v0
	v_exp_f32_e32 v0, v0
	v_pk_mul_f32 v[200:201], v[6:7], v[200:201]
	v_add_f32_e32 v0, 1.0, v0
	v_cvt_pk_bf16_f32 v161, v200, v201
	v_rcp_f32_e32 v200, v0
	v_and_b32_e32 v0, 0xffff0000, v162
	v_max_f32_e64 v0, -v0, -v0
	v_min_f32_e32 v0, 0x41f00000, v0
	v_mul_f32_e32 v0, 0x3fb8aa3b, v0
	v_exp_f32_e32 v0, v0
	s_nop 0
	v_add_f32_e32 v0, 1.0, v0
	v_rcp_f32_e32 v201, v0
	v_lshlrev_b32_e32 v0, 16, v163
	v_max_f32_e64 v0, -v0, -v0
	v_min_f32_e32 v0, 0x41f00000, v0
	v_mul_f32_e32 v0, 0x3fb8aa3b, v0
	v_exp_f32_e32 v0, v0
	v_pk_mul_f32 v[200:201], v[8:9], v[200:201]
	v_add_f32_e32 v0, 1.0, v0
	v_cvt_pk_bf16_f32 v162, v200, v201
	v_rcp_f32_e32 v200, v0
	v_and_b32_e32 v0, 0xffff0000, v163
	v_max_f32_e64 v0, -v0, -v0
	v_min_f32_e32 v0, 0x41f00000, v0
	v_mul_f32_e32 v0, 0x3fb8aa3b, v0
	v_exp_f32_e32 v0, v0
	s_nop 0
	v_add_f32_e32 v0, 1.0, v0
	v_rcp_f32_e32 v201, v0
	v_lshlrev_b32_e32 v0, 16, v156
	v_max_f32_e64 v0, -v0, -v0
	v_min_f32_e32 v0, 0x41f00000, v0
	v_mul_f32_e32 v0, 0x3fb8aa3b, v0
	v_exp_f32_e32 v0, v0
	v_pk_mul_f32 v[200:201], v[10:11], v[200:201]
	v_add_f32_e32 v0, 1.0, v0
	v_cvt_pk_bf16_f32 v163, v200, v201
	global_store_dwordx4 v[198:199], v[160:163], off
	v_add_u32_e32 v200, 0xa0, v2
	v_ashrrev_i32_e32 v201, 31, v200
	v_rcp_f32_e32 v160, v0
	v_and_b32_e32 v0, 0xffff0000, v156
	v_max_f32_e64 v0, -v0, -v0
	v_min_f32_e32 v0, 0x41f00000, v0
	v_mul_f32_e32 v0, 0x3fb8aa3b, v0
	v_exp_f32_e32 v0, v0
	s_nop 0
	v_add_f32_e32 v0, 1.0, v0
	v_rcp_f32_e32 v161, v0
	v_lshlrev_b32_e32 v0, 16, v157
	v_max_f32_e64 v0, -v0, -v0
	v_min_f32_e32 v0, 0x41f00000, v0
	v_mul_f32_e32 v0, 0x3fb8aa3b, v0
	v_exp_f32_e32 v0, v0
	v_pk_mul_f32 v[160:161], v[36:37], v[160:161]
	v_add_f32_e32 v0, 1.0, v0
	v_cvt_pk_bf16_f32 v156, v160, v161
	v_rcp_f32_e32 v160, v0
	v_and_b32_e32 v0, 0xffff0000, v157
	v_max_f32_e64 v0, -v0, -v0
	v_min_f32_e32 v0, 0x41f00000, v0
	v_mul_f32_e32 v0, 0x3fb8aa3b, v0
	v_exp_f32_e32 v0, v0
	s_nop 0
	v_add_f32_e32 v0, 1.0, v0
	v_rcp_f32_e32 v161, v0
	v_lshlrev_b32_e32 v0, 16, v158
	v_max_f32_e64 v0, -v0, -v0
	v_min_f32_e32 v0, 0x41f00000, v0
	v_mul_f32_e32 v0, 0x3fb8aa3b, v0
	v_exp_f32_e32 v0, v0
	v_pk_mul_f32 v[160:161], v[38:39], v[160:161]
	v_add_f32_e32 v0, 1.0, v0
	v_cvt_pk_bf16_f32 v157, v160, v161
	v_rcp_f32_e32 v160, v0
	v_and_b32_e32 v0, 0xffff0000, v158
	v_max_f32_e64 v0, -v0, -v0
	v_min_f32_e32 v0, 0x41f00000, v0
	v_mul_f32_e32 v0, 0x3fb8aa3b, v0
	v_exp_f32_e32 v0, v0
	s_nop 0
	v_add_f32_e32 v0, 1.0, v0
	v_rcp_f32_e32 v161, v0
	v_lshlrev_b32_e32 v0, 16, v159
	v_max_f32_e64 v0, -v0, -v0
	v_min_f32_e32 v0, 0x41f00000, v0
	v_mul_f32_e32 v0, 0x3fb8aa3b, v0
	v_exp_f32_e32 v0, v0
	v_pk_mul_f32 v[160:161], v[40:41], v[160:161]
	v_add_f32_e32 v0, 1.0, v0
	v_cvt_pk_bf16_f32 v158, v160, v161
	v_rcp_f32_e32 v160, v0
	v_and_b32_e32 v0, 0xffff0000, v159
	v_max_f32_e64 v0, -v0, -v0
	v_min_f32_e32 v0, 0x41f00000, v0
	v_mul_f32_e32 v0, 0x3fb8aa3b, v0
	v_exp_f32_e32 v0, v0
	s_nop 0
	v_add_f32_e32 v0, 1.0, v0
	v_rcp_f32_e32 v161, v0
	v_lshlrev_b32_e32 v0, 16, v152
	v_max_f32_e64 v0, -v0, -v0
	v_min_f32_e32 v0, 0x41f00000, v0
	v_mul_f32_e32 v0, 0x3fb8aa3b, v0
	v_exp_f32_e32 v0, v0
	v_pk_mul_f32 v[160:161], v[42:43], v[160:161]
	v_add_f32_e32 v0, 1.0, v0
	v_cvt_pk_bf16_f32 v159, v160, v161
	global_store_dwordx4 v[198:199], v[156:159], off offset:256
	v_add_u32_e32 v198, 0xb0, v2
	v_ashrrev_i32_e32 v199, 31, v198
	v_rcp_f32_e32 v158, v0
	v_and_b32_e32 v0, 0xffff0000, v152
	v_max_f32_e64 v0, -v0, -v0
	v_min_f32_e32 v0, 0x41f00000, v0
	v_mul_f32_e32 v0, 0x3fb8aa3b, v0
	v_exp_f32_e32 v0, v0
	v_lshlrev_b64 v[156:157], 11, v[190:191]
	v_lshl_add_u64 v[156:157], s[56:57], 0, v[156:157]
	v_lshl_add_u64 v[156:157], v[156:157], 0, v[194:195]
	v_add_f32_e32 v0, 1.0, v0
	v_rcp_f32_e32 v159, v0
	v_lshlrev_b32_e32 v0, 16, v153
	v_max_f32_e64 v0, -v0, -v0
	v_min_f32_e32 v0, 0x41f00000, v0
	v_mul_f32_e32 v0, 0x3fb8aa3b, v0
	v_exp_f32_e32 v0, v0
	v_pk_mul_f32 v[158:159], v[12:13], v[158:159]
	v_add_f32_e32 v0, 1.0, v0
	v_cvt_pk_bf16_f32 v152, v158, v159
	v_rcp_f32_e32 v158, v0
	v_and_b32_e32 v0, 0xffff0000, v153
	v_max_f32_e64 v0, -v0, -v0
	v_min_f32_e32 v0, 0x41f00000, v0
	v_mul_f32_e32 v0, 0x3fb8aa3b, v0
	v_exp_f32_e32 v0, v0
	s_nop 0
	v_add_f32_e32 v0, 1.0, v0
	v_rcp_f32_e32 v159, v0
	v_lshlrev_b32_e32 v0, 16, v154
	v_max_f32_e64 v0, -v0, -v0
	v_min_f32_e32 v0, 0x41f00000, v0
	v_mul_f32_e32 v0, 0x3fb8aa3b, v0
	v_exp_f32_e32 v0, v0
	v_pk_mul_f32 v[158:159], v[14:15], v[158:159]
	v_add_f32_e32 v0, 1.0, v0
	v_cvt_pk_bf16_f32 v153, v158, v159
	v_rcp_f32_e32 v158, v0
	v_and_b32_e32 v0, 0xffff0000, v154
	v_max_f32_e64 v0, -v0, -v0
; __device__ __forceinline__ unsigned pk2(float lo, float hi) { v2f v = {lo, hi}; return __builtin_bit_cast(unsigned, __builtin_convertvector(v, v2bf)); }
; __device__ __forceinline__ float bflo(unsigned u) { return __uint_as_float(u << 16); }
; __device__ __forceinline__ float bfhi(unsigned u) { return __uint_as_float(u & 0xffff0000u); }
; #define SG(a_, g_) ((a_) * __builtin_amdgcn_rcpf(einv(g_)))
;     __device__ __forceinline__ void operator()(f32x4 (&acc)[2][2][4][2], const Unit& u, int wr, int wc, int fr, int fq) const {
;     ...
;             for (int m = 0; m < 4; ++m) { const int row = row0 + ai * 128 + m * 16;
; #pragma unroll
;                 for (int bj = 0; bj < 2; ++bj) { const int col = col0 + bj * 128;
;                     const v4u gw = gq[m][bj];
;                     const f32x4 a0 = acc[ai][bj][m][0], a1 = acc[ai][bj][m][1];
;     ...
;                     v4u w; w.x = pk2(SG(a0[0], bflo(gw.x)), SG(a0[1], bfhi(gw.x))); w.y = pk2(SG(a0[2], bflo(gw.y)), SG(a0[3], bfhi(gw.y)));
;                     w.z = pk2(SG(a1[0], bflo(gw.z)), SG(a1[1], bfhi(gw.z))); w.w = pk2(SG(a1[2], bflo(gw.w)), SG(a1[3], bfhi(gw.w)));
;     ...
;                     *(v4u*)(MB + (size_t)row * 1024 + col) = w; } }
	v_min_f32_e32 v0, 0x41f00000, v0
	v_mul_f32_e32 v0, 0x3fb8aa3b, v0
	v_exp_f32_e32 v0, v0
	s_nop 0
	v_add_f32_e32 v0, 1.0, v0
	v_rcp_f32_e32 v159, v0
	v_lshlrev_b32_e32 v0, 16, v155
	v_max_f32_e64 v0, -v0, -v0
	v_min_f32_e32 v0, 0x41f00000, v0
	v_mul_f32_e32 v0, 0x3fb8aa3b, v0
	v_exp_f32_e32 v0, v0
	v_pk_mul_f32 v[158:159], v[16:17], v[158:159]
	v_add_f32_e32 v0, 1.0, v0
	v_cvt_pk_bf16_f32 v154, v158, v159
	v_rcp_f32_e32 v158, v0
	v_and_b32_e32 v0, 0xffff0000, v155
	v_max_f32_e64 v0, -v0, -v0
	v_min_f32_e32 v0, 0x41f00000, v0
	v_mul_f32_e32 v0, 0x3fb8aa3b, v0
	v_exp_f32_e32 v0, v0
	s_nop 0
	v_add_f32_e32 v0, 1.0, v0
	v_rcp_f32_e32 v159, v0
	v_lshlrev_b32_e32 v0, 16, v148
	v_max_f32_e64 v0, -v0, -v0
	v_min_f32_e32 v0, 0x41f00000, v0
	v_mul_f32_e32 v0, 0x3fb8aa3b, v0
	v_exp_f32_e32 v0, v0
	v_pk_mul_f32 v[158:159], v[18:19], v[158:159]
	v_add_f32_e32 v0, 1.0, v0
	v_cvt_pk_bf16_f32 v155, v158, v159
	global_store_dwordx4 v[156:157], v[152:155], off
	s_nop 1
	v_rcp_f32_e32 v152, v0
	v_and_b32_e32 v0, 0xffff0000, v148
	v_max_f32_e64 v0, -v0, -v0
	v_min_f32_e32 v0, 0x41f00000, v0
	v_mul_f32_e32 v0, 0x3fb8aa3b, v0
	v_exp_f32_e32 v0, v0
	s_nop 0
	v_add_f32_e32 v0, 1.0, v0
	v_rcp_f32_e32 v153, v0
	v_lshlrev_b32_e32 v0, 16, v149
	v_max_f32_e64 v0, -v0, -v0
	v_min_f32_e32 v0, 0x41f00000, v0
	v_mul_f32_e32 v0, 0x3fb8aa3b, v0
	v_exp_f32_e32 v0, v0
	v_pk_mul_f32 v[152:153], v[44:45], v[152:153]
	v_add_f32_e32 v0, 1.0, v0
	v_cvt_pk_bf16_f32 v148, v152, v153
	v_rcp_f32_e32 v152, v0
	v_and_b32_e32 v0, 0xffff0000, v149
	v_max_f32_e64 v0, -v0, -v0
	v_min_f32_e32 v0, 0x41f00000, v0
	v_mul_f32_e32 v0, 0x3fb8aa3b, v0
	v_exp_f32_e32 v0, v0
	s_nop 0
	v_add_f32_e32 v0, 1.0, v0
	v_rcp_f32_e32 v153, v0
	v_lshlrev_b32_e32 v0, 16, v150
	v_max_f32_e64 v0, -v0, -v0
	v_min_f32_e32 v0, 0x41f00000, v0
	v_mul_f32_e32 v0, 0x3fb8aa3b, v0
	v_exp_f32_e32 v0, v0
	v_pk_mul_f32 v[152:153], v[46:47], v[152:153]
	v_add_f32_e32 v0, 1.0, v0
	v_cvt_pk_bf16_f32 v149, v152, v153
	v_rcp_f32_e32 v152, v0
	v_and_b32_e32 v0, 0xffff0000, v150
	v_max_f32_e64 v0, -v0, -v0
	v_min_f32_e32 v0, 0x41f00000, v0
	v_mul_f32_e32 v0, 0x3fb8aa3b, v0
	v_exp_f32_e32 v0, v0
	s_nop 0
	v_add_f32_e32 v0, 1.0, v0
	v_rcp_f32_e32 v153, v0
	v_lshlrev_b32_e32 v0, 16, v151
	v_max_f32_e64 v0, -v0, -v0
	v_min_f32_e32 v0, 0x41f00000, v0
	v_mul_f32_e32 v0, 0x3fb8aa3b, v0
	v_exp_f32_e32 v0, v0
	v_pk_mul_f32 v[152:153], v[48:49], v[152:153]
	v_add_f32_e32 v0, 1.0, v0
	v_cvt_pk_bf16_f32 v150, v152, v153
	v_rcp_f32_e32 v152, v0
	v_and_b32_e32 v0, 0xffff0000, v151
	v_max_f32_e64 v0, -v0, -v0
	v_min_f32_e32 v0, 0x41f00000, v0
	v_mul_f32_e32 v0, 0x3fb8aa3b, v0
	v_exp_f32_e32 v0, v0
	s_nop 0
	v_add_f32_e32 v0, 1.0, v0
	v_rcp_f32_e32 v153, v0
	v_lshlrev_b32_e32 v0, 16, v144
	v_max_f32_e64 v0, -v0, -v0
	v_min_f32_e32 v0, 0x41f00000, v0
	v_mul_f32_e32 v0, 0x3fb8aa3b, v0
	v_exp_f32_e32 v0, v0
	v_pk_mul_f32 v[152:153], v[50:51], v[152:153]
	v_add_f32_e32 v0, 1.0, v0
	v_cvt_pk_bf16_f32 v151, v152, v153
	global_store_dwordx4 v[156:157], v[148:151], off offset:256
	s_nop 1
	v_rcp_f32_e32 v150, v0
	v_and_b32_e32 v0, 0xffff0000, v144
	v_max_f32_e64 v0, -v0, -v0
	v_min_f32_e32 v0, 0x41f00000, v0
	v_mul_f32_e32 v0, 0x3fb8aa3b, v0
	v_exp_f32_e32 v0, v0
	v_lshlrev_b64 v[148:149], 11, v[188:189]
	v_lshl_add_u64 v[148:149], s[56:57], 0, v[148:149]
	v_lshl_add_u64 v[148:149], v[148:149], 0, v[194:195]
	v_add_f32_e32 v0, 1.0, v0
	v_rcp_f32_e32 v151, v0
	v_lshlrev_b32_e32 v0, 16, v145
	v_max_f32_e64 v0, -v0, -v0
	v_min_f32_e32 v0, 0x41f00000, v0
	v_mul_f32_e32 v0, 0x3fb8aa3b, v0
	v_exp_f32_e32 v0, v0
	v_pk_mul_f32 v[150:151], v[20:21], v[150:151]
	v_add_f32_e32 v0, 1.0, v0
	v_cvt_pk_bf16_f32 v144, v150, v151
	v_rcp_f32_e32 v150, v0
	v_and_b32_e32 v0, 0xffff0000, v145
	v_max_f32_e64 v0, -v0, -v0
	v_min_f32_e32 v0, 0x41f00000, v0
	v_mul_f32_e32 v0, 0x3fb8aa3b, v0
	v_exp_f32_e32 v0, v0
	s_nop 0
	v_add_f32_e32 v0, 1.0, v0
	v_rcp_f32_e32 v151, v0
	v_lshlrev_b32_e32 v0, 16, v146
	v_max_f32_e64 v0, -v0, -v0
	v_min_f32_e32 v0, 0x41f00000, v0
	v_mul_f32_e32 v0, 0x3fb8aa3b, v0
	v_exp_f32_e32 v0, v0
	v_pk_mul_f32 v[150:151], v[22:23], v[150:151]
	v_add_f32_e32 v0, 1.0, v0
	v_cvt_pk_bf16_f32 v145, v150, v151
	v_rcp_f32_e32 v150, v0
	v_and_b32_e32 v0, 0xffff0000, v146
	v_max_f32_e64 v0, -v0, -v0
	v_min_f32_e32 v0, 0x41f00000, v0
	v_mul_f32_e32 v0, 0x3fb8aa3b, v0
	v_exp_f32_e32 v0, v0
	s_nop 0
	v_add_f32_e32 v0, 1.0, v0
	v_rcp_f32_e32 v151, v0
	v_lshlrev_b32_e32 v0, 16, v147
	v_max_f32_e64 v0, -v0, -v0
	v_min_f32_e32 v0, 0x41f00000, v0
	v_mul_f32_e32 v0, 0x3fb8aa3b, v0
	v_exp_f32_e32 v0, v0
	v_pk_mul_f32 v[150:151], v[24:25], v[150:151]
	v_add_f32_e32 v0, 1.0, v0
	v_cvt_pk_bf16_f32 v146, v150, v151
	v_rcp_f32_e32 v150, v0
	v_and_b32_e32 v0, 0xffff0000, v147
	v_max_f32_e64 v0, -v0, -v0
	v_min_f32_e32 v0, 0x41f00000, v0
	v_mul_f32_e32 v0, 0x3fb8aa3b, v0
	v_exp_f32_e32 v0, v0
	s_nop 0
	v_add_f32_e32 v0, 1.0, v0
	v_rcp_f32_e32 v151, v0
	v_lshlrev_b32_e32 v0, 16, v140
	v_max_f32_e64 v0, -v0, -v0
	v_min_f32_e32 v0, 0x41f00000, v0
	v_mul_f32_e32 v0, 0x3fb8aa3b, v0
	v_exp_f32_e32 v0, v0
	v_pk_mul_f32 v[150:151], v[26:27], v[150:151]
	v_add_f32_e32 v0, 1.0, v0
	v_cvt_pk_bf16_f32 v147, v150, v151
	global_store_dwordx4 v[148:149], v[144:147], off
	s_nop 1
	v_rcp_f32_e32 v144, v0
	v_and_b32_e32 v0, 0xffff0000, v140
	v_max_f32_e64 v0, -v0, -v0
	v_min_f32_e32 v0, 0x41f00000, v0
	v_mul_f32_e32 v0, 0x3fb8aa3b, v0
	v_exp_f32_e32 v0, v0
	s_nop 0
	v_add_f32_e32 v0, 1.0, v0
	v_rcp_f32_e32 v145, v0
	v_lshlrev_b32_e32 v0, 16, v141
	v_max_f32_e64 v0, -v0, -v0
	v_min_f32_e32 v0, 0x41f00000, v0
	v_mul_f32_e32 v0, 0x3fb8aa3b, v0
	v_exp_f32_e32 v0, v0
	v_pk_mul_f32 v[144:145], v[52:53], v[144:145]
; __device__ __forceinline__ unsigned pk2(float lo, float hi) { v2f v = {lo, hi}; return __builtin_bit_cast(unsigned, __builtin_convertvector(v, v2bf)); }
; __device__ __forceinline__ float bflo(unsigned u) { return __uint_as_float(u << 16); }
; __device__ __forceinline__ float bfhi(unsigned u) { return __uint_as_float(u & 0xffff0000u); }
; #define SG(a_, g_) ((a_) * __builtin_amdgcn_rcpf(einv(g_)))
;     __device__ __forceinline__ void operator()(f32x4 (&acc)[2][2][4][2], const Unit& u, int wr, int wc, int fr, int fq) const {
;     ...
;             for (int m = 0; m < 4; ++m)
; #pragma unroll
;                 for (int bj = 0; bj < 2; ++bj) gq[m][bj] = *(const v4u*)(Z + (size_t)T * OFF_GATE + (size_t)(row0 + ai * 128 + m * 16) * 3072 + 2048 + col0 + bj * 128);
; #pragma unroll
;             for (int m = 0; m < 4; ++m) { const int row = row0 + ai * 128 + m * 16;
; #pragma unroll
;                 for (int bj = 0; bj < 2; ++bj) { const int col = col0 + bj * 128;
;                     const v4u gw = gq[m][bj];
;                     const f32x4 a0 = acc[ai][bj][m][0], a1 = acc[ai][bj][m][1];
;     ...
;                     v4u w; w.x = pk2(SG(a0[0], bflo(gw.x)), SG(a0[1], bfhi(gw.x))); w.y = pk2(SG(a0[2], bflo(gw.y)), SG(a0[3], bfhi(gw.y)));
;                     w.z = pk2(SG(a1[0], bflo(gw.z)), SG(a1[1], bfhi(gw.z))); w.w = pk2(SG(a1[2], bflo(gw.w)), SG(a1[3], bfhi(gw.w)));
;     ...
;                     *(v4u*)(MB + (size_t)row * 1024 + col) = w; } }
	v_add_f32_e32 v0, 1.0, v0
	v_cvt_pk_bf16_f32 v140, v144, v145
	v_rcp_f32_e32 v144, v0
	v_and_b32_e32 v0, 0xffff0000, v141
	v_max_f32_e64 v0, -v0, -v0
	v_min_f32_e32 v0, 0x41f00000, v0
	v_mul_f32_e32 v0, 0x3fb8aa3b, v0
	v_exp_f32_e32 v0, v0
	s_nop 0
	v_add_f32_e32 v0, 1.0, v0
	v_rcp_f32_e32 v145, v0
	v_lshlrev_b32_e32 v0, 16, v142
	v_max_f32_e64 v0, -v0, -v0
	v_min_f32_e32 v0, 0x41f00000, v0
	v_mul_f32_e32 v0, 0x3fb8aa3b, v0
	v_exp_f32_e32 v0, v0
	v_pk_mul_f32 v[144:145], v[54:55], v[144:145]
	v_add_f32_e32 v0, 1.0, v0
	v_cvt_pk_bf16_f32 v141, v144, v145
	v_rcp_f32_e32 v144, v0
	v_and_b32_e32 v0, 0xffff0000, v142
	v_max_f32_e64 v0, -v0, -v0
	v_min_f32_e32 v0, 0x41f00000, v0
	v_mul_f32_e32 v0, 0x3fb8aa3b, v0
	v_exp_f32_e32 v0, v0
	s_nop 0
	v_add_f32_e32 v0, 1.0, v0
	v_rcp_f32_e32 v145, v0
	v_lshlrev_b32_e32 v0, 16, v143
	v_max_f32_e64 v0, -v0, -v0
	v_min_f32_e32 v0, 0x41f00000, v0
	v_mul_f32_e32 v0, 0x3fb8aa3b, v0
	v_exp_f32_e32 v0, v0
	v_pk_mul_f32 v[144:145], v[56:57], v[144:145]
	v_add_f32_e32 v0, 1.0, v0
	v_cvt_pk_bf16_f32 v142, v144, v145
	v_rcp_f32_e32 v144, v0
	v_and_b32_e32 v0, 0xffff0000, v143
	v_max_f32_e64 v0, -v0, -v0
	v_min_f32_e32 v0, 0x41f00000, v0
	v_mul_f32_e32 v0, 0x3fb8aa3b, v0
	v_exp_f32_e32 v0, v0
	s_nop 0
	v_add_f32_e32 v0, 1.0, v0
	v_rcp_f32_e32 v145, v0
	v_lshlrev_b32_e32 v0, 16, v136
	v_max_f32_e64 v0, -v0, -v0
	v_min_f32_e32 v0, 0x41f00000, v0
	v_mul_f32_e32 v0, 0x3fb8aa3b, v0
	v_exp_f32_e32 v0, v0
	v_pk_mul_f32 v[144:145], v[58:59], v[144:145]
	v_add_f32_e32 v0, 1.0, v0
	v_cvt_pk_bf16_f32 v143, v144, v145
	global_store_dwordx4 v[148:149], v[140:143], off offset:256
	s_nop 1
	v_rcp_f32_e32 v142, v0
	v_and_b32_e32 v0, 0xffff0000, v136
	v_max_f32_e64 v0, -v0, -v0
	v_min_f32_e32 v0, 0x41f00000, v0
	v_mul_f32_e32 v0, 0x3fb8aa3b, v0
	v_exp_f32_e32 v0, v0
	v_lshlrev_b64 v[140:141], 11, v[186:187]
	v_lshl_add_u64 v[140:141], s[56:57], 0, v[140:141]
	v_lshl_add_u64 v[140:141], v[140:141], 0, v[194:195]
	v_add_f32_e32 v0, 1.0, v0
	v_rcp_f32_e32 v143, v0
	v_lshlrev_b32_e32 v0, 16, v137
	v_max_f32_e64 v0, -v0, -v0
	v_min_f32_e32 v0, 0x41f00000, v0
	v_mul_f32_e32 v0, 0x3fb8aa3b, v0
	v_exp_f32_e32 v0, v0
	v_pk_mul_f32 v[142:143], v[28:29], v[142:143]
	v_add_f32_e32 v0, 1.0, v0
	v_cvt_pk_bf16_f32 v136, v142, v143
	v_rcp_f32_e32 v142, v0
	v_and_b32_e32 v0, 0xffff0000, v137
	v_max_f32_e64 v0, -v0, -v0
	v_min_f32_e32 v0, 0x41f00000, v0
	v_mul_f32_e32 v0, 0x3fb8aa3b, v0
	v_exp_f32_e32 v0, v0
	s_nop 0
	v_add_f32_e32 v0, 1.0, v0
	v_rcp_f32_e32 v143, v0
	v_lshlrev_b32_e32 v0, 16, v138
	v_max_f32_e64 v0, -v0, -v0
	v_min_f32_e32 v0, 0x41f00000, v0
	v_mul_f32_e32 v0, 0x3fb8aa3b, v0
	v_exp_f32_e32 v0, v0
	v_pk_mul_f32 v[142:143], v[30:31], v[142:143]
	v_add_f32_e32 v0, 1.0, v0
	v_cvt_pk_bf16_f32 v137, v142, v143
	v_rcp_f32_e32 v142, v0
	v_and_b32_e32 v0, 0xffff0000, v138
	v_max_f32_e64 v0, -v0, -v0
	v_min_f32_e32 v0, 0x41f00000, v0
	v_mul_f32_e32 v0, 0x3fb8aa3b, v0
	v_exp_f32_e32 v0, v0
	s_nop 0
	v_add_f32_e32 v0, 1.0, v0
	v_rcp_f32_e32 v143, v0
	v_lshlrev_b32_e32 v0, 16, v139
	v_max_f32_e64 v0, -v0, -v0
	v_min_f32_e32 v0, 0x41f00000, v0
	v_mul_f32_e32 v0, 0x3fb8aa3b, v0
	v_exp_f32_e32 v0, v0
	v_pk_mul_f32 v[142:143], v[32:33], v[142:143]
	v_add_f32_e32 v0, 1.0, v0
	v_cvt_pk_bf16_f32 v138, v142, v143
	v_rcp_f32_e32 v142, v0
	v_and_b32_e32 v0, 0xffff0000, v139
	v_max_f32_e64 v0, -v0, -v0
	v_min_f32_e32 v0, 0x41f00000, v0
	v_mul_f32_e32 v0, 0x3fb8aa3b, v0
	v_exp_f32_e32 v0, v0
	s_nop 0
	v_add_f32_e32 v0, 1.0, v0
	v_rcp_f32_e32 v143, v0
	v_lshlrev_b32_e32 v0, 16, v132
	v_max_f32_e64 v0, -v0, -v0
	v_min_f32_e32 v0, 0x41f00000, v0
	v_mul_f32_e32 v0, 0x3fb8aa3b, v0
	v_exp_f32_e32 v0, v0
	v_pk_mul_f32 v[142:143], v[34:35], v[142:143]
	v_add_f32_e32 v0, 1.0, v0
	v_cvt_pk_bf16_f32 v139, v142, v143
	global_store_dwordx4 v[140:141], v[136:139], off
	s_nop 1
	v_rcp_f32_e32 v136, v0
	v_and_b32_e32 v0, 0xffff0000, v132
	v_max_f32_e64 v0, -v0, -v0
	v_min_f32_e32 v0, 0x41f00000, v0
	v_mul_f32_e32 v0, 0x3fb8aa3b, v0
	v_exp_f32_e32 v0, v0
	s_nop 0
	v_add_f32_e32 v0, 1.0, v0
	v_rcp_f32_e32 v137, v0
	v_lshlrev_b32_e32 v0, 16, v133
	v_max_f32_e64 v0, -v0, -v0
	v_min_f32_e32 v0, 0x41f00000, v0
	v_mul_f32_e32 v0, 0x3fb8aa3b, v0
	v_exp_f32_e32 v0, v0
	v_pk_mul_f32 v[136:137], v[60:61], v[136:137]
	v_add_f32_e32 v0, 1.0, v0
	v_cvt_pk_bf16_f32 v132, v136, v137
	v_rcp_f32_e32 v136, v0
	v_and_b32_e32 v0, 0xffff0000, v133
	v_max_f32_e64 v0, -v0, -v0
	v_min_f32_e32 v0, 0x41f00000, v0
	v_mul_f32_e32 v0, 0x3fb8aa3b, v0
	v_exp_f32_e32 v0, v0
	s_nop 0
	v_add_f32_e32 v0, 1.0, v0
	v_rcp_f32_e32 v137, v0
	v_lshlrev_b32_e32 v0, 16, v134
	v_max_f32_e64 v0, -v0, -v0
	v_min_f32_e32 v0, 0x41f00000, v0
	v_mul_f32_e32 v0, 0x3fb8aa3b, v0
	v_exp_f32_e32 v0, v0
	v_pk_mul_f32 v[136:137], v[62:63], v[136:137]
	v_add_f32_e32 v0, 1.0, v0
	v_cvt_pk_bf16_f32 v133, v136, v137
	v_rcp_f32_e32 v136, v0
	v_and_b32_e32 v0, 0xffff0000, v134
	v_max_f32_e64 v0, -v0, -v0
	v_min_f32_e32 v0, 0x41f00000, v0
	v_mul_f32_e32 v0, 0x3fb8aa3b, v0
	v_exp_f32_e32 v0, v0
	s_nop 0
	v_add_f32_e32 v0, 1.0, v0
	v_rcp_f32_e32 v137, v0
	v_lshlrev_b32_e32 v0, 16, v135
	v_max_f32_e64 v0, -v0, -v0
	v_min_f32_e32 v0, 0x41f00000, v0
	v_mul_f32_e32 v0, 0x3fb8aa3b, v0
	v_exp_f32_e32 v0, v0
	v_pk_mul_f32 v[136:137], v[64:65], v[136:137]
	v_add_f32_e32 v0, 1.0, v0
	v_cvt_pk_bf16_f32 v134, v136, v137
	v_rcp_f32_e32 v136, v0
	v_and_b32_e32 v0, 0xffff0000, v135
	v_max_f32_e64 v0, -v0, -v0
	v_min_f32_e32 v0, 0x41f00000, v0
	v_mul_f32_e32 v0, 0x3fb8aa3b, v0
	v_exp_f32_e32 v0, v0
	s_nop 0
	v_add_f32_e32 v0, 1.0, v0
	v_rcp_f32_e32 v137, v0
	s_nop 0
	v_pk_mul_f32 v[136:137], v[66:67], v[136:137]
	s_nop 0
	v_cvt_pk_bf16_f32 v135, v136, v137
	global_store_dwordx4 v[140:141], v[132:135], off offset:256
	s_nop 1
	v_mad_i64_i32 v[132:133], s[6:7], v226, s68, v[196:197]
	v_lshl_add_u64 v[132:133], v[132:133], 0, v[194:195]
	v_lshl_add_u64 v[134:135], v[132:133], 0, s[50:51]
	v_add_co_u32_e32 v132, vcc, s19, v132
	s_nop 1
	v_addc_co_u32_e32 v133, vcc, 0, v133, vcc
	global_load_dwordx4 v[160:163], v[132:133], off
	global_load_dwordx4 v[156:159], v[134:135], off offset:256
	v_mad_i64_i32 v[132:133], s[6:7], v202, s68, v[196:197]
	v_lshl_add_u64 v[132:133], v[132:133], 0, v[194:195]
	v_lshl_add_u64 v[134:135], v[132:133], 0, s[50:51]
	v_add_co_u32_e32 v132, vcc, s19, v132
	s_waitcnt vmcnt(0)
; __device__ __forceinline__ unsigned pk2(float lo, float hi) { v2f v = {lo, hi}; return __builtin_bit_cast(unsigned, __builtin_convertvector(v, v2bf)); }
; __device__ __forceinline__ float bflo(unsigned u) { return __uint_as_float(u << 16); }
; __device__ __forceinline__ float bfhi(unsigned u) { return __uint_as_float(u & 0xffff0000u); }
; #define SG(a_, g_) ((a_) * __builtin_amdgcn_rcpf(einv(g_)))
;     __device__ __forceinline__ void operator()(f32x4 (&acc)[2][2][4][2], const Unit& u, int wr, int wc, int fr, int fq) const {
;     ...
;             for (int m = 0; m < 4; ++m)
; #pragma unroll
;                 for (int bj = 0; bj < 2; ++bj) gq[m][bj] = *(const v4u*)(Z + (size_t)T * OFF_GATE + (size_t)(row0 + ai * 128 + m * 16) * 3072 + 2048 + col0 + bj * 128);
; #pragma unroll
;             for (int m = 0; m < 4; ++m) { const int row = row0 + ai * 128 + m * 16;
; #pragma unroll
;                 for (int bj = 0; bj < 2; ++bj) { const int col = col0 + bj * 128;
;                     const v4u gw = gq[m][bj];
;                     const f32x4 a0 = acc[ai][bj][m][0], a1 = acc[ai][bj][m][1];
;     ...
;                     v4u w; w.x = pk2(SG(a0[0], bflo(gw.x)), SG(a0[1], bfhi(gw.x))); w.y = pk2(SG(a0[2], bflo(gw.y)), SG(a0[3], bfhi(gw.y)));
;                     w.z = pk2(SG(a1[0], bflo(gw.z)), SG(a1[1], bfhi(gw.z))); w.w = pk2(SG(a1[2], bflo(gw.w)), SG(a1[3], bfhi(gw.w)));
;     ...
;                     *(v4u*)(MB + (size_t)row * 1024 + col) = w; } }
	v_lshlrev_b32_e32 v0, 16, v160
	v_max_f32_e64 v0, -v0, -v0
	v_min_f32_e32 v0, 0x41f00000, v0
	v_mul_f32_e32 v0, 0x3fb8aa3b, v0
	v_addc_co_u32_e32 v133, vcc, 0, v133, vcc
	v_exp_f32_e32 v0, v0
	global_load_dwordx4 v[152:155], v[132:133], off
	global_load_dwordx4 v[148:151], v[134:135], off offset:256
	v_mad_i64_i32 v[132:133], s[6:7], v200, s68, v[196:197]
	v_lshl_add_u64 v[132:133], v[132:133], 0, v[194:195]
	v_lshl_add_u64 v[134:135], v[132:133], 0, s[50:51]
	v_add_co_u32_e32 v132, vcc, s19, v132
	v_add_f32_e32 v0, 1.0, v0
	s_nop 0
	v_addc_co_u32_e32 v133, vcc, 0, v133, vcc
	global_load_dwordx4 v[144:147], v[132:133], off
	global_load_dwordx4 v[140:143], v[134:135], off offset:256
	v_mad_i64_i32 v[132:133], s[6:7], v198, s68, v[196:197]
	v_lshlrev_b64 v[196:197], 11, v[226:227]
	v_rcp_f32_e32 v226, v0
	v_and_b32_e32 v0, 0xffff0000, v160
	v_max_f32_e64 v0, -v0, -v0
	v_min_f32_e32 v0, 0x41f00000, v0
	v_mul_f32_e32 v0, 0x3fb8aa3b, v0
	v_exp_f32_e32 v0, v0
	v_lshl_add_u64 v[132:133], v[132:133], 0, v[194:195]
	v_lshl_add_u64 v[134:135], v[132:133], 0, s[50:51]
	v_add_co_u32_e32 v132, vcc, s19, v132
	v_add_f32_e32 v0, 1.0, v0
	v_rcp_f32_e32 v227, v0
	v_lshlrev_b32_e32 v0, 16, v161
	v_max_f32_e64 v0, -v0, -v0
	v_min_f32_e32 v0, 0x41f00000, v0
	v_mul_f32_e32 v0, 0x3fb8aa3b, v0
	v_exp_f32_e32 v0, v0
	v_pk_mul_f32 v[226:227], v[68:69], v[226:227]
	v_lshl_add_u64 v[196:197], s[56:57], 0, v[196:197]
	v_cvt_pk_bf16_f32 v160, v226, v227
	v_add_f32_e32 v0, 1.0, v0
	v_rcp_f32_e32 v226, v0
	v_and_b32_e32 v0, 0xffff0000, v161
	v_max_f32_e64 v0, -v0, -v0
	v_min_f32_e32 v0, 0x41f00000, v0
	v_mul_f32_e32 v0, 0x3fb8aa3b, v0
	v_exp_f32_e32 v0, v0
	v_addc_co_u32_e32 v133, vcc, 0, v133, vcc
	v_lshl_add_u64 v[196:197], v[196:197], 0, v[194:195]
	v_add_f32_e32 v0, 1.0, v0
	v_rcp_f32_e32 v227, v0
	v_lshlrev_b32_e32 v0, 16, v162
	v_max_f32_e64 v0, -v0, -v0
	v_min_f32_e32 v0, 0x41f00000, v0
	v_mul_f32_e32 v0, 0x3fb8aa3b, v0
	v_exp_f32_e32 v0, v0
	v_pk_mul_f32 v[226:227], v[70:71], v[226:227]
	global_load_dwordx4 v[136:139], v[132:133], off
	s_nop 0
	global_load_dwordx4 v[132:135], v[134:135], off offset:256
	v_cvt_pk_bf16_f32 v161, v226, v227
	v_add_f32_e32 v0, 1.0, v0
	v_rcp_f32_e32 v226, v0
	v_and_b32_e32 v0, 0xffff0000, v162
	v_max_f32_e64 v0, -v0, -v0
	v_min_f32_e32 v0, 0x41f00000, v0
	v_mul_f32_e32 v0, 0x3fb8aa3b, v0
	v_exp_f32_e32 v0, v0
	s_mov_b64 s[6:7], 0
	v_add_f32_e32 v0, 1.0, v0
	v_rcp_f32_e32 v227, v0
	v_lshlrev_b32_e32 v0, 16, v163
	v_max_f32_e64 v0, -v0, -v0
	v_min_f32_e32 v0, 0x41f00000, v0
	v_mul_f32_e32 v0, 0x3fb8aa3b, v0
	v_exp_f32_e32 v0, v0
	v_pk_mul_f32 v[226:227], v[72:73], v[226:227]
	v_add_f32_e32 v0, 1.0, v0
	v_cvt_pk_bf16_f32 v162, v226, v227
	v_rcp_f32_e32 v226, v0
	v_and_b32_e32 v0, 0xffff0000, v163
	v_max_f32_e64 v0, -v0, -v0
	v_min_f32_e32 v0, 0x41f00000, v0
	v_mul_f32_e32 v0, 0x3fb8aa3b, v0
	v_exp_f32_e32 v0, v0
	s_nop 0
	v_add_f32_e32 v0, 1.0, v0
	v_rcp_f32_e32 v227, v0
	v_lshlrev_b32_e32 v0, 16, v156
	v_max_f32_e64 v0, -v0, -v0
	v_min_f32_e32 v0, 0x41f00000, v0
	v_mul_f32_e32 v0, 0x3fb8aa3b, v0
	v_exp_f32_e32 v0, v0
	v_pk_mul_f32 v[226:227], v[74:75], v[226:227]
	v_add_f32_e32 v0, 1.0, v0
	v_cvt_pk_bf16_f32 v163, v226, v227
	global_store_dwordx4 v[196:197], v[160:163], off
	s_nop 1
	v_rcp_f32_e32 v160, v0
	v_and_b32_e32 v0, 0xffff0000, v156
	v_max_f32_e64 v0, -v0, -v0
	v_min_f32_e32 v0, 0x41f00000, v0
	v_mul_f32_e32 v0, 0x3fb8aa3b, v0
	v_exp_f32_e32 v0, v0
	s_nop 0
	v_add_f32_e32 v0, 1.0, v0
	v_rcp_f32_e32 v161, v0
	v_lshlrev_b32_e32 v0, 16, v157
	v_max_f32_e64 v0, -v0, -v0
	v_min_f32_e32 v0, 0x41f00000, v0
	v_mul_f32_e32 v0, 0x3fb8aa3b, v0
	v_exp_f32_e32 v0, v0
	v_pk_mul_f32 v[160:161], v[100:101], v[160:161]
	v_add_f32_e32 v0, 1.0, v0
	v_cvt_pk_bf16_f32 v156, v160, v161
	v_rcp_f32_e32 v160, v0
	v_and_b32_e32 v0, 0xffff0000, v157
	v_max_f32_e64 v0, -v0, -v0
	v_min_f32_e32 v0, 0x41f00000, v0
	v_mul_f32_e32 v0, 0x3fb8aa3b, v0
	v_exp_f32_e32 v0, v0
	s_nop 0
	v_add_f32_e32 v0, 1.0, v0
	v_rcp_f32_e32 v161, v0
	v_lshlrev_b32_e32 v0, 16, v158
	v_max_f32_e64 v0, -v0, -v0
	v_min_f32_e32 v0, 0x41f00000, v0
	v_mul_f32_e32 v0, 0x3fb8aa3b, v0
	v_exp_f32_e32 v0, v0
	v_pk_mul_f32 v[160:161], v[102:103], v[160:161]
	v_add_f32_e32 v0, 1.0, v0
	v_cvt_pk_bf16_f32 v157, v160, v161
	v_rcp_f32_e32 v160, v0
	v_and_b32_e32 v0, 0xffff0000, v158
	v_max_f32_e64 v0, -v0, -v0
	v_min_f32_e32 v0, 0x41f00000, v0
	v_mul_f32_e32 v0, 0x3fb8aa3b, v0
	v_exp_f32_e32 v0, v0
	s_nop 0
	v_add_f32_e32 v0, 1.0, v0
	v_rcp_f32_e32 v161, v0
	v_lshlrev_b32_e32 v0, 16, v159
	v_max_f32_e64 v0, -v0, -v0
	v_min_f32_e32 v0, 0x41f00000, v0
	v_mul_f32_e32 v0, 0x3fb8aa3b, v0
	v_exp_f32_e32 v0, v0
	v_pk_mul_f32 v[160:161], v[104:105], v[160:161]
	v_add_f32_e32 v0, 1.0, v0
	v_cvt_pk_bf16_f32 v158, v160, v161
	v_rcp_f32_e32 v160, v0
	v_and_b32_e32 v0, 0xffff0000, v159
	v_max_f32_e64 v0, -v0, -v0
	v_min_f32_e32 v0, 0x41f00000, v0
	v_mul_f32_e32 v0, 0x3fb8aa3b, v0
	v_exp_f32_e32 v0, v0
	s_nop 0
	v_add_f32_e32 v0, 1.0, v0
	v_rcp_f32_e32 v161, v0
	s_waitcnt vmcnt(0)
; __device__ __forceinline__ unsigned pk2(float lo, float hi) { v2f v = {lo, hi}; return __builtin_bit_cast(unsigned, __builtin_convertvector(v, v2bf)); }
; __device__ __forceinline__ float bflo(unsigned u) { return __uint_as_float(u << 16); }
; __device__ __forceinline__ float bfhi(unsigned u) { return __uint_as_float(u & 0xffff0000u); }
; #define SG(a_, g_) ((a_) * __builtin_amdgcn_rcpf(einv(g_)))
;     __device__ __forceinline__ void operator()(f32x4 (&acc)[2][2][4][2], const Unit& u, int wr, int wc, int fr, int fq) const {
;     ...
;             for (int m = 0; m < 4; ++m) { const int row = row0 + ai * 128 + m * 16;
; #pragma unroll
;                 for (int bj = 0; bj < 2; ++bj) { const int col = col0 + bj * 128;
;                     const v4u gw = gq[m][bj];
;                     const f32x4 a0 = acc[ai][bj][m][0], a1 = acc[ai][bj][m][1];
;     ...
;                     v4u w; w.x = pk2(SG(a0[0], bflo(gw.x)), SG(a0[1], bfhi(gw.x))); w.y = pk2(SG(a0[2], bflo(gw.y)), SG(a0[3], bfhi(gw.y)));
;                     w.z = pk2(SG(a1[0], bflo(gw.z)), SG(a1[1], bfhi(gw.z))); w.w = pk2(SG(a1[2], bflo(gw.w)), SG(a1[3], bfhi(gw.w)));
;     ...
;                     *(v4u*)(MB + (size_t)row * 1024 + col) = w; } }
	v_lshlrev_b32_e32 v0, 16, v152
	v_max_f32_e64 v0, -v0, -v0
	v_min_f32_e32 v0, 0x41f00000, v0
	v_mul_f32_e32 v0, 0x3fb8aa3b, v0
	v_exp_f32_e32 v0, v0
	v_pk_mul_f32 v[160:161], v[106:107], v[160:161]
	v_add_f32_e32 v0, 1.0, v0
	v_cvt_pk_bf16_f32 v159, v160, v161
	global_store_dwordx4 v[196:197], v[156:159], off offset:256
	s_nop 1
	v_rcp_f32_e32 v158, v0
	v_and_b32_e32 v0, 0xffff0000, v152
	v_max_f32_e64 v0, -v0, -v0
	v_min_f32_e32 v0, 0x41f00000, v0
	v_mul_f32_e32 v0, 0x3fb8aa3b, v0
	v_exp_f32_e32 v0, v0
	v_lshlrev_b64 v[156:157], 11, v[202:203]
	v_lshl_add_u64 v[156:157], s[56:57], 0, v[156:157]
	v_lshl_add_u64 v[156:157], v[156:157], 0, v[194:195]
	v_add_f32_e32 v0, 1.0, v0
	v_rcp_f32_e32 v159, v0
	v_lshlrev_b32_e32 v0, 16, v153
	v_max_f32_e64 v0, -v0, -v0
	v_min_f32_e32 v0, 0x41f00000, v0
	v_mul_f32_e32 v0, 0x3fb8aa3b, v0
	v_exp_f32_e32 v0, v0
	v_pk_mul_f32 v[158:159], v[76:77], v[158:159]
	v_add_f32_e32 v0, 1.0, v0
	v_cvt_pk_bf16_f32 v152, v158, v159
	v_rcp_f32_e32 v158, v0
	v_and_b32_e32 v0, 0xffff0000, v153
	v_max_f32_e64 v0, -v0, -v0
	v_min_f32_e32 v0, 0x41f00000, v0
	v_mul_f32_e32 v0, 0x3fb8aa3b, v0
	v_exp_f32_e32 v0, v0
	s_nop 0
	v_add_f32_e32 v0, 1.0, v0
	v_rcp_f32_e32 v159, v0
	v_lshlrev_b32_e32 v0, 16, v154
	v_max_f32_e64 v0, -v0, -v0
	v_min_f32_e32 v0, 0x41f00000, v0
	v_mul_f32_e32 v0, 0x3fb8aa3b, v0
	v_exp_f32_e32 v0, v0
	v_pk_mul_f32 v[158:159], v[78:79], v[158:159]
	v_add_f32_e32 v0, 1.0, v0
	v_cvt_pk_bf16_f32 v153, v158, v159
	v_rcp_f32_e32 v158, v0
	v_and_b32_e32 v0, 0xffff0000, v154
	v_max_f32_e64 v0, -v0, -v0
	v_min_f32_e32 v0, 0x41f00000, v0
	v_mul_f32_e32 v0, 0x3fb8aa3b, v0
	v_exp_f32_e32 v0, v0
	s_nop 0
	v_add_f32_e32 v0, 1.0, v0
	v_rcp_f32_e32 v159, v0
	v_lshlrev_b32_e32 v0, 16, v155
	v_max_f32_e64 v0, -v0, -v0
	v_min_f32_e32 v0, 0x41f00000, v0
	v_mul_f32_e32 v0, 0x3fb8aa3b, v0
	v_exp_f32_e32 v0, v0
	v_pk_mul_f32 v[158:159], v[80:81], v[158:159]
	v_add_f32_e32 v0, 1.0, v0
	v_cvt_pk_bf16_f32 v154, v158, v159
	v_rcp_f32_e32 v158, v0
	v_and_b32_e32 v0, 0xffff0000, v155
	v_max_f32_e64 v0, -v0, -v0
	v_min_f32_e32 v0, 0x41f00000, v0
	v_mul_f32_e32 v0, 0x3fb8aa3b, v0
	v_exp_f32_e32 v0, v0
	s_nop 0
	v_add_f32_e32 v0, 1.0, v0
	v_rcp_f32_e32 v159, v0
	v_lshlrev_b32_e32 v0, 16, v148
	v_max_f32_e64 v0, -v0, -v0
	v_min_f32_e32 v0, 0x41f00000, v0
	v_mul_f32_e32 v0, 0x3fb8aa3b, v0
	v_exp_f32_e32 v0, v0
	v_pk_mul_f32 v[158:159], v[82:83], v[158:159]
	v_add_f32_e32 v0, 1.0, v0
	v_cvt_pk_bf16_f32 v155, v158, v159
	global_store_dwordx4 v[156:157], v[152:155], off
	s_nop 1
	v_rcp_f32_e32 v152, v0
	v_and_b32_e32 v0, 0xffff0000, v148
	v_max_f32_e64 v0, -v0, -v0
	v_min_f32_e32 v0, 0x41f00000, v0
	v_mul_f32_e32 v0, 0x3fb8aa3b, v0
	v_exp_f32_e32 v0, v0
	s_nop 0
	v_add_f32_e32 v0, 1.0, v0
	v_rcp_f32_e32 v153, v0
	v_lshlrev_b32_e32 v0, 16, v149
	v_max_f32_e64 v0, -v0, -v0
	v_min_f32_e32 v0, 0x41f00000, v0
	v_mul_f32_e32 v0, 0x3fb8aa3b, v0
	v_exp_f32_e32 v0, v0
	v_pk_mul_f32 v[152:153], v[108:109], v[152:153]
	v_add_f32_e32 v0, 1.0, v0
	v_cvt_pk_bf16_f32 v148, v152, v153
	v_rcp_f32_e32 v152, v0
	v_and_b32_e32 v0, 0xffff0000, v149
	v_max_f32_e64 v0, -v0, -v0
	v_min_f32_e32 v0, 0x41f00000, v0
	v_mul_f32_e32 v0, 0x3fb8aa3b, v0
	v_exp_f32_e32 v0, v0
	s_nop 0
	v_add_f32_e32 v0, 1.0, v0
	v_rcp_f32_e32 v153, v0
	v_lshlrev_b32_e32 v0, 16, v150
	v_max_f32_e64 v0, -v0, -v0
	v_min_f32_e32 v0, 0x41f00000, v0
	v_mul_f32_e32 v0, 0x3fb8aa3b, v0
	v_exp_f32_e32 v0, v0
	v_pk_mul_f32 v[152:153], v[110:111], v[152:153]
	v_add_f32_e32 v0, 1.0, v0
	v_cvt_pk_bf16_f32 v149, v152, v153
	v_rcp_f32_e32 v152, v0
	v_and_b32_e32 v0, 0xffff0000, v150
	v_max_f32_e64 v0, -v0, -v0
	v_min_f32_e32 v0, 0x41f00000, v0
	v_mul_f32_e32 v0, 0x3fb8aa3b, v0
	v_exp_f32_e32 v0, v0
	s_nop 0
	v_add_f32_e32 v0, 1.0, v0
	v_rcp_f32_e32 v153, v0
	v_lshlrev_b32_e32 v0, 16, v151
	v_max_f32_e64 v0, -v0, -v0
	v_min_f32_e32 v0, 0x41f00000, v0
	v_mul_f32_e32 v0, 0x3fb8aa3b, v0
	v_exp_f32_e32 v0, v0
	v_pk_mul_f32 v[152:153], v[112:113], v[152:153]
	v_add_f32_e32 v0, 1.0, v0
	v_cvt_pk_bf16_f32 v150, v152, v153
	v_rcp_f32_e32 v152, v0
	v_and_b32_e32 v0, 0xffff0000, v151
	v_max_f32_e64 v0, -v0, -v0
	v_min_f32_e32 v0, 0x41f00000, v0
	v_mul_f32_e32 v0, 0x3fb8aa3b, v0
	v_exp_f32_e32 v0, v0
	s_nop 0
	v_add_f32_e32 v0, 1.0, v0
	v_rcp_f32_e32 v153, v0
	v_lshlrev_b32_e32 v0, 16, v144
	v_max_f32_e64 v0, -v0, -v0
	v_min_f32_e32 v0, 0x41f00000, v0
	v_mul_f32_e32 v0, 0x3fb8aa3b, v0
	v_exp_f32_e32 v0, v0
	v_pk_mul_f32 v[152:153], v[114:115], v[152:153]
	v_add_f32_e32 v0, 1.0, v0
	v_cvt_pk_bf16_f32 v151, v152, v153
	global_store_dwordx4 v[156:157], v[148:151], off offset:256
	s_nop 1
	v_rcp_f32_e32 v150, v0
	v_and_b32_e32 v0, 0xffff0000, v144
	v_max_f32_e64 v0, -v0, -v0
	v_min_f32_e32 v0, 0x41f00000, v0
	v_mul_f32_e32 v0, 0x3fb8aa3b, v0
	v_exp_f32_e32 v0, v0
	v_lshlrev_b64 v[148:149], 11, v[200:201]
	v_lshl_add_u64 v[148:149], s[56:57], 0, v[148:149]
	v_lshl_add_u64 v[148:149], v[148:149], 0, v[194:195]
	v_add_f32_e32 v0, 1.0, v0
	v_rcp_f32_e32 v151, v0
	v_lshlrev_b32_e32 v0, 16, v145
	v_max_f32_e64 v0, -v0, -v0
	v_min_f32_e32 v0, 0x41f00000, v0
	v_mul_f32_e32 v0, 0x3fb8aa3b, v0
	v_exp_f32_e32 v0, v0
	v_pk_mul_f32 v[150:151], v[84:85], v[150:151]
	v_add_f32_e32 v0, 1.0, v0
	v_cvt_pk_bf16_f32 v144, v150, v151
	v_rcp_f32_e32 v150, v0
	v_and_b32_e32 v0, 0xffff0000, v145
	v_max_f32_e64 v0, -v0, -v0
	v_min_f32_e32 v0, 0x41f00000, v0
	v_mul_f32_e32 v0, 0x3fb8aa3b, v0
	v_exp_f32_e32 v0, v0
	s_nop 0
	v_add_f32_e32 v0, 1.0, v0
	v_rcp_f32_e32 v151, v0
	v_lshlrev_b32_e32 v0, 16, v146
	v_max_f32_e64 v0, -v0, -v0
	v_min_f32_e32 v0, 0x41f00000, v0
	v_mul_f32_e32 v0, 0x3fb8aa3b, v0
	v_exp_f32_e32 v0, v0
; __device__ __forceinline__ unsigned pk2(float lo, float hi) { v2f v = {lo, hi}; return __builtin_bit_cast(unsigned, __builtin_convertvector(v, v2bf)); }
; __device__ __forceinline__ float bflo(unsigned u) { return __uint_as_float(u << 16); }
; __device__ __forceinline__ float bfhi(unsigned u) { return __uint_as_float(u & 0xffff0000u); }
; #define SG(a_, g_) ((a_) * __builtin_amdgcn_rcpf(einv(g_)))
;     __device__ __forceinline__ void operator()(f32x4 (&acc)[2][2][4][2], const Unit& u, int wr, int wc, int fr, int fq) const {
;     ...
;             for (int m = 0; m < 4; ++m) { const int row = row0 + ai * 128 + m * 16;
; #pragma unroll
;                 for (int bj = 0; bj < 2; ++bj) { const int col = col0 + bj * 128;
;                     const v4u gw = gq[m][bj];
;                     const f32x4 a0 = acc[ai][bj][m][0], a1 = acc[ai][bj][m][1];
;     ...
;                     v4u w; w.x = pk2(SG(a0[0], bflo(gw.x)), SG(a0[1], bfhi(gw.x))); w.y = pk2(SG(a0[2], bflo(gw.y)), SG(a0[3], bfhi(gw.y)));
;                     w.z = pk2(SG(a1[0], bflo(gw.z)), SG(a1[1], bfhi(gw.z))); w.w = pk2(SG(a1[2], bflo(gw.w)), SG(a1[3], bfhi(gw.w)));
;     ...
;                     *(v4u*)(MB + (size_t)row * 1024 + col) = w; } }
	v_pk_mul_f32 v[150:151], v[86:87], v[150:151]
	v_add_f32_e32 v0, 1.0, v0
	v_cvt_pk_bf16_f32 v145, v150, v151
	v_rcp_f32_e32 v150, v0
	v_and_b32_e32 v0, 0xffff0000, v146
	v_max_f32_e64 v0, -v0, -v0
	v_min_f32_e32 v0, 0x41f00000, v0
	v_mul_f32_e32 v0, 0x3fb8aa3b, v0
	v_exp_f32_e32 v0, v0
	s_nop 0
	v_add_f32_e32 v0, 1.0, v0
	v_rcp_f32_e32 v151, v0
	v_lshlrev_b32_e32 v0, 16, v147
	v_max_f32_e64 v0, -v0, -v0
	v_min_f32_e32 v0, 0x41f00000, v0
	v_mul_f32_e32 v0, 0x3fb8aa3b, v0
	v_exp_f32_e32 v0, v0
	v_pk_mul_f32 v[150:151], v[88:89], v[150:151]
	v_add_f32_e32 v0, 1.0, v0
	v_cvt_pk_bf16_f32 v146, v150, v151
	v_rcp_f32_e32 v150, v0
	v_and_b32_e32 v0, 0xffff0000, v147
	v_max_f32_e64 v0, -v0, -v0
	v_min_f32_e32 v0, 0x41f00000, v0
	v_mul_f32_e32 v0, 0x3fb8aa3b, v0
	v_exp_f32_e32 v0, v0
	s_nop 0
	v_add_f32_e32 v0, 1.0, v0
	v_rcp_f32_e32 v151, v0
	v_lshlrev_b32_e32 v0, 16, v140
	v_max_f32_e64 v0, -v0, -v0
	v_min_f32_e32 v0, 0x41f00000, v0
	v_mul_f32_e32 v0, 0x3fb8aa3b, v0
	v_exp_f32_e32 v0, v0
	v_pk_mul_f32 v[150:151], v[90:91], v[150:151]
	v_add_f32_e32 v0, 1.0, v0
	v_cvt_pk_bf16_f32 v147, v150, v151
	global_store_dwordx4 v[148:149], v[144:147], off
	s_nop 1
	v_rcp_f32_e32 v144, v0
	v_and_b32_e32 v0, 0xffff0000, v140
	v_max_f32_e64 v0, -v0, -v0
	v_min_f32_e32 v0, 0x41f00000, v0
	v_mul_f32_e32 v0, 0x3fb8aa3b, v0
	v_exp_f32_e32 v0, v0
	s_nop 0
	v_add_f32_e32 v0, 1.0, v0
	v_rcp_f32_e32 v145, v0
	v_lshlrev_b32_e32 v0, 16, v141
	v_max_f32_e64 v0, -v0, -v0
	v_min_f32_e32 v0, 0x41f00000, v0
	v_mul_f32_e32 v0, 0x3fb8aa3b, v0
	v_exp_f32_e32 v0, v0
	v_pk_mul_f32 v[144:145], v[116:117], v[144:145]
	v_add_f32_e32 v0, 1.0, v0
	v_cvt_pk_bf16_f32 v140, v144, v145
	v_rcp_f32_e32 v144, v0
	v_and_b32_e32 v0, 0xffff0000, v141
	v_max_f32_e64 v0, -v0, -v0
	v_min_f32_e32 v0, 0x41f00000, v0
	v_mul_f32_e32 v0, 0x3fb8aa3b, v0
	v_exp_f32_e32 v0, v0
	s_nop 0
	v_add_f32_e32 v0, 1.0, v0
	v_rcp_f32_e32 v145, v0
	v_lshlrev_b32_e32 v0, 16, v142
	v_max_f32_e64 v0, -v0, -v0
	v_min_f32_e32 v0, 0x41f00000, v0
	v_mul_f32_e32 v0, 0x3fb8aa3b, v0
	v_exp_f32_e32 v0, v0
	v_pk_mul_f32 v[144:145], v[118:119], v[144:145]
	v_add_f32_e32 v0, 1.0, v0
	v_cvt_pk_bf16_f32 v141, v144, v145
	v_rcp_f32_e32 v144, v0
	v_and_b32_e32 v0, 0xffff0000, v142
	v_max_f32_e64 v0, -v0, -v0
	v_min_f32_e32 v0, 0x41f00000, v0
	v_mul_f32_e32 v0, 0x3fb8aa3b, v0
	v_exp_f32_e32 v0, v0
	s_nop 0
	v_add_f32_e32 v0, 1.0, v0
	v_rcp_f32_e32 v145, v0
	v_lshlrev_b32_e32 v0, 16, v143
	v_max_f32_e64 v0, -v0, -v0
	v_min_f32_e32 v0, 0x41f00000, v0
	v_mul_f32_e32 v0, 0x3fb8aa3b, v0
	v_exp_f32_e32 v0, v0
	v_pk_mul_f32 v[144:145], v[120:121], v[144:145]
	v_add_f32_e32 v0, 1.0, v0
	v_cvt_pk_bf16_f32 v142, v144, v145
	v_rcp_f32_e32 v144, v0
	v_and_b32_e32 v0, 0xffff0000, v143
	v_max_f32_e64 v0, -v0, -v0
	v_min_f32_e32 v0, 0x41f00000, v0
	v_mul_f32_e32 v0, 0x3fb8aa3b, v0
	v_exp_f32_e32 v0, v0
	s_nop 0
	v_add_f32_e32 v0, 1.0, v0
	v_rcp_f32_e32 v145, v0
	v_lshlrev_b32_e32 v0, 16, v136
	v_max_f32_e64 v0, -v0, -v0
	v_min_f32_e32 v0, 0x41f00000, v0
	v_mul_f32_e32 v0, 0x3fb8aa3b, v0
	v_exp_f32_e32 v0, v0
	v_pk_mul_f32 v[144:145], v[122:123], v[144:145]
	v_add_f32_e32 v0, 1.0, v0
	v_cvt_pk_bf16_f32 v143, v144, v145
	global_store_dwordx4 v[148:149], v[140:143], off offset:256
	s_nop 1
	v_rcp_f32_e32 v142, v0
	v_and_b32_e32 v0, 0xffff0000, v136
	v_max_f32_e64 v0, -v0, -v0
	v_min_f32_e32 v0, 0x41f00000, v0
	v_mul_f32_e32 v0, 0x3fb8aa3b, v0
	v_exp_f32_e32 v0, v0
	v_lshlrev_b64 v[140:141], 11, v[198:199]
	v_lshl_add_u64 v[140:141], s[56:57], 0, v[140:141]
	v_lshl_add_u64 v[140:141], v[140:141], 0, v[194:195]
	v_add_f32_e32 v0, 1.0, v0
	v_rcp_f32_e32 v143, v0
	v_lshlrev_b32_e32 v0, 16, v137
	v_max_f32_e64 v0, -v0, -v0
; __device__ __forceinline__ unsigned pk2(float lo, float hi) { v2f v = {lo, hi}; return __builtin_bit_cast(unsigned, __builtin_convertvector(v, v2bf)); }
; __device__ __forceinline__ float bflo(unsigned u) { return __uint_as_float(u << 16); }
; __device__ __forceinline__ float bfhi(unsigned u) { return __uint_as_float(u & 0xffff0000u); }
; #define SG(a_, g_) ((a_) * __builtin_amdgcn_rcpf(einv(g_)))
;     __device__ __forceinline__ void operator()(f32x4 (&acc)[2][2][4][2], const Unit& u, int wr, int wc, int fr, int fq) const {
;     ...
;             for (int m = 0; m < 4; ++m) { const int row = row0 + ai * 128 + m * 16;
; #pragma unroll
;                 for (int bj = 0; bj < 2; ++bj) { const int col = col0 + bj * 128;
;                     const v4u gw = gq[m][bj];
;                     const f32x4 a0 = acc[ai][bj][m][0], a1 = acc[ai][bj][m][1];
;     ...
;                     v4u w; w.x = pk2(SG(a0[0], bflo(gw.x)), SG(a0[1], bfhi(gw.x))); w.y = pk2(SG(a0[2], bflo(gw.y)), SG(a0[3], bfhi(gw.y)));
;                     w.z = pk2(SG(a1[0], bflo(gw.z)), SG(a1[1], bfhi(gw.z))); w.w = pk2(SG(a1[2], bflo(gw.w)), SG(a1[3], bfhi(gw.w)));
;     ...
;                     *(v4u*)(MB + (size_t)row * 1024 + col) = w; } }
	v_min_f32_e32 v0, 0x41f00000, v0
	v_mul_f32_e32 v0, 0x3fb8aa3b, v0
	v_exp_f32_e32 v0, v0
	v_pk_mul_f32 v[142:143], v[92:93], v[142:143]
	v_add_f32_e32 v0, 1.0, v0
	v_cvt_pk_bf16_f32 v136, v142, v143
	v_rcp_f32_e32 v142, v0
	v_and_b32_e32 v0, 0xffff0000, v137
	v_max_f32_e64 v0, -v0, -v0
	v_min_f32_e32 v0, 0x41f00000, v0
	v_mul_f32_e32 v0, 0x3fb8aa3b, v0
	v_exp_f32_e32 v0, v0
	s_nop 0
	v_add_f32_e32 v0, 1.0, v0
	v_rcp_f32_e32 v143, v0
	v_lshlrev_b32_e32 v0, 16, v138
	v_max_f32_e64 v0, -v0, -v0
	v_min_f32_e32 v0, 0x41f00000, v0
	v_mul_f32_e32 v0, 0x3fb8aa3b, v0
	v_exp_f32_e32 v0, v0
	v_pk_mul_f32 v[142:143], v[94:95], v[142:143]
	v_add_f32_e32 v0, 1.0, v0
	v_cvt_pk_bf16_f32 v137, v142, v143
	v_rcp_f32_e32 v142, v0
	v_and_b32_e32 v0, 0xffff0000, v138
	v_max_f32_e64 v0, -v0, -v0
	v_min_f32_e32 v0, 0x41f00000, v0
	v_mul_f32_e32 v0, 0x3fb8aa3b, v0
	v_exp_f32_e32 v0, v0
	s_nop 0
	v_add_f32_e32 v0, 1.0, v0
	v_rcp_f32_e32 v143, v0
	v_lshlrev_b32_e32 v0, 16, v139
	v_max_f32_e64 v0, -v0, -v0
	v_min_f32_e32 v0, 0x41f00000, v0
	v_mul_f32_e32 v0, 0x3fb8aa3b, v0
	v_exp_f32_e32 v0, v0
	v_pk_mul_f32 v[142:143], v[96:97], v[142:143]
	v_add_f32_e32 v0, 1.0, v0
	v_cvt_pk_bf16_f32 v138, v142, v143
	v_rcp_f32_e32 v142, v0
	v_and_b32_e32 v0, 0xffff0000, v139
	v_max_f32_e64 v0, -v0, -v0
	v_min_f32_e32 v0, 0x41f00000, v0
	v_mul_f32_e32 v0, 0x3fb8aa3b, v0
	v_exp_f32_e32 v0, v0
	s_nop 0
	v_add_f32_e32 v0, 1.0, v0
	v_rcp_f32_e32 v143, v0
	v_lshlrev_b32_e32 v0, 16, v132
	v_max_f32_e64 v0, -v0, -v0
	v_min_f32_e32 v0, 0x41f00000, v0
	v_mul_f32_e32 v0, 0x3fb8aa3b, v0
	v_exp_f32_e32 v0, v0
	v_pk_mul_f32 v[142:143], v[98:99], v[142:143]
	v_add_f32_e32 v0, 1.0, v0
	v_cvt_pk_bf16_f32 v139, v142, v143
	global_store_dwordx4 v[140:141], v[136:139], off
	s_nop 1
	v_rcp_f32_e32 v136, v0
	v_and_b32_e32 v0, 0xffff0000, v132
	v_max_f32_e64 v0, -v0, -v0
	v_min_f32_e32 v0, 0x41f00000, v0
	v_mul_f32_e32 v0, 0x3fb8aa3b, v0
	v_exp_f32_e32 v0, v0
	s_nop 0
	v_add_f32_e32 v0, 1.0, v0
	v_rcp_f32_e32 v137, v0
	v_lshlrev_b32_e32 v0, 16, v133
	v_max_f32_e64 v0, -v0, -v0
	v_min_f32_e32 v0, 0x41f00000, v0
	v_mul_f32_e32 v0, 0x3fb8aa3b, v0
	v_exp_f32_e32 v0, v0
	v_pk_mul_f32 v[136:137], v[124:125], v[136:137]
	v_add_f32_e32 v0, 1.0, v0
	v_cvt_pk_bf16_f32 v132, v136, v137
	v_rcp_f32_e32 v136, v0
	v_and_b32_e32 v0, 0xffff0000, v133
	v_max_f32_e64 v0, -v0, -v0
	v_min_f32_e32 v0, 0x41f00000, v0
	v_mul_f32_e32 v0, 0x3fb8aa3b, v0
	v_exp_f32_e32 v0, v0
	s_nop 0
	v_add_f32_e32 v0, 1.0, v0
	v_rcp_f32_e32 v137, v0
	v_lshlrev_b32_e32 v0, 16, v134
	v_max_f32_e64 v0, -v0, -v0
	v_min_f32_e32 v0, 0x41f00000, v0
	v_mul_f32_e32 v0, 0x3fb8aa3b, v0
	v_exp_f32_e32 v0, v0
	v_pk_mul_f32 v[136:137], v[126:127], v[136:137]
	v_add_f32_e32 v0, 1.0, v0
	v_cvt_pk_bf16_f32 v133, v136, v137
	v_rcp_f32_e32 v136, v0
	v_and_b32_e32 v0, 0xffff0000, v134
	v_max_f32_e64 v0, -v0, -v0
	v_min_f32_e32 v0, 0x41f00000, v0
	v_mul_f32_e32 v0, 0x3fb8aa3b, v0
	v_exp_f32_e32 v0, v0
	s_nop 0
	v_add_f32_e32 v0, 1.0, v0
	v_rcp_f32_e32 v137, v0
	v_lshlrev_b32_e32 v0, 16, v135
	v_max_f32_e64 v0, -v0, -v0
	v_min_f32_e32 v0, 0x41f00000, v0
	v_mul_f32_e32 v0, 0x3fb8aa3b, v0
	v_exp_f32_e32 v0, v0
	v_pk_mul_f32 v[136:137], v[128:129], v[136:137]
	v_add_f32_e32 v0, 1.0, v0
	v_cvt_pk_bf16_f32 v134, v136, v137
	v_rcp_f32_e32 v136, v0
	v_and_b32_e32 v0, 0xffff0000, v135
	v_max_f32_e64 v0, -v0, -v0
	v_min_f32_e32 v0, 0x41f00000, v0
	v_mul_f32_e32 v0, 0x3fb8aa3b, v0
	v_exp_f32_e32 v0, v0
	s_nop 0
	v_add_f32_e32 v0, 1.0, v0
	v_rcp_f32_e32 v137, v0
	s_nop 0
	v_pk_mul_f32 v[136:137], v[130:131], v[136:137]
	s_nop 0
	v_cvt_pk_bf16_f32 v135, v136, v137
	global_store_dwordx4 v[140:141], v[132:135], off offset:256

; #define PG8_STAGE(bufoff, gbase, voff) do { _Pragma("unroll") for (int _i = 0; _i < 2; ++_i) \
;         __builtin_amdgcn_global_load_lds((const unsigned*)((const char*)(gbase) + (voff)[_i]), (PG8_LAS unsigned*)(lds + (bufoff) + ldsw + _i * 8192), 16, 0, 0); } while (0)
; #define PG8_LDA(dst, b, h) do { _Pragma("unroll") for (int m = 0; m < 4; ++m) _Pragma("unroll") for (int k = 0; k < 2; ++k) dst[m][k] = *(const PG8_LAS bf16x8*)(lds + PG8_SA(b, h) + aoff + m * 2048 + k * 1024); } while (0)
; #define PG8_LDB(dst, b, h) do { _Pragma("unroll") for (int n = 0; n < 2; ++n) _Pragma("unroll") for (int k = 0; k < 2; ++k) dst[n][k] = *(const PG8_LAS bf16x8*)(lds + PG8_SB(b, h) + boff + n * 2048 + k * 1024); } while (0)
; #define PG8_MMA(ai, bj, At, Bt) do { __builtin_amdgcn_s_setprio(1); _Pragma("unroll") for (int m = 0; m < 4; ++m) _Pragma("unroll") for (int n = 0; n < 2; ++n) _Pragma("unroll") for (int k = 0; k < 2; ++k) \
;         acc[ai][bj][m][n] = __builtin_amdgcn_mfma_f32_16x16x32_bf16(Bt[n][k], At[m][k], acc[ai][bj][m][n], 0, 0, 0); __builtin_amdgcn_s_setprio(0); } while (0)
; #define PG8_WAIT_V(n) asm volatile("s_waitcnt vmcnt(" #n ")" ::: "memory")
; #define PG8_WAIT_L(n) asm volatile("s_waitcnt lgkmcnt(" #n ")" ::: "memory")
; #define PG8_BAR __builtin_amdgcn_s_barrier()
; #define PG8_SCHED __builtin_amdgcn_sched_barrier(0)
; template <class Epi, class Sched>
; __device__ __forceinline__ void gemm_phase(PG8_LAS unsigned char* lds, const Gemm g, const Sched& S, const Epi& E) {
;     ...
;             PG8_LDB(B0, 0, 0); PG8_SCHED; PG8_LDA(At, 0, 0); PG8_STAGE(PG8_SA(1, 1), a1 + hstep, voffA);
;             PG8_WAIT_L(8); PG8_BAR; PG8_WAIT_L(0); PG8_MMA(0, 0, At, B0); PG8_BAR; PG8_SCHED;
;             PG8_LDB(B1, 0, 1); PG8_STAGE(PG8_SB(0, 0), b2, voffB);
;             PG8_BAR; PG8_WAIT_L(0); PG8_MMA(0, 1, At, B1); PG8_BAR;
;             PG8_LDA(At, 0, 1); PG8_STAGE(PG8_SA(0, 0), a2, voffA);
;             PG8_BAR; PG8_WAIT_L(0); PG8_MMA(1, 0, At, B0); PG8_BAR; PG8_SCHED;
;             PG8_STAGE(PG8_SB(0, 1), b2 + hstep, voffB);
;             PG8_WAIT_V(6); PG8_BAR; PG8_MMA(1, 1, At, B1); PG8_BAR;
.LBB0_548:
	s_add_u32 s10, vcc_lo, 0xfffc0080
	s_addc_u32 s11, vcc_hi, -1
	s_add_i32 s84, 0, 0x10000
	v_add_u32_e32 v156, s84, v141
	ds_read_b128 v[144:147], v156
	ds_read_b128 v[148:151], v156 offset:1024
	ds_read_b128 v[152:155], v156 offset:2048
	ds_read_b128 v[156:159], v156 offset:3072
	s_cmp_eq_u32 s83, 12
	s_cselect_b32 s51, s21, s11
	s_cselect_b32 s50, s79, s10
	s_cselect_b32 s11, s19, s82
	s_cselect_b32 s10, s80, s81
	v_lshl_add_u64 v[202:203], vcc, 0, v[136:137]
	s_add_i32 m0, s70, 0xc000
	ds_read_b128 v[160:163], v143
	ds_read_b128 v[174:177], v143 offset:1024
	ds_read_b128 v[178:181], v143 offset:2048
	ds_read_b128 v[182:185], v143 offset:3072
	ds_read_b128 v[186:189], v143 offset:4096
	ds_read_b128 v[190:193], v143 offset:5120
	ds_read_b128 v[194:197], v143 offset:6144
	ds_read_b128 v[198:201], v143 offset:7168
	global_load_lds_dwordx4 v[202:203], off
	v_lshl_add_u64 v[202:203], vcc, 0, v[138:139]
	s_add_i32 m0, s70, 0xe000
	s_nop 0
	global_load_lds_dwordx4 v[202:203], off
	s_waitcnt lgkmcnt(8)
	s_barrier
	s_waitcnt lgkmcnt(0)
	s_setprio 1
	v_mfma_f32_16x16x32_bf16 v[6:9], v[144:147], v[160:163], v[6:9]
	v_mfma_f32_16x16x32_bf16 v[2:5], v[152:155], v[160:163], v[2:5]
	v_mfma_f32_16x16x32_bf16 v[22:25], v[144:147], v[178:181], v[22:25]
	v_mfma_f32_16x16x32_bf16 v[18:21], v[152:155], v[178:181], v[18:21]
	v_mfma_f32_16x16x32_bf16 v[38:41], v[144:147], v[186:189], v[38:41]
	v_mfma_f32_16x16x32_bf16 v[34:37], v[152:155], v[186:189], v[34:37]
	v_mfma_f32_16x16x32_bf16 v[54:57], v[144:147], v[194:197], v[54:57]
	v_mfma_f32_16x16x32_bf16 v[50:53], v[152:155], v[194:197], v[50:53]
	v_mfma_f32_16x16x32_bf16 v[6:9], v[148:151], v[174:177], v[6:9]
	v_mfma_f32_16x16x32_bf16 v[2:5], v[156:159], v[174:177], v[2:5]
	v_mfma_f32_16x16x32_bf16 v[22:25], v[148:151], v[182:185], v[22:25]
	v_mfma_f32_16x16x32_bf16 v[18:21], v[156:159], v[182:185], v[18:21]
	v_mfma_f32_16x16x32_bf16 v[38:41], v[148:151], v[190:193], v[38:41]
	v_mfma_f32_16x16x32_bf16 v[34:37], v[156:159], v[190:193], v[34:37]
	v_mfma_f32_16x16x32_bf16 v[54:57], v[148:151], v[198:201], v[54:57]
	v_mfma_f32_16x16x32_bf16 v[50:53], v[156:159], v[198:201], v[50:53]
	s_setprio 0
	s_barrier
	s_add_i32 s86, 0, 0x14000
	v_add_u32_e32 v202, s86, v141
	s_add_i32 s84, s84, s53
	ds_read_b128 v[222:225], v202
	ds_read_b128 v[226:229], v202 offset:1024
	ds_read_b128 v[230:233], v202 offset:2048
	ds_read_b128 v[234:237], v202 offset:3072
	v_lshl_add_u64 v[202:203], s[10:11], 0, v[0:1]
	s_mov_b32 m0, s84
	v_lshl_add_u64 v[238:239], s[10:11], 0, v[130:131]
	global_load_lds_dwordx4 v[202:203], off
	s_add_i32 m0, s84, 0x2000
	s_nop 0
	global_load_lds_dwordx4 v[238:239], off
	s_barrier
	s_waitcnt lgkmcnt(0)
	s_setprio 1
	v_mfma_f32_16x16x32_bf16 v[14:17], v[222:225], v[160:163], v[14:17]
	v_mfma_f32_16x16x32_bf16 v[10:13], v[230:233], v[160:163], v[10:13]
	v_mfma_f32_16x16x32_bf16 v[30:33], v[222:225], v[178:181], v[30:33]
	v_mfma_f32_16x16x32_bf16 v[26:29], v[230:233], v[178:181], v[26:29]
	v_mfma_f32_16x16x32_bf16 v[46:49], v[222:225], v[186:189], v[46:49]
	v_mfma_f32_16x16x32_bf16 v[42:45], v[230:233], v[186:189], v[42:45]
	v_mfma_f32_16x16x32_bf16 v[62:65], v[222:225], v[194:197], v[62:65]
	v_mfma_f32_16x16x32_bf16 v[58:61], v[230:233], v[194:197], v[58:61]
	v_mfma_f32_16x16x32_bf16 v[14:17], v[226:229], v[174:177], v[14:17]
	v_mfma_f32_16x16x32_bf16 v[10:13], v[234:237], v[174:177], v[10:13]
	v_mfma_f32_16x16x32_bf16 v[30:33], v[226:229], v[182:185], v[30:33]
	v_mfma_f32_16x16x32_bf16 v[26:29], v[234:237], v[182:185], v[26:29]
	v_mfma_f32_16x16x32_bf16 v[46:49], v[226:229], v[190:193], v[46:49]
	v_mfma_f32_16x16x32_bf16 v[42:45], v[234:237], v[190:193], v[42:45]
	v_mfma_f32_16x16x32_bf16 v[62:65], v[226:229], v[198:201], v[62:65]
	v_mfma_f32_16x16x32_bf16 v[58:61], v[234:237], v[198:201], v[58:61]
	s_setprio 0
	s_mov_b32 m0, s70
	v_lshl_add_u64 v[240:241], s[50:51], 0, v[134:135]
	s_barrier
	ds_read_b128 v[160:163], v143 offset:16384
	ds_read_b128 v[174:177], v143 offset:17408
	ds_read_b128 v[178:181], v143 offset:18432
	ds_read_b128 v[182:185], v143 offset:19456
	ds_read_b128 v[186:189], v143 offset:20480
	ds_read_b128 v[190:193], v143 offset:21504
	ds_read_b128 v[194:197], v143 offset:22528
	ds_read_b128 v[198:201], v143 offset:23552
	global_load_lds_dwordx4 v[240:241], off
	v_lshl_add_u64 v[242:243], s[50:51], 0, v[132:133]
	s_mov_b32 m0, s71
	s_nop 0
	global_load_lds_dwordx4 v[242:243], off
	s_barrier
	s_waitcnt lgkmcnt(0)
	s_setprio 1
	v_mfma_f32_16x16x32_bf16 v[66:69], v[144:147], v[160:163], v[66:69]
	v_mfma_f32_16x16x32_bf16 v[70:73], v[152:155], v[160:163], v[70:73]
	v_mfma_f32_16x16x32_bf16 v[82:85], v[144:147], v[178:181], v[82:85]
	v_mfma_f32_16x16x32_bf16 v[86:89], v[152:155], v[178:181], v[86:89]
	v_mfma_f32_16x16x32_bf16 v[98:101], v[144:147], v[186:189], v[98:101]
	v_mfma_f32_16x16x32_bf16 v[102:105], v[152:155], v[186:189], v[102:105]
	v_mfma_f32_16x16x32_bf16 v[114:117], v[144:147], v[194:197], v[114:117]
	v_mfma_f32_16x16x32_bf16 v[118:121], v[152:155], v[194:197], v[118:121]
	v_mfma_f32_16x16x32_bf16 v[66:69], v[148:151], v[174:177], v[66:69]
	v_mfma_f32_16x16x32_bf16 v[70:73], v[156:159], v[174:177], v[70:73]
	v_mfma_f32_16x16x32_bf16 v[82:85], v[148:151], v[182:185], v[82:85]
	v_mfma_f32_16x16x32_bf16 v[86:89], v[156:159], v[182:185], v[86:89]
	v_mfma_f32_16x16x32_bf16 v[98:101], v[148:151], v[190:193], v[98:101]
	v_mfma_f32_16x16x32_bf16 v[102:105], v[156:159], v[190:193], v[102:105]
	v_mfma_f32_16x16x32_bf16 v[114:117], v[148:151], v[198:201], v[114:117]
	v_mfma_f32_16x16x32_bf16 v[118:121], v[156:159], v[198:201], v[118:121]
	s_setprio 0
	s_barrier
; #define PG8_STAGE(bufoff, gbase, voff) do { _Pragma("unroll") for (int _i = 0; _i < 2; ++_i) \
;         __builtin_amdgcn_global_load_lds((const unsigned*)((const char*)(gbase) + (voff)[_i]), (PG8_LAS unsigned*)(lds + (bufoff) + ldsw + _i * 8192), 16, 0, 0); } while (0)
; #define PG8_LDA(dst, b, h) do { _Pragma("unroll") for (int m = 0; m < 4; ++m) _Pragma("unroll") for (int k = 0; k < 2; ++k) dst[m][k] = *(const PG8_LAS bf16x8*)(lds + PG8_SA(b, h) + aoff + m * 2048 + k * 1024); } while (0)
; #define PG8_LDB(dst, b, h) do { _Pragma("unroll") for (int n = 0; n < 2; ++n) _Pragma("unroll") for (int k = 0; k < 2; ++k) dst[n][k] = *(const PG8_LAS bf16x8*)(lds + PG8_SB(b, h) + boff + n * 2048 + k * 1024); } while (0)
; #define PG8_MMA(ai, bj, At, Bt) do { __builtin_amdgcn_s_setprio(1); _Pragma("unroll") for (int m = 0; m < 4; ++m) _Pragma("unroll") for (int n = 0; n < 2; ++n) _Pragma("unroll") for (int k = 0; k < 2; ++k) \
;         acc[ai][bj][m][n] = __builtin_amdgcn_mfma_f32_16x16x32_bf16(Bt[n][k], At[m][k], acc[ai][bj][m][n], 0, 0, 0); __builtin_amdgcn_s_setprio(0); } while (0)
; #define PG8_WAIT_V(n) asm volatile("s_waitcnt vmcnt(" #n ")" ::: "memory")
; #define PG8_WAIT_L(n) asm volatile("s_waitcnt lgkmcnt(" #n ")" ::: "memory")
; #define PG8_BAR __builtin_amdgcn_s_barrier()
; #define PG8_SCHED __builtin_amdgcn_sched_barrier(0)
; template <class Epi, class Sched>
; __device__ __forceinline__ void gemm_phase(PG8_LAS unsigned char* lds, const Gemm g, const Sched& S, const Epi& E) {
;     ...
;             PG8_STAGE(PG8_SB(0, 1), b2 + hstep, voffB);
;             PG8_WAIT_V(6); PG8_BAR; PG8_MMA(1, 1, At, B1); PG8_BAR;
;             PG8_LDB(B0, 1, 0); PG8_SCHED; PG8_LDA(At, 1, 0); PG8_STAGE(PG8_SA(0, 1), a2 + hstep, voffA);
;             PG8_WAIT_L(8); PG8_BAR; PG8_WAIT_L(0); PG8_MMA(0, 0, At, B0); PG8_BAR; PG8_SCHED;
;             PG8_LDB(B1, 1, 1); PG8_STAGE(PG8_SB(1, 0), b3, voffB);
;             PG8_BAR; PG8_WAIT_L(0); PG8_MMA(0, 1, At, B1); PG8_BAR;
;             PG8_LDA(At, 1, 1); PG8_STAGE(PG8_SA(1, 0), a3, voffA);
;             PG8_BAR; PG8_WAIT_L(0); PG8_MMA(1, 0, At, B0); PG8_BAR; PG8_SCHED;
	s_add_u32 s84, s10, 0x40000
	s_addc_u32 s85, s11, 0
	s_add_i32 s86, s86, s53
	v_lshl_add_u64 v[144:145], s[84:85], 0, v[0:1]
	s_mov_b32 m0, s86
	s_nop 0
	global_load_lds_dwordx4 v[144:145], off
	v_lshl_add_u64 v[144:145], s[84:85], 0, v[130:131]
	s_add_i32 m0, s86, 0x2000
	s_nop 0
	global_load_lds_dwordx4 v[144:145], off
	s_waitcnt vmcnt(6)
	s_barrier
	s_setprio 1
	v_mfma_f32_16x16x32_bf16 v[78:81], v[222:225], v[160:163], v[78:81]
	v_mfma_f32_16x16x32_bf16 v[74:77], v[230:233], v[160:163], v[74:77]
	v_mfma_f32_16x16x32_bf16 v[94:97], v[222:225], v[178:181], v[94:97]
	v_mfma_f32_16x16x32_bf16 v[90:93], v[230:233], v[178:181], v[90:93]
	v_mfma_f32_16x16x32_bf16 v[110:113], v[222:225], v[186:189], v[110:113]
	v_mfma_f32_16x16x32_bf16 v[106:109], v[230:233], v[186:189], v[106:109]
	v_mfma_f32_16x16x32_bf16 v[126:129], v[222:225], v[194:197], v[126:129]
	v_mfma_f32_16x16x32_bf16 v[122:125], v[230:233], v[194:197], v[122:125]
	v_mfma_f32_16x16x32_bf16 v[78:81], v[226:229], v[174:177], v[78:81]
	v_mfma_f32_16x16x32_bf16 v[74:77], v[234:237], v[174:177], v[74:77]
	v_mfma_f32_16x16x32_bf16 v[94:97], v[226:229], v[182:185], v[94:97]
	v_mfma_f32_16x16x32_bf16 v[90:93], v[234:237], v[182:185], v[90:93]
	v_mfma_f32_16x16x32_bf16 v[110:113], v[226:229], v[190:193], v[110:113]
	v_mfma_f32_16x16x32_bf16 v[106:109], v[234:237], v[190:193], v[106:109]
	v_mfma_f32_16x16x32_bf16 v[126:129], v[226:229], v[198:201], v[126:129]
	v_mfma_f32_16x16x32_bf16 v[122:125], v[234:237], v[198:201], v[122:125]
	s_setprio 0
	s_add_i32 s84, 0, 0x18000
	v_add_u32_e32 v156, s84, v141
	s_barrier
	ds_read_b128 v[144:147], v156
	ds_read_b128 v[148:151], v156 offset:1024
	ds_read_b128 v[152:155], v156 offset:2048
	ds_read_b128 v[156:159], v156 offset:3072
	s_add_u32 s50, s50, 0x40000
	s_addc_u32 s51, s51, 0
	s_mov_b32 m0, s72
	v_lshl_add_u64 v[222:223], s[50:51], 0, v[134:135]
	ds_read_b128 v[160:163], v143 offset:32768
	ds_read_b128 v[174:177], v143 offset:33792
	ds_read_b128 v[178:181], v143 offset:34816
	ds_read_b128 v[182:185], v143 offset:35840
	ds_read_b128 v[186:189], v143 offset:36864
	ds_read_b128 v[190:193], v143 offset:37888
	ds_read_b128 v[194:197], v143 offset:38912
	ds_read_b128 v[198:201], v143 offset:39936
	global_load_lds_dwordx4 v[222:223], off
	v_lshl_add_u64 v[222:223], s[50:51], 0, v[132:133]
	s_mov_b32 m0, s73
	s_nop 0
	global_load_lds_dwordx4 v[222:223], off
	s_waitcnt lgkmcnt(8)
	s_barrier
	s_waitcnt lgkmcnt(0)
	s_setprio 1
	v_mfma_f32_16x16x32_bf16 v[6:9], v[144:147], v[160:163], v[6:9]
	v_mfma_f32_16x16x32_bf16 v[2:5], v[152:155], v[160:163], v[2:5]
	v_mfma_f32_16x16x32_bf16 v[22:25], v[144:147], v[178:181], v[22:25]
	v_mfma_f32_16x16x32_bf16 v[18:21], v[152:155], v[178:181], v[18:21]
	v_mfma_f32_16x16x32_bf16 v[38:41], v[144:147], v[186:189], v[38:41]
	v_mfma_f32_16x16x32_bf16 v[34:37], v[152:155], v[186:189], v[34:37]
	v_mfma_f32_16x16x32_bf16 v[54:57], v[144:147], v[194:197], v[54:57]
	v_mfma_f32_16x16x32_bf16 v[50:53], v[152:155], v[194:197], v[50:53]
	v_mfma_f32_16x16x32_bf16 v[6:9], v[148:151], v[174:177], v[6:9]
	v_mfma_f32_16x16x32_bf16 v[2:5], v[156:159], v[174:177], v[2:5]
	v_mfma_f32_16x16x32_bf16 v[22:25], v[148:151], v[182:185], v[22:25]
	v_mfma_f32_16x16x32_bf16 v[18:21], v[156:159], v[182:185], v[18:21]
	v_mfma_f32_16x16x32_bf16 v[38:41], v[148:151], v[190:193], v[38:41]
	v_mfma_f32_16x16x32_bf16 v[34:37], v[156:159], v[190:193], v[34:37]
	v_mfma_f32_16x16x32_bf16 v[54:57], v[148:151], v[198:201], v[54:57]
	v_mfma_f32_16x16x32_bf16 v[50:53], v[156:159], v[198:201], v[50:53]
	s_setprio 0
	s_barrier
	s_add_i32 s50, 0, 0x1c000
	s_add_i32 s51, s84, s53
	v_add_u32_e32 v221, s50, v141
	v_lshl_add_u64 v[202:203], v[202:203], 0, s[8:9]
	s_mov_b32 m0, s51
	ds_read_b128 v[222:225], v221
	ds_read_b128 v[226:229], v221 offset:1024
	ds_read_b128 v[230:233], v221 offset:2048
	ds_read_b128 v[234:237], v221 offset:3072
	global_load_lds_dwordx4 v[202:203], off
	v_lshl_add_u64 v[202:203], v[238:239], 0, s[8:9]
	s_add_i32 m0, s51, 0x2000
	s_nop 0
	global_load_lds_dwordx4 v[202:203], off
	s_barrier
	s_waitcnt lgkmcnt(0)
	s_setprio 1
	v_mfma_f32_16x16x32_bf16 v[14:17], v[222:225], v[160:163], v[14:17]
	v_mfma_f32_16x16x32_bf16 v[10:13], v[230:233], v[160:163], v[10:13]
	v_mfma_f32_16x16x32_bf16 v[30:33], v[222:225], v[178:181], v[30:33]
	v_mfma_f32_16x16x32_bf16 v[26:29], v[230:233], v[178:181], v[26:29]
	v_mfma_f32_16x16x32_bf16 v[46:49], v[222:225], v[186:189], v[46:49]
	v_mfma_f32_16x16x32_bf16 v[42:45], v[230:233], v[186:189], v[42:45]
	v_mfma_f32_16x16x32_bf16 v[62:65], v[222:225], v[194:197], v[62:65]
	v_mfma_f32_16x16x32_bf16 v[58:61], v[230:233], v[194:197], v[58:61]
	v_mfma_f32_16x16x32_bf16 v[14:17], v[226:229], v[174:177], v[14:17]
	v_mfma_f32_16x16x32_bf16 v[10:13], v[234:237], v[174:177], v[10:13]
	v_mfma_f32_16x16x32_bf16 v[30:33], v[226:229], v[182:185], v[30:33]
	v_mfma_f32_16x16x32_bf16 v[26:29], v[234:237], v[182:185], v[26:29]
	v_mfma_f32_16x16x32_bf16 v[46:49], v[226:229], v[190:193], v[46:49]
	v_mfma_f32_16x16x32_bf16 v[42:45], v[234:237], v[190:193], v[42:45]
	v_mfma_f32_16x16x32_bf16 v[62:65], v[226:229], v[198:201], v[62:65]
	v_mfma_f32_16x16x32_bf16 v[58:61], v[234:237], v[198:201], v[58:61]
	s_setprio 0
	s_mov_b32 m0, s74
	v_lshl_add_u64 v[202:203], v[240:241], 0, s[8:9]
	s_barrier
	ds_read_b128 v[160:163], v143 offset:49152
	ds_read_b128 v[174:177], v143 offset:50176
	ds_read_b128 v[178:181], v143 offset:51200
	ds_read_b128 v[182:185], v143 offset:52224
	ds_read_b128 v[186:189], v143 offset:53248
	ds_read_b128 v[190:193], v143 offset:54272
	ds_read_b128 v[194:197], v143 offset:55296
	ds_read_b128 v[198:201], v143 offset:56320
	global_load_lds_dwordx4 v[202:203], off
	v_lshl_add_u64 v[202:203], v[242:243], 0, s[8:9]
	s_mov_b32 m0, s75
	s_nop 0
	global_load_lds_dwordx4 v[202:203], off
	s_barrier
; #define PG8_STAGE(bufoff, gbase, voff) do { _Pragma("unroll") for (int _i = 0; _i < 2; ++_i) \
;         __builtin_amdgcn_global_load_lds((const unsigned*)((const char*)(gbase) + (voff)[_i]), (PG8_LAS unsigned*)(lds + (bufoff) + ldsw + _i * 8192), 16, 0, 0); } while (0)
; #define PG8_MMA(ai, bj, At, Bt) do { __builtin_amdgcn_s_setprio(1); _Pragma("unroll") for (int m = 0; m < 4; ++m) _Pragma("unroll") for (int n = 0; n < 2; ++n) _Pragma("unroll") for (int k = 0; k < 2; ++k) \
;         acc[ai][bj][m][n] = __builtin_amdgcn_mfma_f32_16x16x32_bf16(Bt[n][k], At[m][k], acc[ai][bj][m][n], 0, 0, 0); __builtin_amdgcn_s_setprio(0); } while (0)
; #define PG8_WAIT_V(n) asm volatile("s_waitcnt vmcnt(" #n ")" ::: "memory")
; #define PG8_WAIT_L(n) asm volatile("s_waitcnt lgkmcnt(" #n ")" ::: "memory")
; #define PG8_BAR __builtin_amdgcn_s_barrier()
; #define PG8_SCHED __builtin_amdgcn_sched_barrier(0)
; template <class Epi, class Sched>
; __device__ __forceinline__ void gemm_phase(PG8_LAS unsigned char* lds, const Gemm g, const Sched& S, const Epi& E) {
;     ...
;             PG8_BAR; PG8_WAIT_L(0); PG8_MMA(1, 0, At, B0); PG8_BAR; PG8_SCHED;
;             PG8_STAGE(PG8_SB(1, 1), b3 + hstep, voffB);
;             PG8_WAIT_V(6); PG8_BAR; PG8_MMA(1, 1, At, B1); PG8_BAR;
;     __device__ __forceinline__ void operator()(const f32x4 (&acc)[2][2][4][2], const Unit& u, int wr, int wc, int fr, int fq) const {
;         const int row0 = u.pm * 256 + wr * 64 + fr, col0 = u.pn * 256 + wc * 32 + 8 * fq;
; #pragma unroll
;         for (int ai = 0; ai < 2; ++ai)
; #pragma unroll
;             for (int m = 0; m < 4; ++m) { const size_t ro = (size_t)(row0 + ai * 128 + m * 16) * 1024 + col0;
; #pragma unroll
;                 for (int bj = 0; bj < 2; ++bj) { *(f32x4*)(XO + ro + bj * 128) = acc[ai][bj][m][0]; *(f32x4*)(XO + ro + bj * 128 + 4) = acc[ai][bj][m][1]; } }
;     }
	s_waitcnt lgkmcnt(0)
	s_setprio 1
	v_mfma_f32_16x16x32_bf16 v[66:69], v[144:147], v[160:163], v[66:69]
	v_mfma_f32_16x16x32_bf16 v[70:73], v[152:155], v[160:163], v[70:73]
	v_mfma_f32_16x16x32_bf16 v[82:85], v[144:147], v[178:181], v[82:85]
	v_mfma_f32_16x16x32_bf16 v[86:89], v[152:155], v[178:181], v[86:89]
	v_mfma_f32_16x16x32_bf16 v[98:101], v[144:147], v[186:189], v[98:101]
	v_mfma_f32_16x16x32_bf16 v[102:105], v[152:155], v[186:189], v[102:105]
	v_mfma_f32_16x16x32_bf16 v[114:117], v[144:147], v[194:197], v[114:117]
	v_mfma_f32_16x16x32_bf16 v[118:121], v[152:155], v[194:197], v[118:121]
	v_mfma_f32_16x16x32_bf16 v[66:69], v[148:151], v[174:177], v[66:69]
	v_mfma_f32_16x16x32_bf16 v[70:73], v[156:159], v[174:177], v[70:73]
	v_mfma_f32_16x16x32_bf16 v[82:85], v[148:151], v[182:185], v[82:85]
	v_mfma_f32_16x16x32_bf16 v[86:89], v[156:159], v[182:185], v[86:89]
	v_mfma_f32_16x16x32_bf16 v[98:101], v[148:151], v[190:193], v[98:101]
	v_mfma_f32_16x16x32_bf16 v[102:105], v[156:159], v[190:193], v[102:105]
	v_mfma_f32_16x16x32_bf16 v[114:117], v[148:151], v[198:201], v[114:117]
	v_mfma_f32_16x16x32_bf16 v[118:121], v[156:159], v[198:201], v[118:121]
	s_setprio 0
	s_barrier
	s_add_u32 s10, s10, 0x40080
	s_addc_u32 s11, s11, 0
	s_add_i32 s50, s50, s53
	v_lshl_add_u64 v[144:145], s[10:11], 0, v[0:1]
	s_mov_b32 m0, s50
	s_nop 0
	global_load_lds_dwordx4 v[144:145], off
	v_lshl_add_u64 v[144:145], s[10:11], 0, v[130:131]
	s_add_i32 m0, s50, 0x2000
	s_nop 0
	global_load_lds_dwordx4 v[144:145], off
	s_waitcnt vmcnt(6)
	s_barrier
	s_setprio 1
	v_mfma_f32_16x16x32_bf16 v[78:81], v[222:225], v[160:163], v[78:81]
	v_mfma_f32_16x16x32_bf16 v[74:77], v[230:233], v[160:163], v[74:77]
	v_mfma_f32_16x16x32_bf16 v[94:97], v[222:225], v[178:181], v[94:97]
	v_mfma_f32_16x16x32_bf16 v[90:93], v[230:233], v[178:181], v[90:93]
	v_mfma_f32_16x16x32_bf16 v[110:113], v[222:225], v[186:189], v[110:113]
	v_mfma_f32_16x16x32_bf16 v[106:109], v[230:233], v[186:189], v[106:109]
	v_mfma_f32_16x16x32_bf16 v[126:129], v[222:225], v[194:197], v[126:129]
	v_mfma_f32_16x16x32_bf16 v[122:125], v[230:233], v[194:197], v[122:125]
	v_mfma_f32_16x16x32_bf16 v[78:81], v[226:229], v[174:177], v[78:81]
	v_mfma_f32_16x16x32_bf16 v[74:77], v[234:237], v[174:177], v[74:77]
	v_mfma_f32_16x16x32_bf16 v[94:97], v[226:229], v[182:185], v[94:97]
	v_mfma_f32_16x16x32_bf16 v[90:93], v[234:237], v[182:185], v[90:93]
	v_mfma_f32_16x16x32_bf16 v[110:113], v[226:229], v[190:193], v[110:113]
	v_mfma_f32_16x16x32_bf16 v[106:109], v[234:237], v[190:193], v[106:109]
	v_mfma_f32_16x16x32_bf16 v[126:129], v[226:229], v[198:201], v[126:129]
	v_mfma_f32_16x16x32_bf16 v[122:125], v[234:237], v[198:201], v[122:125]
	s_setprio 0
	s_add_i32 s83, s83, 2
	s_add_u32 vcc_lo, vcc_lo, 0x100
	s_addc_u32 vcc_hi, vcc_hi, 0
	s_add_u32 s81, s81, 0x100
	s_addc_u32 s82, s82, 0
	s_cmp_gt_u32 s83, 13
	s_barrier
	s_cbranch_scc0 .LBB0_548
	v_lshl_add_u32 v144, s78, 8, v140
	v_lshl_or_b32 v146, s77, 8, v142
	v_ashrrev_i32_e32 v145, 31, v144
	v_ashrrev_i32_e32 v147, 31, v146
	v_lshlrev_b64 v[148:149], 12, v[144:145]
	v_lshl_add_u64 v[148:149], s[62:63], 0, v[148:149]
	v_lshlrev_b64 v[146:147], 2, v[146:147]
	v_lshl_add_u64 v[148:149], v[148:149], 0, v[146:147]
	global_store_dwordx4 v[148:149], v[6:9], off
	global_store_dwordx4 v[148:149], v[2:5], off offset:16
	global_store_dwordx4 v[148:149], v[14:17], off offset:512
	global_store_dwordx4 v[148:149], v[10:13], off offset:528
	v_or_b32_e32 v2, 16, v144
	v_ashrrev_i32_e32 v3, 31, v2
	v_lshlrev_b64 v[2:3], 12, v[2:3]
	v_lshl_add_u64 v[2:3], s[62:63], 0, v[2:3]
	v_lshl_add_u64 v[2:3], v[2:3], 0, v[146:147]
	global_store_dwordx4 v[2:3], v[22:25], off
	global_store_dwordx4 v[2:3], v[18:21], off offset:16
	global_store_dwordx4 v[2:3], v[30:33], off offset:512
	global_store_dwordx4 v[2:3], v[26:29], off offset:528
	v_or_b32_e32 v2, 32, v144
	v_ashrrev_i32_e32 v3, 31, v2
	v_lshlrev_b64 v[2:3], 12, v[2:3]
	v_lshl_add_u64 v[2:3], s[62:63], 0, v[2:3]
	v_lshl_add_u64 v[2:3], v[2:3], 0, v[146:147]
	global_store_dwordx4 v[2:3], v[38:41], off
	global_store_dwordx4 v[2:3], v[34:37], off offset:16
	global_store_dwordx4 v[2:3], v[46:49], off offset:512
	global_store_dwordx4 v[2:3], v[42:45], off offset:528
	v_or_b32_e32 v2, 48, v144
	v_ashrrev_i32_e32 v3, 31, v2
	v_lshlrev_b64 v[2:3], 12, v[2:3]
	v_lshl_add_u64 v[2:3], s[62:63], 0, v[2:3]
	v_lshl_add_u64 v[2:3], v[2:3], 0, v[146:147]
	v_add_co_u32_e32 v4, vcc, s54, v148
	global_store_dwordx4 v[2:3], v[54:57], off
	global_store_dwordx4 v[2:3], v[50:53], off offset:16
	global_store_dwordx4 v[2:3], v[62:65], off offset:512
	global_store_dwordx4 v[2:3], v[58:61], off offset:528
	v_lshl_add_u64 v[2:3], v[148:149], 0, s[42:43]
	v_addc_co_u32_e32 v5, vcc, 0, v149, vcc
	s_mov_b64 s[10:11], 0x90000
	global_store_dwordx4 v[4:5], v[66:69], off
	global_store_dwordx4 v[2:3], v[70:73], off offset:16
	global_store_dwordx4 v[2:3], v[78:81], off offset:512
	global_store_dwordx4 v[2:3], v[74:77], off offset:528
	v_lshl_add_u64 v[2:3], v[148:149], 0, s[10:11]
	s_mov_b32 s10, 0x90000
	v_add_co_u32_e32 v4, vcc, s10, v148
	s_mov_b64 s[10:11], 0xa0000
	s_nop 0
	v_addc_co_u32_e32 v5, vcc, 0, v149, vcc
	global_store_dwordx4 v[4:5], v[82:85], off
	global_store_dwordx4 v[2:3], v[86:89], off offset:16
	global_store_dwordx4 v[2:3], v[94:97], off offset:512
	global_store_dwordx4 v[2:3], v[90:93], off offset:528
	v_lshl_add_u64 v[2:3], v[148:149], 0, s[10:11]
	s_mov_b32 s10, 0xa0000
	v_add_co_u32_e32 v4, vcc, s10, v148
	s_mov_b64 s[10:11], 0xb0000
	s_nop 0
	v_addc_co_u32_e32 v5, vcc, 0, v149, vcc
	global_store_dwordx4 v[4:5], v[98:101], off
	global_store_dwordx4 v[2:3], v[102:105], off offset:16
	global_store_dwordx4 v[2:3], v[110:113], off offset:512
	global_store_dwordx4 v[2:3], v[106:109], off offset:528
	v_add_co_u32_e32 v4, vcc, 0xb0000, v148
	v_lshl_add_u64 v[2:3], v[148:149], 0, s[10:11]
	s_nop 0
	v_addc_co_u32_e32 v5, vcc, 0, v149, vcc
	s_andn2_b64 vcc, exec, s[36:37]
	s_mov_b64 s[10:11], -1
	global_store_dwordx4 v[4:5], v[114:117], off
	global_store_dwordx4 v[2:3], v[118:121], off offset:16
	global_store_dwordx4 v[2:3], v[126:129], off offset:512
	global_store_dwordx4 v[2:3], v[122:125], off offset:528
	s_cbranch_vccnz .LBB0_540
;     __device__ __forceinline__ void init(f32x4 (&acc)[2][2][4][2], const Unit& u, int wr, int wc, int fr, int fq) const {
;         const int row0 = u.pm * 256 + wr * 64 + fr, col0 = u.pn * 256 + wc * 32 + 8 * fq;
; #pragma unroll
;         for (int ai = 0; ai < 2; ++ai)
; #pragma unroll
;             for (int m = 0; m < 4; ++m) { const size_t ro = (size_t)(row0 + ai * 128 + m * 16) * 1024 + col0;
; #pragma unroll
;                 for (int bj = 0; bj < 2; ++bj) { acc[ai][bj][m][0] = *(const f32x4*)(XI + ro + bj * 128); acc[ai][bj][m][1] = *(const f32x4*)(XI + ro + bj * 128 + 4); } }
;     }
	v_lshl_add_u32 v50, s20, 8, v140
	v_lshl_or_b32 v2, s18, 8, v142
	v_ashrrev_i32_e32 v51, 31, v50
	v_ashrrev_i32_e32 v3, 31, v2
	v_lshlrev_b64 v[4:5], 12, v[50:51]
	v_lshl_add_u64 v[4:5], s[6:7], 0, v[4:5]
	v_lshlrev_b64 v[52:53], 2, v[2:3]
	v_lshl_add_u64 v[114:115], v[4:5], 0, v[52:53]
	v_add_co_u32_e32 v66, vcc, s54, v114
	s_mov_b64 s[10:11], 0x90000
	s_nop 0
	v_addc_co_u32_e32 v67, vcc, 0, v115, vcc
	v_lshl_add_u64 v[94:95], v[114:115], 0, s[10:11]
	s_mov_b32 s10, 0x90000
	v_add_co_u32_e32 v82, vcc, s10, v114
	s_mov_b64 s[10:11], 0xa0000
	v_or_b32_e32 v18, 16, v50
	v_or_b32_e32 v34, 32, v50
	v_or_b32_e32 v50, 48, v50
	v_addc_co_u32_e32 v83, vcc, 0, v115, vcc
	v_lshl_add_u64 v[110:111], v[114:115], 0, s[10:11]
	s_mov_b32 s10, 0xa0000
	v_ashrrev_i32_e32 v19, 31, v18
	v_ashrrev_i32_e32 v35, 31, v34
	v_ashrrev_i32_e32 v51, 31, v50
	v_add_co_u32_e32 v98, vcc, s10, v114
	s_mov_b64 s[10:11], 0xb0000
	v_lshlrev_b64 v[18:19], 12, v[18:19]
	v_lshlrev_b64 v[34:35], 12, v[34:35]
	v_lshlrev_b64 v[50:51], 12, v[50:51]
	v_addc_co_u32_e32 v99, vcc, 0, v115, vcc
	v_lshl_add_u64 v[126:127], v[114:115], 0, s[10:11]
	s_mov_b32 s10, 0xb0000
	global_load_dwordx4 v[2:5], v[114:115], off offset:16
	global_load_dwordx4 v[6:9], v[114:115], off
	global_load_dwordx4 v[10:13], v[114:115], off offset:528
	global_load_dwordx4 v[14:17], v[114:115], off offset:512
	v_lshl_add_u64 v[18:19], s[6:7], 0, v[18:19]
	v_lshl_add_u64 v[34:35], s[6:7], 0, v[34:35]
	v_lshl_add_u64 v[50:51], s[6:7], 0, v[50:51]
	v_lshl_add_u64 v[78:79], v[114:115], 0, s[42:43]
	v_add_co_u32_e32 v114, vcc, s10, v114
	v_lshl_add_u64 v[30:31], v[18:19], 0, v[52:53]
	v_lshl_add_u64 v[46:47], v[34:35], 0, v[52:53]
	v_lshl_add_u64 v[62:63], v[50:51], 0, v[52:53]
	v_addc_co_u32_e32 v115, vcc, 0, v115, vcc
	global_load_dwordx4 v[18:21], v[30:31], off offset:16
	global_load_dwordx4 v[22:25], v[30:31], off
	global_load_dwordx4 v[26:29], v[30:31], off offset:528
	s_nop 0
	global_load_dwordx4 v[30:33], v[30:31], off offset:512
	s_nop 0
	global_load_dwordx4 v[34:37], v[46:47], off offset:16
	global_load_dwordx4 v[38:41], v[46:47], off
	global_load_dwordx4 v[42:45], v[46:47], off offset:528
	s_nop 0
	global_load_dwordx4 v[46:49], v[46:47], off offset:512
	s_nop 0
	global_load_dwordx4 v[50:53], v[62:63], off offset:16
	global_load_dwordx4 v[54:57], v[62:63], off
	global_load_dwordx4 v[58:61], v[62:63], off offset:528
	s_nop 0
	global_load_dwordx4 v[62:65], v[62:63], off offset:512
	s_nop 0
	global_load_dwordx4 v[66:69], v[66:67], off
	s_nop 0
	global_load_dwordx4 v[74:77], v[78:79], off offset:528
	global_load_dwordx4 v[70:73], v[78:79], off offset:16
	s_nop 0
	global_load_dwordx4 v[78:81], v[78:79], off offset:512
	s_nop 0
	global_load_dwordx4 v[82:85], v[82:83], off
	s_nop 0
	global_load_dwordx4 v[90:93], v[94:95], off offset:528
	global_load_dwordx4 v[86:89], v[94:95], off offset:16
	s_nop 0
	global_load_dwordx4 v[94:97], v[94:95], off offset:512
	s_nop 0
	global_load_dwordx4 v[98:101], v[98:99], off
	s_nop 0
	global_load_dwordx4 v[106:109], v[110:111], off offset:528
	global_load_dwordx4 v[102:105], v[110:111], off offset:16
	s_nop 0
	global_load_dwordx4 v[110:113], v[110:111], off offset:512
	s_nop 0
	global_load_dwordx4 v[114:117], v[114:115], off
	s_nop 0
	global_load_dwordx4 v[122:125], v[126:127], off offset:528
	global_load_dwordx4 v[118:121], v[126:127], off offset:16
	s_nop 0
	global_load_dwordx4 v[126:129], v[126:127], off offset:512
	s_mov_b64 s[10:11], 0
	s_branch .LBB0_540
